# same as previous but the whole item (loads, wait, LDS transpose, stores) now runs between the two s_barriers of the grid barrier, nothing before or after it
# speedup vs baseline: 1.0335x; 1.0125x over previous
; DEV void phase_prologue_a(const Frame& F0) {
;     ...
;         constexpr int GU_NB = 2 * FF / 32, GU_ITEMS = 16 * GU_NB;
;         for (int it = F.gw; it < NE * GU_ITEMS; it += F.NGW) { const int e = it / GU_ITEMS, r = it % GU_ITEMS, kb = r / GU_NB, nb = r % GU_NB; const int d0 = 32 * nb, j = d0 >> 8, w = d0 & 255;
;             const float* src = (w < 128 ? GIN(I_WGATE) : GIN(I_WUP)) + ((size_t)l * NE + e) * 1024 * FF;
;             tr_item(src, FF, 128 * j + (w & 127), 64 * kb, (bf16_t*)(F.ws + WS_WGU) + ((size_t)l * NE + e) * 2 * FF * 1024, 1024, d0, scr, F.lane); }
.LBB0_115:
	s_or_b64 exec, exec, s[30:31]
	s_cselect_b32 s38, 1, 0
	v_writelane_b32 v255, s38, 61
	v_readlane_b32 s38, v255, 59
	s_add_i32 s39, s38, 1
	v_writelane_b32 v255, s39, 59
	s_mov_b32 s41, 0
	v_readlane_b32 s39, v251, 29
	s_cmp_eq_u32 s39, 0
	s_cbranch_scc1 .Lbw0_none
	v_readlane_b32 s40, v255, 51
	s_cmp_lg_u32 s40, 0x100
	s_cbranch_scc1 .Lbw0_none
	v_readlane_b32 s40, v255, 48
	s_mul_i32 s40, s40, 7
	s_mul_i32 s38, s38, 0x700
	s_add_i32 s40, s40, s38
	s_add_i32 s40, s40, s39
	s_add_i32 s40, s40, -1
	s_cmp_lt_u32 s40, 0x11f00
	s_cbranch_scc0 .Lbw0_none
	s_mov_b32 s41, 1
	s_cmp_lt_u32 s40, 0x8000
	s_cbranch_scc1 .Lbw0_have
	s_mov_b32 s41, 2
	s_sub_i32 s40, s40, 0x8000
	s_cmp_lt_u32 s40, 0x5200
	s_cbranch_scc1 .Lbw0_have
	s_mov_b32 s41, 3
	s_sub_i32 s40, s40, 0x5200

; #define LAS __attribute__((address_space(3)))
; #define NT_LOAD(p) __builtin_nontemporal_load(p)
; DEV void tr_item(const float* W, int ldw, int col0, int k0, bf16_t* WT, int K, int row0, LAS float* scr, int lane) {
; #pragma unroll 8
;     for (int i = 0; i < 32; ++i) { const int kk = 2 * i + (lane >> 5); scr[kk * 33 + (lane & 31)] = NT_LOAD(&W[(size_t)(k0 + kk) * ldw + col0 + (lane & 31)]); }
.Lbw0_gate:
	s_add_u32 s42, s100, s42
	s_addc_u32 s43, s101, 0
	s_lshl_b32 s39, s41, 16
	s_or_b32 s41, s39, s40
	v_lshrrev_b32_e32 v173, 5, v200
	v_and_b32_e32 v174, 31, v200
	v_lshlrev_b32_e32 v174, 2, v174
	v_lshl_add_u32 v80, v173, 13, v174
	v_mov_b32_e32 v81, 0
	s_mov_b64 s[100:101], 0x4000
	v_lshl_add_u64 v[64:65], s[42:43], 0, v[80:81]
	v_lshl_add_u64 v[66:67], v[64:65], 0, s[100:101]
	v_lshl_add_u64 v[68:69], v[66:67], 0, s[100:101]
	v_lshl_add_u64 v[70:71], v[68:69], 0, s[100:101]
	v_lshl_add_u64 v[72:73], v[70:71], 0, s[100:101]
	v_lshl_add_u64 v[74:75], v[72:73], 0, s[100:101]
	v_lshl_add_u64 v[76:77], v[74:75], 0, s[100:101]
	v_lshl_add_u64 v[78:79], v[76:77], 0, s[100:101]
	s_mov_b64 s[100:101], 0x20000
	global_load_dword v82, v[64:65], off nt
	global_load_dword v83, v[66:67], off nt
	global_load_dword v84, v[68:69], off nt
	global_load_dword v85, v[70:71], off nt
	global_load_dword v86, v[72:73], off nt
	global_load_dword v87, v[74:75], off nt
	global_load_dword v88, v[76:77], off nt
	global_load_dword v89, v[78:79], off nt
	v_lshl_add_u64 v[64:65], v[64:65], 0, s[100:101]
	v_lshl_add_u64 v[66:67], v[66:67], 0, s[100:101]
	v_lshl_add_u64 v[68:69], v[68:69], 0, s[100:101]
	v_lshl_add_u64 v[70:71], v[70:71], 0, s[100:101]
	v_lshl_add_u64 v[72:73], v[72:73], 0, s[100:101]
	v_lshl_add_u64 v[74:75], v[74:75], 0, s[100:101]
	v_lshl_add_u64 v[76:77], v[76:77], 0, s[100:101]
	v_lshl_add_u64 v[78:79], v[78:79], 0, s[100:101]
	global_load_dword v90, v[64:65], off nt
	global_load_dword v91, v[66:67], off nt
	global_load_dword v92, v[68:69], off nt
	global_load_dword v93, v[70:71], off nt
	global_load_dword v94, v[72:73], off nt
	global_load_dword v95, v[74:75], off nt
	global_load_dword v96, v[76:77], off nt
	global_load_dword v97, v[78:79], off nt
	v_lshl_add_u64 v[64:65], v[64:65], 0, s[100:101]
	v_lshl_add_u64 v[66:67], v[66:67], 0, s[100:101]
	v_lshl_add_u64 v[68:69], v[68:69], 0, s[100:101]
	v_lshl_add_u64 v[70:71], v[70:71], 0, s[100:101]
	v_lshl_add_u64 v[72:73], v[72:73], 0, s[100:101]
	v_lshl_add_u64 v[74:75], v[74:75], 0, s[100:101]
	v_lshl_add_u64 v[76:77], v[76:77], 0, s[100:101]
	v_lshl_add_u64 v[78:79], v[78:79], 0, s[100:101]
	global_load_dword v98, v[64:65], off nt
	global_load_dword v99, v[66:67], off nt
	global_load_dword v100, v[68:69], off nt
	global_load_dword v101, v[70:71], off nt
	global_load_dword v102, v[72:73], off nt
	global_load_dword v103, v[74:75], off nt
	global_load_dword v104, v[76:77], off nt
	global_load_dword v105, v[78:79], off nt
	v_lshl_add_u64 v[64:65], v[64:65], 0, s[100:101]
	v_lshl_add_u64 v[66:67], v[66:67], 0, s[100:101]
	v_lshl_add_u64 v[68:69], v[68:69], 0, s[100:101]
	v_lshl_add_u64 v[70:71], v[70:71], 0, s[100:101]
	v_lshl_add_u64 v[72:73], v[72:73], 0, s[100:101]
	v_lshl_add_u64 v[74:75], v[74:75], 0, s[100:101]
	v_lshl_add_u64 v[76:77], v[76:77], 0, s[100:101]
	v_lshl_add_u64 v[78:79], v[78:79], 0, s[100:101]
	global_load_dword v106, v[64:65], off nt
	global_load_dword v107, v[66:67], off nt
	global_load_dword v108, v[68:69], off nt
	global_load_dword v109, v[70:71], off nt
	global_load_dword v110, v[72:73], off nt
	global_load_dword v111, v[74:75], off nt
	global_load_dword v112, v[76:77], off nt
	global_load_dword v113, v[78:79], off nt
	s_branch .Lbw0_fin
.Lbw0_none:
	s_mov_b32 s41, 0
; DEV void tr_item(const float* W, int ldw, int col0, int k0, bf16_t* WT, int K, int row0, LAS float* scr, int lane) {
;     ...
;     for (int i = 0; i < 32; ++i) { const int kk = 2 * i + (lane >> 5); scr[kk * 33 + (lane & 31)] = NT_LOAD(&W[(size_t)(k0 + kk) * ldw + col0 + (lane & 31)]); }
;     WAVE_LDS_SYNC();
;     const int c = lane & 7;
; #pragma unroll
;     for (int j = 0; j < 4; ++j) { const int n = (lane >> 3) + 8 * j; const LAS float* s = scr + (8 * c) * 33 + n;
;         u32x4 o; o.x = pk2(s[0 * 33], s[1 * 33]); o.y = pk2(s[2 * 33], s[3 * 33]); o.z = pk2(s[4 * 33], s[5 * 33]); o.w = pk2(s[6 * 33], s[7 * 33]);
;         NT_STORE(o, (u32x4*)(WT + (size_t)(row0 + n) * K + k0 + 8 * c)); }
;     WAVE_LDS_SYNC();
; DEV float gate_tf(const Frame& F, int l, int gi, float x) {
;     const int ty = gi >> 2, hh = gi & 3, li = l >> 1;
;     if (!(l & 1)) {
;         if (ty < 2) return -expf(GIN(I_EVALOG)[(li * 2 + ty) * 4 + hh]) * softplus_f(x + GIN(I_EVDTB)[(li * 2 + ty) * 4 + hh]);
;         return sigmoid_f(x);
;     }
;     const int d = ty & 1, k = ty >> 1; const float gb = GIN(I_ODGB)[((li * 2 + d) * 2 + k) * 4 + hh];
;     return k ? -softplus_f(-(x + gb)) : x + gb;
; }
; template <int RG> DEV void xg_rows(const Frame& F, int l, int row0, f32x4 (&v)[RG][4]) {
;     int b, s; row_bs(row0, b, s); const int mr = s < CTX ? B_ : b;
;     const float* mod = (const float*)(F.ws + WS_MOD) + ((size_t)l * NR + mr) * 6144;
; #pragma unroll
;     for (int j = 0; j < 4; ++j) { const f32x4 sh = *((const f32x4*)mod + F.lane + 64 * j), sc = *((const f32x4*)(mod + 1024) + F.lane + 64 * j);
; #pragma unroll
;         for (int q = 0; q < RG; ++q) v[q][j] = v[q][j] * (1.0f + sc) + sh; }
; #pragma unroll
;     for (int q = 0; q < RG; ++q) { u32x2* xo = (u32x2*)((bf16_t*)(F.ws + WS_XIN) + (size_t)(row0 + q) * 1024) + F.lane;
; #pragma unroll
;         for (int j = 0; j < 4; ++j) xo[64 * j] = (u32x2){pk2(v[q][j].x, v[q][j].y), pk2(v[q][j].z, v[q][j].w)}; }
; }
; template <int RG> DEV void xg0_group(const Frame& F, int r) {
;         f32x4 v[RG][4];
; #pragma unroll
;         for (int q = 0; q < RG; ++q) { const f32x4* hr = (const f32x4*)HROW(F, 0, r + q) + F.lane;
; #pragma unroll
;             for (int j = 0; j < 4; ++j) v[q][j] = hr[64 * j]; }
;         xg_rows<RG>(F, 0, r, v);
;     }
; DEV void phase_xg0(const Frame& F0) {
;     const Frame F = refresh(F0);
.Lbw0_fin:
	v_writelane_b32 v255, s41, 60
	s_nop 0
	v_readlane_b32 s40, v255, 60
	s_cmp_eq_u32 s40, 0
	s_cbranch_scc1 .Lbw0_skip
	s_lshr_b32 s41, s40, 16
	s_and_b32 s40, s40, 0xffff
	s_and_b32 s38, s40, 0x7ff
	s_lshr_b32 s39, s38, 7
	s_and_b32 s38, s38, 0x7f
	s_lshl_b32 s42, s38, 16
	s_lshl_b32 s39, s39, 7
	s_add_i32 s42, s42, s39
	s_lshr_b32 s39, s40, 11
	s_lshl_b32 s39, s39, 23
	s_add_i32 s42, s42, s39
	s_lshl_b32 s39, s41, 27
	s_add_u32 s42, s42, s39
	s_add_u32 s42, s42, 0x2bc8000
	v_readlane_b32 s100, v255, 53
	v_readlane_b32 s101, v255, 54
	s_add_u32 s42, s100, s42
	s_addc_u32 s43, s101, 0
	v_readlane_b32 s39, v251, 29
	s_lshl_b32 s39, s39, 14
	v_and_b32_e32 v173, 31, v200
	v_lshrrev_b32_e32 v174, 5, v200
	v_mul_u32_u24_e32 v174, 33, v174
	v_add_u32_e32 v174, v174, v173
	v_lshl_add_u32 v147, v174, 2, s39
	v_add_u32_e32 v148, 0x400, v147
	v_add_u32_e32 v166, 0x840, v147
	v_add_u32_e32 v167, 0xc40, v147
	v_add_u32_e32 v168, 0x1080, v147
	v_add_u32_e32 v169, 0x1480, v147
	v_add_u32_e32 v170, 0x18c0, v147
	v_add_u32_e32 v171, 0x1cc0, v147
	v_and_b32_e32 v173, 7, v200
	v_lshrrev_b32_e32 v174, 3, v200
	v_mul_u32_u24_e32 v175, 0x108, v173
	v_add_u32_e32 v175, v175, v174
	v_lshl_add_u32 v172, v175, 2, s39
	v_lshlrev_b32_e32 v173, 4, v173
	v_lshl_add_u32 v80, v174, 11, v173
	v_mov_b32_e32 v81, 0
	s_mov_b64 s[100:101], 0x4000
	v_lshl_add_u64 v[64:65], s[42:43], 0, v[80:81]
	v_lshl_add_u64 v[66:67], v[64:65], 0, s[100:101]
	v_lshl_add_u64 v[68:69], v[66:67], 0, s[100:101]
	v_lshl_add_u64 v[70:71], v[68:69], 0, s[100:101]
	s_waitcnt vmcnt(0)
	ds_write2_b32 v147, v82, v83 offset1:66
	ds_write2_b32 v147, v84, v85 offset0:132 offset1:198
	ds_write2_b32 v148, v86, v87 offset0:8 offset1:74
	ds_write2_b32 v148, v88, v89 offset0:140 offset1:206
	ds_write2_b32 v166, v90, v91 offset1:66
	ds_write2_b32 v166, v92, v93 offset0:132 offset1:198
	ds_write2_b32 v167, v94, v95 offset0:8 offset1:74
	ds_write2_b32 v167, v96, v97 offset0:140 offset1:206
	ds_write2_b32 v168, v98, v99 offset1:66
	ds_write2_b32 v168, v100, v101 offset0:132 offset1:198
	ds_write2_b32 v169, v102, v103 offset0:8 offset1:74
	ds_write2_b32 v169, v104, v105 offset0:140 offset1:206
	ds_write2_b32 v170, v106, v107 offset1:66
	ds_write2_b32 v170, v108, v109 offset0:132 offset1:198
	ds_write2_b32 v171, v110, v111 offset0:8 offset1:74
	ds_write2_b32 v171, v112, v113 offset0:140 offset1:206
	ds_read2_b32 v[114:115], v172 offset1:8
	ds_read2_b32 v[116:117], v172 offset0:33 offset1:41
	ds_read2_b32 v[118:119], v172 offset0:66 offset1:74
	ds_read2_b32 v[120:121], v172 offset0:99 offset1:107
	ds_read2_b32 v[122:123], v172 offset0:132 offset1:140
	ds_read2_b32 v[124:125], v172 offset0:165 offset1:173
	ds_read2_b32 v[126:127], v172 offset0:198 offset1:206
	ds_read2_b32 v[128:129], v172 offset0:231 offset1:239
	ds_read2_b32 v[130:131], v172 offset0:16 offset1:24
	ds_read2_b32 v[132:133], v172 offset0:49 offset1:57
	ds_read2_b32 v[134:135], v172 offset0:82 offset1:90
	ds_read2_b32 v[136:137], v172 offset0:115 offset1:123
	s_waitcnt lgkmcnt(4)
	v_cvt_pk_bf16_f32 v150, v114, v116
	v_cvt_pk_bf16_f32 v151, v118, v120
	v_cvt_pk_bf16_f32 v152, v122, v124
	v_cvt_pk_bf16_f32 v153, v126, v128
	v_cvt_pk_bf16_f32 v154, v115, v117
	v_cvt_pk_bf16_f32 v155, v119, v121
	v_cvt_pk_bf16_f32 v156, v123, v125
	v_cvt_pk_bf16_f32 v157, v127, v129
	ds_read2_b32 v[138:139], v172 offset0:148 offset1:156
	ds_read2_b32 v[140:141], v172 offset0:181 offset1:189
	ds_read2_b32 v[142:143], v172 offset0:214 offset1:222
	ds_read2_b32 v[144:145], v172 offset0:247 offset1:255
	global_store_dwordx4 v[64:65], v[150:153], off nt
	global_store_dwordx4 v[66:67], v[154:157], off nt
	s_waitcnt lgkmcnt(0)
	v_cvt_pk_bf16_f32 v158, v130, v132
	v_cvt_pk_bf16_f32 v159, v134, v136
	v_cvt_pk_bf16_f32 v160, v138, v140
	v_cvt_pk_bf16_f32 v161, v142, v144
	v_cvt_pk_bf16_f32 v162, v131, v133
	v_cvt_pk_bf16_f32 v163, v135, v137
	v_cvt_pk_bf16_f32 v164, v139, v141
	v_cvt_pk_bf16_f32 v165, v143, v145
	global_store_dwordx4 v[68:69], v[158:161], off nt
	global_store_dwordx4 v[70:71], v[162:165], off nt
.Lbw0_skip:
	s_waitcnt lgkmcnt(0)
	v_readlane_b32 s38, v255, 61
	s_cmp_lg_u32 s38, 0
	s_lshl_b32 s82, s96, 5
	s_abs_i32 s4, s82
	v_cvt_f32_u32_e32 v0, s4
	v_readlane_b32 s0, v251, 0
	v_readlane_b32 s1, v251, 1
	v_readlane_b32 s2, v251, 2
	v_rcp_iflag_f32_e32 v0, v0
	v_readlane_b32 s3, v251, 3
	s_mov_b64 s[0:1], s[2:3]
	s_sub_i32 s2, 0, s4
	v_mul_f32_e32 v0, 0x4f7ffffe, v0
	v_cvt_u32_f32_e32 v0, v0
	v_readlane_b32 s10, v251, 29
	s_waitcnt lgkmcnt(0)
	s_barrier
	v_readfirstlane_b32 s3, v0
	s_mul_i32 s2, s2, s3
	s_mul_hi_u32 s2, s3, s2
	s_add_i32 s2, s3, s2
	v_writelane_b32 v252, s2, 2
	s_mul_hi_u32 s2, s2, 0x4400
	s_mul_i32 s2, s2, s4
	s_sub_i32 s2, 0x4400, s2
	s_sub_i32 s3, s2, s4
	s_cmp_ge_u32 s2, s4
	s_cselect_b32 s2, s3, s2
	s_sub_i32 s3, s2, s4
	s_cmp_ge_u32 s2, s4
	s_cselect_b32 s2, s3, s2
	v_writelane_b32 v252, s4, 3
	s_sub_i32 s3, 0x4400, s2
	s_lshl_b32 s4, s95, 5
	s_lshl_b32 s2, s10, 2
	v_mov_b32_e32 v64, v200
	v_writelane_b32 v252, s4, 4
	s_add_i32 s2, s2, s4
	v_writelane_b32 v252, s3, 5
	s_cmp_ge_i32 s2, s3
	v_ashrrev_i32_e32 v65, 31, v64
	s_cbranch_scc1 .LBB0_120
	s_add_u32 s11, s0, 0x10000
	s_addc_u32 s12, s1, 0
	s_ashr_i32 s3, s2, 31
	s_add_u32 s13, s2, 3
	s_addc_u32 s14, s3, 0
	s_ashr_i32 s83, s82, 31
	s_lshl_b64 s[4:5], s[2:3], 11
	s_add_u32 s4, s0, s4
	s_addc_u32 s5, s1, s5
	v_lshl_add_u64 v[0:1], v[64:65], 3, s[4:5]
	s_mov_b64 s[4:5], 0x37099e00
	v_lshl_add_u64 v[66:67], v[0:1], 0, s[4:5]
	s_lshl_b64 s[4:5], s[82:83], 11
	v_lshlrev_b64 v[68:69], 4, v[64:65]
	s_mov_b64 s[6:7], 0x1000
	s_movk_i32 s3, 0xf000
	s_branch .LBB0_118

; #define LAS __attribute__((address_space(3)))
; #define NT_LOAD(p) __builtin_nontemporal_load(p)
; DEV void tr_item(const float* W, int ldw, int col0, int k0, bf16_t* WT, int K, int row0, LAS float* scr, int lane) {
; #pragma unroll 8
;     for (int i = 0; i < 32; ++i) { const int kk = 2 * i + (lane >> 5); scr[kk * 33 + (lane & 31)] = NT_LOAD(&W[(size_t)(k0 + kk) * ldw + col0 + (lane & 31)]); }
; DEV void phase_prologue_a(const Frame& F0) {
;     ...
;         constexpr int GU_NB = 2 * FF / 32, GU_ITEMS = 16 * GU_NB;
;         for (int it = F.gw; it < NE * GU_ITEMS; it += F.NGW) { const int e = it / GU_ITEMS, r = it % GU_ITEMS, kb = r / GU_NB, nb = r % GU_NB; const int d0 = 32 * nb, j = d0 >> 8, w = d0 & 255;
;             const float* src = (w < 128 ? GIN(I_WGATE) : GIN(I_WUP)) + ((size_t)l * NE + e) * 1024 * FF;
;             tr_item(src, FF, 128 * j + (w & 127), 64 * kb, (bf16_t*)(F.ws + WS_WGU) + ((size_t)l * NE + e) * 2 * FF * 1024, 1024, d0, scr, F.lane); }
.Lbw1_gate:
	s_add_u32 s42, s100, s42
	s_addc_u32 s43, s101, 0
	s_lshl_b32 s39, s41, 16
	s_or_b32 s41, s39, s40
	v_lshrrev_b32_e32 v134, 5, v200
	v_and_b32_e32 v135, 31, v200
	v_lshlrev_b32_e32 v135, 2, v135
	v_lshl_add_u32 v44, v134, 13, v135
	v_mov_b32_e32 v45, 0
	s_mov_b64 s[100:101], 0x4000
	v_lshl_add_u64 v[28:29], s[42:43], 0, v[44:45]
	v_lshl_add_u64 v[30:31], v[28:29], 0, s[100:101]
	v_lshl_add_u64 v[32:33], v[30:31], 0, s[100:101]
	v_lshl_add_u64 v[34:35], v[32:33], 0, s[100:101]
	v_lshl_add_u64 v[36:37], v[34:35], 0, s[100:101]
	v_lshl_add_u64 v[38:39], v[36:37], 0, s[100:101]
	v_lshl_add_u64 v[40:41], v[38:39], 0, s[100:101]
	v_lshl_add_u64 v[42:43], v[40:41], 0, s[100:101]
	s_mov_b64 s[100:101], 0x20000
	global_load_dword v27, v[28:29], off nt
	global_load_dword v46, v[30:31], off nt
	global_load_dword v47, v[32:33], off nt
	global_load_dword v48, v[34:35], off nt
	global_load_dword v49, v[36:37], off nt
	global_load_dword v50, v[38:39], off nt
	global_load_dword v51, v[40:41], off nt
	global_load_dword v52, v[42:43], off nt
	v_lshl_add_u64 v[28:29], v[28:29], 0, s[100:101]
	v_lshl_add_u64 v[30:31], v[30:31], 0, s[100:101]
	v_lshl_add_u64 v[32:33], v[32:33], 0, s[100:101]
	v_lshl_add_u64 v[34:35], v[34:35], 0, s[100:101]
	v_lshl_add_u64 v[36:37], v[36:37], 0, s[100:101]
	v_lshl_add_u64 v[38:39], v[38:39], 0, s[100:101]
	v_lshl_add_u64 v[40:41], v[40:41], 0, s[100:101]
	v_lshl_add_u64 v[42:43], v[42:43], 0, s[100:101]
	global_load_dword v53, v[28:29], off nt
	global_load_dword v54, v[30:31], off nt
	global_load_dword v55, v[32:33], off nt
	global_load_dword v56, v[34:35], off nt
	global_load_dword v57, v[36:37], off nt
	global_load_dword v58, v[38:39], off nt
	global_load_dword v59, v[40:41], off nt
	global_load_dword v60, v[42:43], off nt
	v_lshl_add_u64 v[28:29], v[28:29], 0, s[100:101]
	v_lshl_add_u64 v[30:31], v[30:31], 0, s[100:101]
	v_lshl_add_u64 v[32:33], v[32:33], 0, s[100:101]
	v_lshl_add_u64 v[34:35], v[34:35], 0, s[100:101]
	v_lshl_add_u64 v[36:37], v[36:37], 0, s[100:101]
	v_lshl_add_u64 v[38:39], v[38:39], 0, s[100:101]
	v_lshl_add_u64 v[40:41], v[40:41], 0, s[100:101]
	v_lshl_add_u64 v[42:43], v[42:43], 0, s[100:101]
	global_load_dword v61, v[28:29], off nt
	global_load_dword v62, v[30:31], off nt
	global_load_dword v63, v[32:33], off nt
	global_load_dword v64, v[34:35], off nt
	global_load_dword v65, v[36:37], off nt
	global_load_dword v66, v[38:39], off nt
	global_load_dword v67, v[40:41], off nt
	global_load_dword v68, v[42:43], off nt
	v_lshl_add_u64 v[28:29], v[28:29], 0, s[100:101]
	v_lshl_add_u64 v[30:31], v[30:31], 0, s[100:101]
	v_lshl_add_u64 v[32:33], v[32:33], 0, s[100:101]
	v_lshl_add_u64 v[34:35], v[34:35], 0, s[100:101]
	v_lshl_add_u64 v[36:37], v[36:37], 0, s[100:101]
	v_lshl_add_u64 v[38:39], v[38:39], 0, s[100:101]
	v_lshl_add_u64 v[40:41], v[40:41], 0, s[100:101]
	v_lshl_add_u64 v[42:43], v[42:43], 0, s[100:101]
	global_load_dword v69, v[28:29], off nt
	global_load_dword v70, v[30:31], off nt
	global_load_dword v71, v[32:33], off nt
	global_load_dword v72, v[34:35], off nt
	global_load_dword v73, v[36:37], off nt
	global_load_dword v74, v[38:39], off nt
	global_load_dword v75, v[40:41], off nt
	global_load_dword v76, v[42:43], off nt
	s_branch .Lbw1_fin

; #define WAVE_LDS_SYNC() do { int _z = 0; (void)emu::wave_xchg(&_z, 4); } while (0)
; #define LAS __attribute__((address_space(3)))
; #define WAVE_LDS_SYNC() asm volatile("s_waitcnt lgkmcnt(0)" ::: "memory")
; #define NT_LOAD(p) __builtin_nontemporal_load(p)
; #define NT_STORE(v, p) __builtin_nontemporal_store((v), (p))
; DEV unsigned pk2(float lo, float hi) { return f2bf(lo) | (f2bf(hi) << 16); }
; DEV unsigned pk2(float lo, float hi) { const f32x2n_t v = {lo, hi}; return __builtin_bit_cast(unsigned, __builtin_convertvector(v, bf16x2n_t)); }
; DEV void tr_item(const float* W, int ldw, int col0, int k0, bf16_t* WT, int K, int row0, LAS float* scr, int lane) {
;     ...
;     for (int i = 0; i < 32; ++i) { const int kk = 2 * i + (lane >> 5); scr[kk * 33 + (lane & 31)] = NT_LOAD(&W[(size_t)(k0 + kk) * ldw + col0 + (lane & 31)]); }
;     WAVE_LDS_SYNC();
;     const int c = lane & 7;
; #pragma unroll
;     for (int j = 0; j < 4; ++j) { const int n = (lane >> 3) + 8 * j; const LAS float* s = scr + (8 * c) * 33 + n;
;         u32x4 o; o.x = pk2(s[0 * 33], s[1 * 33]); o.y = pk2(s[2 * 33], s[3 * 33]); o.z = pk2(s[4 * 33], s[5 * 33]); o.w = pk2(s[6 * 33], s[7 * 33]);
;         NT_STORE(o, (u32x4*)(WT + (size_t)(row0 + n) * K + k0 + 8 * c)); }
;     WAVE_LDS_SYNC();
; DEV ClProb cl_decode(const Frame& F, int p, int odd, int nhh) {
;     ...
;     const bf16_t* P = (const bf16_t*)(F.ws + WS_P); const bf16_t* Q = (const bf16_t*)(F.ws + WS_QKV);
;     ...
;     return c;
.Lbw1_fin:
	v_writelane_b32 v255, s41, 60
	s_nop 0
	v_readlane_b32 s40, v255, 60
	s_cmp_eq_u32 s40, 0
	s_cbranch_scc1 .Lbw1_skip
	s_lshr_b32 s41, s40, 16
	s_and_b32 s40, s40, 0xffff
	s_and_b32 s38, s40, 0x7ff
	s_lshr_b32 s39, s38, 7
	s_and_b32 s38, s38, 0x7f
	s_lshl_b32 s42, s38, 16
	s_lshl_b32 s39, s39, 7
	s_add_i32 s42, s42, s39
	s_lshr_b32 s39, s40, 11
	s_lshl_b32 s39, s39, 23
	s_add_i32 s42, s42, s39
	s_lshl_b32 s39, s41, 27
	s_add_u32 s42, s42, s39
	s_add_u32 s42, s42, 0x2bc8000
	v_readlane_b32 s100, v255, 53
	v_readlane_b32 s101, v255, 54
	s_add_u32 s42, s100, s42
	s_addc_u32 s43, s101, 0
	v_readlane_b32 s39, v251, 29
	s_lshl_b32 s39, s39, 14
	v_and_b32_e32 v134, 31, v200
	v_lshrrev_b32_e32 v135, 5, v200
	v_mul_u32_u24_e32 v135, 33, v135
	v_add_u32_e32 v135, v135, v134
	v_lshl_add_u32 v77, v135, 2, s39
	v_add_u32_e32 v126, 0x400, v77
	v_add_u32_e32 v127, 0x840, v77
	v_add_u32_e32 v128, 0xc40, v77
	v_add_u32_e32 v129, 0x1080, v77
	v_add_u32_e32 v130, 0x1480, v77
	v_add_u32_e32 v131, 0x18c0, v77
	v_add_u32_e32 v132, 0x1cc0, v77
	v_and_b32_e32 v134, 7, v200
	v_lshrrev_b32_e32 v135, 3, v200
	v_mul_u32_u24_e32 v136, 0x108, v134
	v_add_u32_e32 v136, v136, v135
	v_lshl_add_u32 v133, v136, 2, s39
	v_lshlrev_b32_e32 v134, 4, v134
	v_lshl_add_u32 v44, v135, 11, v134
	v_mov_b32_e32 v45, 0
	s_mov_b64 s[100:101], 0x4000
	v_lshl_add_u64 v[28:29], s[42:43], 0, v[44:45]
	v_lshl_add_u64 v[30:31], v[28:29], 0, s[100:101]
	v_lshl_add_u64 v[32:33], v[30:31], 0, s[100:101]
	v_lshl_add_u64 v[34:35], v[32:33], 0, s[100:101]
	s_waitcnt vmcnt(0)
	ds_write2_b32 v77, v27, v46 offset1:66
	ds_write2_b32 v77, v47, v48 offset0:132 offset1:198
	ds_write2_b32 v126, v49, v50 offset0:8 offset1:74
	ds_write2_b32 v126, v51, v52 offset0:140 offset1:206
	ds_write2_b32 v127, v53, v54 offset1:66
	ds_write2_b32 v127, v55, v56 offset0:132 offset1:198
	ds_write2_b32 v128, v57, v58 offset0:8 offset1:74
	ds_write2_b32 v128, v59, v60 offset0:140 offset1:206
	ds_write2_b32 v129, v61, v62 offset1:66
	ds_write2_b32 v129, v63, v64 offset0:132 offset1:198
	ds_write2_b32 v130, v65, v66 offset0:8 offset1:74
	ds_write2_b32 v130, v67, v68 offset0:140 offset1:206
	ds_write2_b32 v131, v69, v70 offset1:66
	ds_write2_b32 v131, v71, v72 offset0:132 offset1:198
	ds_write2_b32 v132, v73, v74 offset0:8 offset1:74
	ds_write2_b32 v132, v75, v76 offset0:140 offset1:206
	ds_read2_b32 v[78:79], v133 offset1:8
	ds_read2_b32 v[80:81], v133 offset0:33 offset1:41
	ds_read2_b32 v[82:83], v133 offset0:66 offset1:74
	ds_read2_b32 v[84:85], v133 offset0:99 offset1:107
	ds_read2_b32 v[86:87], v133 offset0:132 offset1:140
	ds_read2_b32 v[88:89], v133 offset0:165 offset1:173
	ds_read2_b32 v[90:91], v133 offset0:198 offset1:206
	ds_read2_b32 v[92:93], v133 offset0:231 offset1:239
	ds_read2_b32 v[94:95], v133 offset0:16 offset1:24
	ds_read2_b32 v[96:97], v133 offset0:49 offset1:57
	ds_read2_b32 v[98:99], v133 offset0:82 offset1:90
	ds_read2_b32 v[100:101], v133 offset0:115 offset1:123
	s_waitcnt lgkmcnt(4)
	v_cvt_pk_bf16_f32 v110, v78, v80
	v_cvt_pk_bf16_f32 v111, v82, v84
	v_cvt_pk_bf16_f32 v112, v86, v88
	v_cvt_pk_bf16_f32 v113, v90, v92
	v_cvt_pk_bf16_f32 v114, v79, v81
	v_cvt_pk_bf16_f32 v115, v83, v85
	v_cvt_pk_bf16_f32 v116, v87, v89
	v_cvt_pk_bf16_f32 v117, v91, v93
	ds_read2_b32 v[102:103], v133 offset0:148 offset1:156
	ds_read2_b32 v[104:105], v133 offset0:181 offset1:189
	ds_read2_b32 v[106:107], v133 offset0:214 offset1:222
	ds_read2_b32 v[108:109], v133 offset0:247 offset1:255
	global_store_dwordx4 v[28:29], v[110:113], off nt
	global_store_dwordx4 v[30:31], v[114:117], off nt
	s_waitcnt lgkmcnt(0)
	v_cvt_pk_bf16_f32 v118, v94, v96
	v_cvt_pk_bf16_f32 v119, v98, v100
	v_cvt_pk_bf16_f32 v120, v102, v104
	v_cvt_pk_bf16_f32 v121, v106, v108
	v_cvt_pk_bf16_f32 v122, v95, v97
	v_cvt_pk_bf16_f32 v123, v99, v101
	v_cvt_pk_bf16_f32 v124, v103, v105
	v_cvt_pk_bf16_f32 v125, v107, v109
	global_store_dwordx4 v[32:33], v[118:121], off nt
	global_store_dwordx4 v[34:35], v[122:125], off nt
.Lbw1_skip:
	s_waitcnt lgkmcnt(0)
	v_readlane_b32 s38, v255, 61
	s_cmp_lg_u32 s38, 0
	s_ashr_i32 s81, s95, 31
	s_lshr_b32 s0, s81, 29
	s_add_i32 s0, s95, s0
	s_ashr_i32 s6, s0, 3
	s_and_b32 s0, s0, -8
	s_sub_i32 s7, s95, s0
	s_cmp_gt_i32 s7, 3
	s_cselect_b64 s[0:1], -1, 0
	v_writelane_b32 v252, s0, 6
	s_ashr_i32 s83, s96, 31
	s_movk_i32 s88, 0x1600
	v_writelane_b32 v252, s1, 7
	s_add_i32 s0, s7, -4
	v_writelane_b32 v252, s0, 8
	s_movk_i32 s84, 0x10ff
	v_readlane_b32 s0, v252, 5
	s_add_i32 s0, s0, s95
	s_cmpk_gt_i32 s95, 0xff
	v_writelane_b32 v252, s0, 9
	s_cselect_b64 s[0:1], -1, 0
	v_writelane_b32 v252, s0, 10
	v_mov_b32_e32 v1, 0
	v_mov_b32_e32 v202, 1
	v_writelane_b32 v252, s1, 11
	s_mul_hi_i32 s0, s95, 0x78787879
	s_ashr_i32 s1, s0, 6
	s_lshr_b32 s2, s0, 31
	s_ashr_i32 s0, s0, 5
	s_add_i32 s0, s0, s2
	s_and_b32 s8, s0, 1
	s_mulk_i32 s0, 0x44
	s_sub_i32 s0, s95, s0
	s_add_i32 s4, s1, s2
	s_lshl_b32 s9, s0, 6
	s_cmp_lt_i32 s0, 4
	s_cselect_b64 s[0:1], -1, 0
	s_add_i32 s2, s9, 0xffffff00
	s_sub_i32 s3, 0x10ff, s9
	s_sub_i32 s5, 0xff, s9
	v_writelane_b32 v252, s0, 12
	s_cmp_eq_u32 s8, 0
	v_mov_b32_e32 v203, 0x260
	v_writelane_b32 v252, s1, 13
	s_cselect_b64 s[0:1], -1, 0
	v_writelane_b32 v252, s0, 14
	v_mov_b32_e32 v204, 0x3ecc95a3
	v_mov_b32_e32 v205, 0x2000
	v_writelane_b32 v252, s1, 15
	s_and_b64 s[0:1], s[0:1], exec
	s_cselect_b32 s0, s2, s3
	v_writelane_b32 v252, s0, 16
	s_cselect_b32 s0, s9, s5
	v_writelane_b32 v252, s9, 17
	s_addk_i32 s0, 0x4000
	v_writelane_b32 v252, s0, 18
	s_ashr_i32 s1, s96, 3
	v_writelane_b32 v252, s8, 19
	s_lshl_b32 s0, s8, 2
	s_mul_i32 s1, s1, s7
	v_writelane_b32 v252, s0, 20
	s_and_b32 s0, s96, 7
; #define GAS __attribute__((address_space(1)))
;     const int odd = l & 1, nhh = odd ? 4 : 8;
;     ...
;     const GAS bf16_t* P = (const GAS bf16_t*)(F.ws + WS_P); const GAS bf16_t* Q = (const GAS bf16_t*)(F.ws + WS_QKV);
;     ...
;     const int odd = l & 1; const int nlin = B_ * (odd ? 4 : 8) * 2 * 4; const int ns5 = odd ? B_ * 2 * 32 : 0;
;     const int vcu = (F.G % 8 == 0) ? (F.bid % 8) * (F.G / 8) + F.bid / 8 : F.bid;
;     if (!odd || F.G <= nlin) {
;         for (int it = vcu; it < nlin + ns5; it += F.G) {
;             if (it < nlin) { if (mode != 2) seq_linear_item(F, l, it, mode >= 10 ? mode - 10 : 0); } else if (mode != 1 && mode < 10) seq_s5_item(F, l, it - nlin, 1);
;             __syncthreads();
;         }
;     } else if (vcu < nlin) { if (mode != 2) seq_linear_item(F, l, vcu, mode >= 10 ? mode - 10 : 0); }
;     else { for (int it = vcu - nlin; it < ns5; it += F.G - nlin) { if (mode != 1 && mode < 10) seq_s5_item(F, l, it, 1); __syncthreads(); } }
; }
	s_add_i32 s1, s1, s6
	s_add_i32 s2, s96, 0xffffff80
	v_writelane_b32 v252, s6, 21
	s_cmp_lt_i32 s7, 0
	v_writelane_b32 v252, s2, 22
	s_cselect_b64 s[2:3], -1, 0
	s_cmp_eq_u32 s0, 0
	v_writelane_b32 v252, s7, 23
	s_cselect_b32 s9, s1, s95
	v_writelane_b32 v252, s2, 24
	s_cmpk_gt_i32 s9, 0x7f
	s_cselect_b64 s[0:1], -1, 0
	v_writelane_b32 v252, s3, 25
	v_writelane_b32 v252, s0, 26
	s_ashr_i32 s2, s9, 2
	s_add_i32 s10, s9, 0xffffff80
	v_writelane_b32 v252, s1, 27
	s_ashr_i32 s0, s9, 3
	s_lshr_b32 s1, s0, 30
	s_add_i32 s1, s0, s1
	s_and_b32 s1, s1, 0x1fffffc
	s_sub_i32 s0, s0, s1
	s_lshr_b32 s1, s2, 29
	s_add_i32 s1, s2, s1
	s_lshl_b32 s0, s0, 7
	s_and_b32 s5, s9, 3
	s_bfe_i32 s3, s2, 0x10000
	s_and_b32 s6, s2, 1
	s_ashr_i32 s7, s1, 3
	s_ashr_i32 s1, s0, 31
	s_cmp_eq_u32 s6, 0
	s_mul_i32 s12, s2, 0x44
	s_cselect_b64 s[14:15], -1, 0
	s_lshl_b32 s2, s7, 8
	s_add_i32 s8, s2, 0x4000
	s_and_b32 s2, s3, 0xff
	v_writelane_b32 v252, s8, 28
	s_or_b32 s8, s8, s2
	s_and_b64 s[2:3], s[14:15], exec
	s_cselect_b32 s2, s88, 0xffffea00
	v_writelane_b32 v252, s2, 29
	s_mul_hi_i32 s2, s8, 0x1600
	v_writelane_b32 v252, s2, 30
	s_mul_i32 s2, s8, 0x1600
	s_cselect_b32 s11, 0, -1
	v_writelane_b32 v252, s2, 31
	s_lshl_b32 s2, s5, 6
	s_ashr_i32 s13, s12, 31
	v_writelane_b32 v252, s2, 32
	s_lshl_b64 s[2:3], s[12:13], 11
	v_writelane_b32 v252, s2, 33
	v_writelane_b32 v253, s10, 0
	v_mov_b32_e32 v206, 0x3727c5ac
	v_writelane_b32 v252, s3, 34
	s_lshl_b64 s[2:3], s[12:13], 13
	v_writelane_b32 v252, s2, 35
	v_mov_b32_e32 v207, 0x4400
	v_mov_b32_e32 v208, 0x3db504f3
	v_writelane_b32 v252, s3, 36
	s_mov_b32 s2, s12
	v_writelane_b32 v252, s2, 37
	v_mov_b32_e32 v209, 0x7f800000
	v_mov_b32_e32 v146, 0x3f317218
	v_writelane_b32 v252, s3, 38
	s_lshl_b64 s[2:3], s[12:13], 14
	v_writelane_b32 v252, s2, 39
	s_mov_b32 s13, s11
	v_mov_b32_e32 v210, 0x10ff
	v_writelane_b32 v252, s3, 40
	s_lshl_b32 s2, s7, 12
	v_writelane_b32 v252, s2, 41
	s_movk_i32 s7, 0x800
	v_writelane_b32 v252, s14, 42
	s_and_b64 s[2:3], s[14:15], exec
	s_cselect_b32 s12, s7, 0xfffff800
	s_abs_i32 s3, s54
	v_cvt_f32_u32_e32 v0, s3
	v_writelane_b32 v252, s15, 43
	v_writelane_b32 v252, s11, 44
	s_mul_i32 s2, s6, 0x4400
	v_writelane_b32 v252, s2, 45
	s_lshl_b32 s2, s5, 5
	s_or_b32 s2, s0, s2
	v_rcp_iflag_f32_e32 v0, v0
	v_writelane_b32 v252, s2, 46
	s_ashr_i32 s2, s4, 31
	v_writelane_b32 v252, s2, 47
	s_abs_i32 s2, s4
	v_writelane_b32 v252, s2, 48
	s_abs_i32 s2, s95
	v_writelane_b32 v252, s2, 49
	v_mul_f32_e32 v0, 0x4f7ffffe, v0
	s_mul_hi_i32 s5, s12, 5
	v_cvt_u32_f32_e32 v0, v0
	v_writelane_b32 v252, s12, 50
	s_mul_i32 s4, s12, 5
	s_sub_i32 s2, 0, s3
	v_writelane_b32 v252, s13, 51
	v_writelane_b32 v252, s4, 52
	s_ashr_i32 s55, s54, 31
	v_mov_b32_e32 v211, 0xff
	v_writelane_b32 v252, s5, 53
	v_writelane_b32 v252, s3, 54
	v_readfirstlane_b32 s3, v0
	s_mul_i32 s2, s2, s3
	s_mul_hi_u32 s2, s3, s2
	s_add_i32 s2, s3, s2
	v_writelane_b32 v252, s2, 55
	s_lshl_b64 s[2:3], s[54:55], 2
	v_writelane_b32 v252, s2, 56
	s_mul_i32 s4, s96, 0x8800
	v_mov_b32_e32 v201, 0x1000
	v_writelane_b32 v252, s3, 57
	s_mul_i32 s3, s95, 0x8800
	s_mul_hi_i32 s2, s95, 0x8800
	s_add_u32 s3, s3, 0x40d54c00
	v_writelane_b32 v252, s3, 58
	s_addc_u32 s2, s2, 0
	v_writelane_b32 v252, s2, 59
	s_mul_hi_i32 s2, s96, 0x8800
	v_writelane_b32 v252, s2, 60
	s_mul_i32 s3, s9, 0x8800
	s_mul_hi_i32 s2, s9, 0x8800
	v_writelane_b32 v252, s9, 61
	s_add_u32 s5, s3, 0x40d54c00
	v_writelane_b32 v252, s5, 62
	s_addc_u32 s2, s2, 0
	s_add_i32 s3, s3, 0xffbc0000
	v_writelane_b32 v252, s2, 63
	s_mul_hi_i32 s2, s10, 0x8800
	s_add_u32 s3, s3, 0x40d54c00
	v_writelane_b32 v253, s3, 1
	s_addc_u32 s2, s2, 0
	v_writelane_b32 v253, s2, 2
	v_writelane_b32 v253, s4, 3
	s_add_i32 s2, s4, 0xffbc0000
	v_writelane_b32 v253, s2, 4
	s_lshl_b64 s[0:1], s[0:1], 1
	v_writelane_b32 v253, s0, 5
	s_add_i32 s86, 0, 0x20200
	v_mov_b32_e32 v250, 0x2200
	v_writelane_b32 v253, s1, 6
	s_add_i32 s0, 0, 0x27e00
	v_writelane_b32 v253, s0, 7
	s_add_i32 s0, 0, 0x27e04
	v_writelane_b32 v253, s0, 8
	s_add_i32 s0, 0, 0x15000
	v_writelane_b32 v253, s0, 9
	s_add_i32 s0, 0, 0x24400
	v_writelane_b32 v253, s0, 10
	s_add_i32 s0, 0, 0x23200
	v_writelane_b32 v253, s0, 11
	s_add_i32 s0, 0, 0x21000
	v_writelane_b32 v253, s0, 12
	s_add_i32 s0, 0, 0x24600
	v_writelane_b32 v253, s0, 13
	s_add_i32 s0, 0, 0xe400
	v_writelane_b32 v253, s0, 14
	s_add_i32 s0, 0, 0xe800
	v_writelane_b32 v253, s0, 15
	s_add_i32 s0, 0, 0xec00
	v_writelane_b32 v253, s0, 16
	s_add_i32 s0, 0, 0x10400
	v_writelane_b32 v253, s0, 17
	s_add_i32 s0, 0, 0xc400
	v_writelane_b32 v253, s0, 18
	s_add_i32 s0, 0, 0xc800
	v_writelane_b32 v253, s0, 19
	s_add_i32 s0, 0, 0xcc00
	v_writelane_b32 v253, s0, 20
	s_add_i32 s0, 0, 0xd000
	v_writelane_b32 v253, s0, 21
	s_add_i32 s0, 0, 0xd400
	v_writelane_b32 v253, s0, 22
	s_add_i32 s0, 0, 0xdc00
	v_writelane_b32 v253, s0, 23
	s_mov_b32 s1, 0
	v_writelane_b32 v253, s95, 24
	s_mov_b32 s52, s1
	v_writelane_b32 v253, s96, 25
	v_writelane_b32 v253, s44, 26
	s_mov_b32 s0, s82
	v_mov_b32_e32 v220, 0xba800000
	v_writelane_b32 v253, s45, 27
	v_writelane_b32 v253, s46, 28
	v_writelane_b32 v253, s47, 29
	v_writelane_b32 v253, s48, 30
	v_writelane_b32 v253, s49, 31
	v_writelane_b32 v253, s50, 32
	v_writelane_b32 v253, s51, 33
	v_writelane_b32 v253, s52, 34
	v_writelane_b32 v253, s53, 35
	v_writelane_b32 v253, s54, 36
	v_writelane_b32 v253, s55, 37
	v_writelane_b32 v253, s56, 38
	v_writelane_b32 v253, s57, 39
	v_writelane_b32 v253, s58, 40
	v_writelane_b32 v253, s59, 41
	v_writelane_b32 v253, s54, 42
	v_mov_b32_e32 v221, 0x3a800000
	v_mov_b32_e32 v222, 0x900
	v_writelane_b32 v253, s55, 43
	v_writelane_b32 v253, s0, 44
	v_mov_b32_e32 v149, 0x10000
	s_mov_b32 s94, 0xf800000
	v_writelane_b32 v253, s1, 45
	v_writelane_b32 v253, s81, 46
	v_writelane_b32 v253, s83, 47
	s_mov_b32 s97, 0x3fb8aa3b
	s_mov_b32 s80, 0xc2ce8ed0
	s_mov_b32 s85, 0x42b17218
	s_movk_i32 s89, 0x1fff
	s_mov_b64 s[90:91], 0x80
	s_mov_b32 s92, 0x3fd744fd
	v_writelane_b32 v253, s86, 48
	s_waitcnt lgkmcnt(0)
	s_barrier
	s_branch .LBB0_173

; #define WAIT_VM(n) do {} while (0)
; #define WAIT_VM(n) asm volatile("s_waitcnt vmcnt(" #n ")" ::: "memory")
; DEV unsigned xb_ld(unsigned* p) { return __hip_atomic_load(p, __ATOMIC_RELAXED, __HIP_MEMORY_SCOPE_AGENT); }
; DEV void fence_acquire() { __builtin_amdgcn_fence(__ATOMIC_ACQUIRE, "agent"); }
; #define XB_SPIN(cond, bar) do { unsigned _sp = 0; while (cond) { s_sleep1(); \
;     if ((++_sp & 255u) == 0u) { if (xb_ld(&(bar)[XB_TMO])) break; if (_sp > XB_SPIN_CAP) { xb_add(&(bar)[XB_TMO], 1u); break; } } } } while (0)
; DEV void xcd_barrier(const XcdBarrier& b) {
;     ...
;             XB_SPIN(xb_ld(&bar[XB_XGEN(bx)]) == gen, bar);
;             fence_acquire();
;             WAIT_VM(0);
;         }
;     }
;     __syncthreads();
; DEV void phase_prologue_a(const Frame& F0) {
;     ...
;         constexpr int GU_NB = 2 * FF / 32, GU_ITEMS = 16 * GU_NB;
;         for (int it = F.gw; it < NE * GU_ITEMS; it += F.NGW) { const int e = it / GU_ITEMS, r = it % GU_ITEMS, kb = r / GU_NB, nb = r % GU_NB; const int d0 = 32 * nb, j = d0 >> 8, w = d0 & 255;
;             const float* src = (w < 128 ? GIN(I_WGATE) : GIN(I_WUP)) + ((size_t)l * NE + e) * 1024 * FF;
;             tr_item(src, FF, 128 * j + (w & 127), 64 * kb, (bf16_t*)(F.ws + WS_WGU) + ((size_t)l * NE + e) * 2 * FF * 1024, 1024, d0, scr, F.lane); }
.LBB0_241:
	v_writelane_b32 v253, s58, 51
	s_nop 1
	v_writelane_b32 v253, s59, 52
	v_writelane_b32 v253, s56, 53
	s_nop 1
	v_writelane_b32 v253, s57, 54
	s_or_b64 exec, exec, s[34:35]
	s_cselect_b32 s38, 1, 0
	v_writelane_b32 v255, s38, 61
	v_readlane_b32 s38, v255, 59
	s_add_i32 s39, s38, 1
	v_writelane_b32 v255, s39, 59
	s_mov_b32 s41, 0
	v_readlane_b32 s39, v251, 29
	s_cmp_eq_u32 s39, 0
	s_cbranch_scc1 .Lbw2_none
	v_readlane_b32 s40, v255, 51
	s_cmp_lg_u32 s40, 0x100
	s_cbranch_scc1 .Lbw2_none
	v_readlane_b32 s40, v255, 48
	s_mul_i32 s40, s40, 7
	s_mul_i32 s38, s38, 0x700
	s_add_i32 s40, s40, s38
	s_add_i32 s40, s40, s39
	s_add_i32 s40, s40, -1
	s_cmp_lt_u32 s40, 0x11f00
	s_cbranch_scc0 .Lbw2_none
	s_mov_b32 s41, 1
	s_cmp_lt_u32 s40, 0x8000
	s_cbranch_scc1 .Lbw2_have
	s_mov_b32 s41, 2
	s_sub_i32 s40, s40, 0x8000
	s_cmp_lt_u32 s40, 0x5200
	s_cbranch_scc1 .Lbw2_have
	s_mov_b32 s41, 3
	s_sub_i32 s40, s40, 0x5200

; #define LAS __attribute__((address_space(3)))
; #define NT_LOAD(p) __builtin_nontemporal_load(p)
; DEV void tr_item(const float* W, int ldw, int col0, int k0, bf16_t* WT, int K, int row0, LAS float* scr, int lane) {
; #pragma unroll 8
;     for (int i = 0; i < 32; ++i) { const int kk = 2 * i + (lane >> 5); scr[kk * 33 + (lane & 31)] = NT_LOAD(&W[(size_t)(k0 + kk) * ldw + col0 + (lane & 31)]); }
.Lbw2_gate:
	s_add_u32 s42, s100, s42
	s_addc_u32 s43, s101, 0
	s_lshl_b32 s39, s41, 16
	s_or_b32 s41, s39, s40
	v_lshrrev_b32_e32 v129, 5, v200
	v_and_b32_e32 v130, 31, v200
	v_lshlrev_b32_e32 v130, 2, v130
	v_lshl_add_u32 v36, v129, 13, v130
	v_mov_b32_e32 v37, 0
	s_mov_b64 s[100:101], 0x4000
	v_lshl_add_u64 v[20:21], s[42:43], 0, v[36:37]
	v_lshl_add_u64 v[22:23], v[20:21], 0, s[100:101]
	v_lshl_add_u64 v[24:25], v[22:23], 0, s[100:101]
	v_lshl_add_u64 v[26:27], v[24:25], 0, s[100:101]
	v_lshl_add_u64 v[28:29], v[26:27], 0, s[100:101]
	v_lshl_add_u64 v[30:31], v[28:29], 0, s[100:101]
	v_lshl_add_u64 v[32:33], v[30:31], 0, s[100:101]
	v_lshl_add_u64 v[34:35], v[32:33], 0, s[100:101]
	s_mov_b64 s[100:101], 0x20000
	global_load_dword v38, v[20:21], off nt
	global_load_dword v39, v[22:23], off nt
	global_load_dword v40, v[24:25], off nt
	global_load_dword v41, v[26:27], off nt
	global_load_dword v42, v[28:29], off nt
	global_load_dword v43, v[30:31], off nt
	global_load_dword v44, v[32:33], off nt
	global_load_dword v45, v[34:35], off nt
	v_lshl_add_u64 v[20:21], v[20:21], 0, s[100:101]
	v_lshl_add_u64 v[22:23], v[22:23], 0, s[100:101]
	v_lshl_add_u64 v[24:25], v[24:25], 0, s[100:101]
	v_lshl_add_u64 v[26:27], v[26:27], 0, s[100:101]
	v_lshl_add_u64 v[28:29], v[28:29], 0, s[100:101]
	v_lshl_add_u64 v[30:31], v[30:31], 0, s[100:101]
	v_lshl_add_u64 v[32:33], v[32:33], 0, s[100:101]
	v_lshl_add_u64 v[34:35], v[34:35], 0, s[100:101]
	global_load_dword v46, v[20:21], off nt
	global_load_dword v47, v[22:23], off nt
	global_load_dword v48, v[24:25], off nt
	global_load_dword v49, v[26:27], off nt
	global_load_dword v50, v[28:29], off nt
	global_load_dword v51, v[30:31], off nt
	global_load_dword v52, v[32:33], off nt
	global_load_dword v53, v[34:35], off nt
	v_lshl_add_u64 v[20:21], v[20:21], 0, s[100:101]
	v_lshl_add_u64 v[22:23], v[22:23], 0, s[100:101]
	v_lshl_add_u64 v[24:25], v[24:25], 0, s[100:101]
	v_lshl_add_u64 v[26:27], v[26:27], 0, s[100:101]
	v_lshl_add_u64 v[28:29], v[28:29], 0, s[100:101]
	v_lshl_add_u64 v[30:31], v[30:31], 0, s[100:101]
	v_lshl_add_u64 v[32:33], v[32:33], 0, s[100:101]
	v_lshl_add_u64 v[34:35], v[34:35], 0, s[100:101]
	global_load_dword v54, v[20:21], off nt
	global_load_dword v55, v[22:23], off nt
	global_load_dword v56, v[24:25], off nt
	global_load_dword v57, v[26:27], off nt
	global_load_dword v58, v[28:29], off nt
	global_load_dword v59, v[30:31], off nt
	global_load_dword v60, v[32:33], off nt
	global_load_dword v61, v[34:35], off nt
	v_lshl_add_u64 v[20:21], v[20:21], 0, s[100:101]
	v_lshl_add_u64 v[22:23], v[22:23], 0, s[100:101]
	v_lshl_add_u64 v[24:25], v[24:25], 0, s[100:101]
	v_lshl_add_u64 v[26:27], v[26:27], 0, s[100:101]
	v_lshl_add_u64 v[28:29], v[28:29], 0, s[100:101]
	v_lshl_add_u64 v[30:31], v[30:31], 0, s[100:101]
	v_lshl_add_u64 v[32:33], v[32:33], 0, s[100:101]
	v_lshl_add_u64 v[34:35], v[34:35], 0, s[100:101]
	global_load_dword v62, v[20:21], off nt
	global_load_dword v63, v[22:23], off nt
	global_load_dword v64, v[24:25], off nt
	global_load_dword v65, v[26:27], off nt
	global_load_dword v66, v[28:29], off nt
	global_load_dword v67, v[30:31], off nt
	global_load_dword v68, v[32:33], off nt
	global_load_dword v69, v[34:35], off nt
	s_branch .Lbw2_fin

; #define WAVE_LDS_SYNC() do { int _z = 0; (void)emu::wave_xchg(&_z, 4); } while (0)
; #define LAS __attribute__((address_space(3)))
; #define WAVE_LDS_SYNC() asm volatile("s_waitcnt lgkmcnt(0)" ::: "memory")
; #define NT_LOAD(p) __builtin_nontemporal_load(p)
; #define NT_STORE(v, p) __builtin_nontemporal_store((v), (p))
; DEV unsigned pk2(float lo, float hi) { return f2bf(lo) | (f2bf(hi) << 16); }
; DEV unsigned pk2(float lo, float hi) { const f32x2n_t v = {lo, hi}; return __builtin_bit_cast(unsigned, __builtin_convertvector(v, bf16x2n_t)); }
; DEV void tr_item(const float* W, int ldw, int col0, int k0, bf16_t* WT, int K, int row0, LAS float* scr, int lane) {
; #pragma unroll 8
;     for (int i = 0; i < 32; ++i) { const int kk = 2 * i + (lane >> 5); scr[kk * 33 + (lane & 31)] = NT_LOAD(&W[(size_t)(k0 + kk) * ldw + col0 + (lane & 31)]); }
;     WAVE_LDS_SYNC();
;     const int c = lane & 7;
; #pragma unroll
;     for (int j = 0; j < 4; ++j) { const int n = (lane >> 3) + 8 * j; const LAS float* s = scr + (8 * c) * 33 + n;
;         u32x4 o; o.x = pk2(s[0 * 33], s[1 * 33]); o.y = pk2(s[2 * 33], s[3 * 33]); o.z = pk2(s[4 * 33], s[5 * 33]); o.w = pk2(s[6 * 33], s[7 * 33]);
;         NT_STORE(o, (u32x4*)(WT + (size_t)(row0 + n) * K + k0 + 8 * c)); }
;     WAVE_LDS_SYNC();
.Lbw2_fin:
	v_writelane_b32 v255, s41, 60
	s_nop 0
	v_readlane_b32 s40, v255, 60
	s_cmp_eq_u32 s40, 0
	s_cbranch_scc1 .Lbw2_skip
	s_lshr_b32 s41, s40, 16
	s_and_b32 s40, s40, 0xffff
	s_and_b32 s38, s40, 0x7ff
	s_lshr_b32 s39, s38, 7
	s_and_b32 s38, s38, 0x7f
	s_lshl_b32 s42, s38, 16
	s_lshl_b32 s39, s39, 7
	s_add_i32 s42, s42, s39
	s_lshr_b32 s39, s40, 11
	s_lshl_b32 s39, s39, 23
	s_add_i32 s42, s42, s39
	s_lshl_b32 s39, s41, 27
	s_add_u32 s42, s42, s39
	s_add_u32 s42, s42, 0x2bc8000
	v_readlane_b32 s100, v255, 53
	v_readlane_b32 s101, v255, 54
	s_add_u32 s42, s100, s42
	s_addc_u32 s43, s101, 0
	v_readlane_b32 s39, v251, 29
	s_lshl_b32 s39, s39, 14
	v_and_b32_e32 v129, 31, v200
	v_lshrrev_b32_e32 v130, 5, v200
	v_mul_u32_u24_e32 v130, 33, v130
	v_add_u32_e32 v130, v130, v129
	v_lshl_add_u32 v120, v130, 2, s39
	v_add_u32_e32 v121, 0x400, v120
	v_add_u32_e32 v122, 0x840, v120
	v_add_u32_e32 v123, 0xc40, v120
	v_add_u32_e32 v124, 0x1080, v120
	v_add_u32_e32 v125, 0x1480, v120
	v_add_u32_e32 v126, 0x18c0, v120
	v_add_u32_e32 v127, 0x1cc0, v120
	v_and_b32_e32 v129, 7, v200
	v_lshrrev_b32_e32 v130, 3, v200
	v_mul_u32_u24_e32 v131, 0x108, v129
	v_add_u32_e32 v131, v131, v130
	v_lshl_add_u32 v128, v131, 2, s39
	v_lshlrev_b32_e32 v129, 4, v129
	v_lshl_add_u32 v36, v130, 11, v129
	v_mov_b32_e32 v37, 0
	s_mov_b64 s[100:101], 0x4000
	v_lshl_add_u64 v[20:21], s[42:43], 0, v[36:37]
	v_lshl_add_u64 v[22:23], v[20:21], 0, s[100:101]
	v_lshl_add_u64 v[24:25], v[22:23], 0, s[100:101]
	v_lshl_add_u64 v[26:27], v[24:25], 0, s[100:101]
	s_waitcnt vmcnt(0)
	ds_write2_b32 v120, v38, v39 offset1:66
	ds_write2_b32 v120, v40, v41 offset0:132 offset1:198
	ds_write2_b32 v121, v42, v43 offset0:8 offset1:74
	ds_write2_b32 v121, v44, v45 offset0:140 offset1:206
	ds_write2_b32 v122, v46, v47 offset1:66
	ds_write2_b32 v122, v48, v49 offset0:132 offset1:198
	ds_write2_b32 v123, v50, v51 offset0:8 offset1:74
	ds_write2_b32 v123, v52, v53 offset0:140 offset1:206
	ds_write2_b32 v124, v54, v55 offset1:66
	ds_write2_b32 v124, v56, v57 offset0:132 offset1:198
	ds_write2_b32 v125, v58, v59 offset0:8 offset1:74
	ds_write2_b32 v125, v60, v61 offset0:140 offset1:206
	ds_write2_b32 v126, v62, v63 offset1:66
	ds_write2_b32 v126, v64, v65 offset0:132 offset1:198
	ds_write2_b32 v127, v66, v67 offset0:8 offset1:74
	ds_write2_b32 v127, v68, v69 offset0:140 offset1:206
	ds_read2_b32 v[70:71], v128 offset1:8
	ds_read2_b32 v[72:73], v128 offset0:33 offset1:41
	ds_read2_b32 v[74:75], v128 offset0:66 offset1:74
	ds_read2_b32 v[76:77], v128 offset0:99 offset1:107
	ds_read2_b32 v[78:79], v128 offset0:132 offset1:140
	ds_read2_b32 v[80:81], v128 offset0:165 offset1:173
	ds_read2_b32 v[82:83], v128 offset0:198 offset1:206
	ds_read2_b32 v[84:85], v128 offset0:231 offset1:239
	ds_read2_b32 v[88:89], v128 offset0:16 offset1:24
	ds_read2_b32 v[90:91], v128 offset0:49 offset1:57
	ds_read2_b32 v[92:93], v128 offset0:82 offset1:90
	ds_read2_b32 v[94:95], v128 offset0:115 offset1:123
	s_waitcnt lgkmcnt(4)
	v_cvt_pk_bf16_f32 v104, v70, v72
	v_cvt_pk_bf16_f32 v105, v74, v76
	v_cvt_pk_bf16_f32 v106, v78, v80
	v_cvt_pk_bf16_f32 v107, v82, v84
	v_cvt_pk_bf16_f32 v108, v71, v73
	v_cvt_pk_bf16_f32 v109, v75, v77
	v_cvt_pk_bf16_f32 v110, v79, v81
	v_cvt_pk_bf16_f32 v111, v83, v85
	ds_read2_b32 v[96:97], v128 offset0:148 offset1:156
	ds_read2_b32 v[98:99], v128 offset0:181 offset1:189
	ds_read2_b32 v[100:101], v128 offset0:214 offset1:222
	ds_read2_b32 v[102:103], v128 offset0:247 offset1:255
	global_store_dwordx4 v[20:21], v[104:107], off nt
	global_store_dwordx4 v[22:23], v[108:111], off nt
	s_waitcnt lgkmcnt(0)
	v_cvt_pk_bf16_f32 v112, v88, v90
	v_cvt_pk_bf16_f32 v113, v92, v94
	v_cvt_pk_bf16_f32 v114, v96, v98
	v_cvt_pk_bf16_f32 v115, v100, v102
	v_cvt_pk_bf16_f32 v116, v89, v91
	v_cvt_pk_bf16_f32 v117, v93, v95
	v_cvt_pk_bf16_f32 v118, v97, v99
	v_cvt_pk_bf16_f32 v119, v101, v103
	global_store_dwordx4 v[24:25], v[112:115], off nt
	global_store_dwordx4 v[26:27], v[116:119], off nt
; DEV void row_bs(int r, int& b, int& s) { if (r < LATR) { b = r / SEQ; s = CTX + r % SEQ; } else { const int q = r - LATR; b = q / CTX; s = q % CTX; } }
; #define ROW_GROUPS(nrows, CALL4, CALL2) do { const int _r4 = ((nrows) / (4 * F.NGW)) * (4 * F.NGW); \
;     for (int r = 4 * F.gw; r < _r4; r += 4 * F.NGW) { CALL4; } for (int r = _r4 + (F.wave * F.G + F.bid); r < (nrows); r += F.NGW) { CALL2; } } while (0)
; template <int RG> DEV void prep_group(const Frame& F, int l, int r) {
;     const int odd = l & 1, li = l >> 1; const int nin = odd ? NIN_O : NIN_E, nseg = odd ? 2 : 3, qld = odd ? 1024 : 1536;
;     const bf16_t* P = (const bf16_t*)(F.ws + WS_P); bf16_t* Q = (bf16_t*)(F.ws + WS_QKV);
;     const float* cw = odd ? GIN(I_ODCONV) + (size_t)li * 9 * 1024 : GIN(I_EVCONV) + (size_t)li * 9 * 1536; const int cch = odd ? 1024 : 1536;
;     {
;         int b, s; row_bs(r, b, s); const bool lat = s >= CTX; const int rr = lat ? (s - CTX) >> 6 : 0, cc = lat ? (s - CTX) & 63 : s;
;         const int ncol = lat ? 64 : CTX;
;         for (int seg = 0; seg < nseg; ++seg) {
;             const int ch0 = seg * 512 + F.lane * 8; float a[RG][8];
; #pragma unroll
;             for (int q = 0; q < RG; ++q)
; #pragma unroll
;                 for (int i = 0; i < 8; ++i) a[q][i] = 0.f;
;             u32x4 pv[3][RG + 2]; f32x4 w0[3][3], w1[3][3];
; #pragma unroll
;             for (int kh = 0; kh < 3; ++kh) {
;                 const int r2 = rr + kh - 1; const bool rok = lat ? (r2 >= 0 && r2 < SEQ / 64) : (kh == 1); const int r2c = rok ? r2 : rr;
;                 const int rowbase = lat ? b * SEQ + r2c * 64 : LATR + b * CTX;
; #pragma unroll
;                 for (int dc = 0; dc < RG + 2; ++dc) { const int c2 = cc - 1 + dc; const bool ok = rok && c2 >= 0 && c2 < ncol; const int c2c = ok ? c2 : cc;
;                     const u32x4 t4 = *(const u32x4*)(P + (size_t)(rowbase + c2c) * nin + ch0); pv[kh][dc] = ok ? t4 : (u32x4){0u, 0u, 0u, 0u}; }
; #pragma unroll
;                 for (int kw = 0; kw < 3; ++kw) { w0[kh][kw] = *(const f32x4*)(cw + (kh * 3 + kw) * cch + ch0); w1[kh][kw] = *(const f32x4*)(cw + (kh * 3 + kw) * cch + ch0 + 4); }
;             }
; DEV void phase_prep(const Frame& F0, int l) {
;     const Frame F = refresh(F0);
;     const int odd = l & 1;
;     ROW_GROUPS(MROWS, prep_group<4>(F, l, r), prep_group<1>(F, l, r));
.Lbw2_skip:
	s_waitcnt lgkmcnt(0)
	v_readlane_b32 s38, v255, 61
	s_cmp_lg_u32 s38, 0
	s_mov_b64 s[74:75], s[54:55]
	v_readlane_b32 s4, v251, 0
	v_readlane_b32 s2, v251, 29
	v_readlane_b32 s0, v251, 30
	v_readlane_b32 s5, v251, 1
	v_readlane_b32 s6, v251, 2
	v_readlane_b32 s7, v251, 3
	v_writelane_b32 v251, s64, 47
	v_mov_b32_e32 v223, v200
	s_mov_b64 s[4:5], s[6:7]
	v_writelane_b32 v251, s65, 48
	v_writelane_b32 v251, s66, 49
	v_writelane_b32 v251, s67, 50
	v_writelane_b32 v251, s68, 51
	v_writelane_b32 v251, s69, 52
	v_writelane_b32 v251, s70, 53
	v_writelane_b32 v251, s71, 54
	s_waitcnt lgkmcnt(0)
	s_barrier
	v_writelane_b32 v251, s72, 55
	v_writelane_b32 v253, s2, 55
	s_add_i32 s2, s2, s0
	v_writelane_b32 v253, s4, 56
	v_writelane_b32 v251, s73, 56
	s_mov_b32 s0, s2
	v_writelane_b32 v253, s5, 57
	v_writelane_b32 v251, s74, 57
	v_writelane_b32 v253, s0, 58
	v_and_b32_e32 v227, 15, v223
	v_writelane_b32 v251, s75, 58
	v_writelane_b32 v253, s1, 59
	s_lshl_b32 s93, s2, 2
	v_cmp_lt_u32_e64 s[2:3], 7, v227
	v_writelane_b32 v251, s76, 59
	v_writelane_b32 v251, s77, 60
	v_writelane_b32 v253, s2, 60
	v_writelane_b32 v251, s78, 61
	v_bfe_u32 v226, v223, 2, 2
	v_writelane_b32 v253, s3, 61
	v_writelane_b32 v253, s52, 62
	v_writelane_b32 v251, s79, 62
	v_readlane_b32 s0, v252, 5
	v_lshrrev_b32_e32 v0, 1, v223
	v_writelane_b32 v253, s53, 63
	v_add_u32_e32 v229, s52, v226
	v_readlane_b32 s52, v251, 31
	s_cmp_ge_i32 s93, s0
	v_lshlrev_b32_e32 v152, 3, v223
	v_ashrrev_i32_e32 v224, 4, v223
	v_and_b32_e32 v225, 3, v223
	v_and_b32_e32 v228, 4, v0
	v_lshlrev_b32_e32 v154, 2, v227
	v_lshlrev_b32_e32 v150, 1, v227
	v_readlane_b32 s53, v251, 32
	v_readlane_b32 s54, v251, 33
	v_readlane_b32 s55, v251, 34
	v_readlane_b32 s56, v251, 35
	v_readlane_b32 s57, v251, 36
	v_readlane_b32 s58, v251, 37
	v_readlane_b32 s59, v251, 38
	v_readlane_b32 s60, v251, 39
	v_readlane_b32 s61, v251, 40
	v_readlane_b32 s62, v251, 41
	v_readlane_b32 s63, v251, 42
	v_readlane_b32 s64, v251, 43
	v_readlane_b32 s65, v251, 44
	v_readlane_b32 s66, v251, 45
	v_readlane_b32 s67, v251, 46
	s_cbranch_scc1 .LBB0_306
	v_readlane_b32 s14, v253, 62
	s_lshr_b32 s0, s14, 1
	v_readlane_b32 s2, v253, 49
	s_cmp_lg_u32 s2, 0
	s_cselect_b64 s[12:13], -1, 0
	s_cmp_eq_u32 s2, 0
	s_cselect_b64 s[2:3], -1, 0
	v_writelane_b32 v254, s2, 0
	v_readlane_b32 s15, v253, 63
	v_readlane_b32 s18, v253, 56
	v_writelane_b32 v254, s3, 1
	s_and_b64 s[2:3], s[12:13], exec
	s_movk_i32 s2, 0x1100
	s_cselect_b32 s16, 0xb00, s2
	s_movk_i32 s2, 0x600
	s_cselect_b32 s15, 0x400, s2
	v_readlane_b32 s19, v253, 57
	s_add_u32 s20, s18, 0x415d4c00
	s_addc_u32 s21, s19, 0
	s_add_u32 s2, s18, 0x4a654c00
	s_addc_u32 s3, s19, 0
	v_writelane_b32 v254, s2, 2
	v_mov_b32_e32 v155, v1
	v_readlane_b32 s36, v251, 12
	v_writelane_b32 v254, s3, 3
	s_and_b64 s[2:3], s[12:13], exec
	s_mov_b32 s2, 0x9000
	s_cselect_b32 s2, s2, 0xd800
	s_mul_hi_u32 s4, s2, s0
	s_mul_i32 s0, s2, s0
	v_cmp_gt_i32_e64 s[2:3], 64, v223
	s_lshl_b32 s5, s15, 1
	s_lshl_b32 s7, s15, 2
	v_writelane_b32 v254, s2, 4
	s_lshl_b32 s11, s15, 3
	v_readlane_b32 s50, v251, 26
	v_writelane_b32 v254, s3, 5
	s_and_b32 s2, s14, 2
	v_and_or_b32 v2, v226, 1, s2
	v_lshlrev_b32_e32 v2, 3, v2
	v_or3_b32 v4, v2, v228, v225
	v_lshl_add_u64 v[2:3], s[18:19], 0, v[154:155]
	s_mov_b64 s[2:3], 0x39298800
	v_lshl_add_u64 v[156:157], v[2:3], 0, s[2:3]
	s_and_b64 s[2:3], s[12:13], exec
	v_readlane_b32 s37, v251, 13
	v_readlane_b32 s51, v251, 27
	s_cselect_b32 s3, s50, s36
	s_cselect_b32 s2, s51, s37
	s_add_u32 s18, s3, s0
	s_addc_u32 s19, s2, s4
	v_writelane_b32 v254, s18, 6
	v_lshl_or_b32 v0, v229, 2, v225
	s_mul_i32 s6, s15, 3
	v_writelane_b32 v254, s19, 7
	v_writelane_b32 v254, s20, 8
	s_mul_i32 s8, s15, 5
	s_mul_i32 s9, s15, 6
	s_mul_i32 s10, s15, 7
	v_readlane_b32 s38, v251, 14
	v_readlane_b32 s39, v251, 15
	v_readlane_b32 s40, v251, 16
	v_readlane_b32 s41, v251, 17
	v_readlane_b32 s42, v251, 18
	v_readlane_b32 s44, v251, 20
	v_readlane_b32 s46, v251, 22
	v_lshlrev_b64 v[2:3], 2, v[0:1]
	v_lshlrev_b32_e32 v0, 2, v4
	v_mov_b32_e32 v151, v1
	v_writelane_b32 v254, s21, 9
	s_mov_b32 s17, s1
	v_lshl_add_u64 v[158:159], s[38:39], 0, v[2:3]
	v_lshl_add_u64 v[160:161], s[40:41], 0, v[2:3]
	v_lshl_add_u64 v[162:163], s[52:53], 0, v[0:1]
	v_lshl_add_u64 v[164:165], s[20:21], 0, v[150:151]
	v_writelane_b32 v254, s15, 10
	s_lshl_b32 s0, s15, 2
	s_lshl_b32 s24, s5, 2
	s_lshl_b32 s26, s6, 2
	s_lshl_b32 s38, s7, 2
	s_lshl_b32 s40, s8, 2
	s_lshl_b32 s42, s9, 2
	s_lshl_b32 s44, s10, 2
	s_lshl_b32 s46, s11, 2
	v_readlane_b32 s43, v251, 19
	v_readlane_b32 s45, v251, 21
	v_readlane_b32 s47, v251, 23
	v_readlane_b32 s48, v251, 24
	v_readlane_b32 s49, v251, 25
	s_branch .LBB0_246

; #define WAIT_VM(n) do {} while (0)
; #define WAIT_VM(n) asm volatile("s_waitcnt vmcnt(" #n ")" ::: "memory")
; DEV unsigned xb_ld(unsigned* p) { return __hip_atomic_load(p, __ATOMIC_RELAXED, __HIP_MEMORY_SCOPE_AGENT); }
; DEV void fence_acquire() { __builtin_amdgcn_fence(__ATOMIC_ACQUIRE, "agent"); }
; #define XB_SPIN(cond, bar) do { unsigned _sp = 0; while (cond) { s_sleep1(); \
;     if ((++_sp & 255u) == 0u) { if (xb_ld(&(bar)[XB_TMO])) break; if (_sp > XB_SPIN_CAP) { xb_add(&(bar)[XB_TMO], 1u); break; } } } } while (0)
; DEV void xcd_barrier(const XcdBarrier& b) {
;     ...
;             XB_SPIN(xb_ld(&bar[XB_XGEN(bx)]) == gen, bar);
;             fence_acquire();
;             WAIT_VM(0);
;         }
;     }
;     __syncthreads();
; DEV void phase_prologue_a(const Frame& F0) {
;     ...
;         constexpr int GU_NB = 2 * FF / 32, GU_ITEMS = 16 * GU_NB;
;         for (int it = F.gw; it < NE * GU_ITEMS; it += F.NGW) { const int e = it / GU_ITEMS, r = it % GU_ITEMS, kb = r / GU_NB, nb = r % GU_NB; const int d0 = 32 * nb, j = d0 >> 8, w = d0 & 255;
;             const float* src = (w < 128 ? GIN(I_WGATE) : GIN(I_WUP)) + ((size_t)l * NE + e) * 1024 * FF;
;             tr_item(src, FF, 128 * j + (w & 127), 64 * kb, (bf16_t*)(F.ws + WS_WGU) + ((size_t)l * NE + e) * 2 * FF * 1024, 1024, d0, scr, F.lane); }
.LBB0_422:
	s_or_b64 exec, exec, s[34:35]
	s_cselect_b32 s38, 1, 0
	v_writelane_b32 v255, s38, 61
	v_readlane_b32 s38, v255, 59
	s_add_i32 s39, s38, 1
	v_writelane_b32 v255, s39, 59
	s_mov_b32 s41, 0
	v_readlane_b32 s39, v251, 29
	s_cmp_eq_u32 s39, 0
	s_cbranch_scc1 .Lbw3_none
	v_readlane_b32 s40, v255, 51
	s_cmp_lg_u32 s40, 0x100
	s_cbranch_scc1 .Lbw3_none
	v_readlane_b32 s40, v255, 48
	s_mul_i32 s40, s40, 7
	s_mul_i32 s38, s38, 0x700
	s_add_i32 s40, s40, s38
	s_add_i32 s40, s40, s39
	s_add_i32 s40, s40, -1
	s_cmp_lt_u32 s40, 0x11f00
	s_cbranch_scc0 .Lbw3_none
	s_mov_b32 s41, 1
	s_cmp_lt_u32 s40, 0x8000
	s_cbranch_scc1 .Lbw3_have
	s_mov_b32 s41, 2
	s_sub_i32 s40, s40, 0x8000
	s_cmp_lt_u32 s40, 0x5200
	s_cbranch_scc1 .Lbw3_have
	s_mov_b32 s41, 3
	s_sub_i32 s40, s40, 0x5200

; #define LAS __attribute__((address_space(3)))
; #define NT_LOAD(p) __builtin_nontemporal_load(p)
; DEV void tr_item(const float* W, int ldw, int col0, int k0, bf16_t* WT, int K, int row0, LAS float* scr, int lane) {
; #pragma unroll 8
;     for (int i = 0; i < 32; ++i) { const int kk = 2 * i + (lane >> 5); scr[kk * 33 + (lane & 31)] = NT_LOAD(&W[(size_t)(k0 + kk) * ldw + col0 + (lane & 31)]); }
.Lbw3_gate:
	s_add_u32 s42, s100, s42
	s_addc_u32 s43, s101, 0
	s_lshl_b32 s39, s41, 16
	s_or_b32 s41, s39, s40
	v_lshrrev_b32_e32 v144, 5, v200
	v_and_b32_e32 v145, 31, v200
	v_lshlrev_b32_e32 v145, 2, v145
	v_lshl_add_u32 v36, v144, 13, v145
	v_mov_b32_e32 v37, 0
	s_mov_b64 s[100:101], 0x4000
	v_lshl_add_u64 v[20:21], s[42:43], 0, v[36:37]
	v_lshl_add_u64 v[22:23], v[20:21], 0, s[100:101]
	v_lshl_add_u64 v[24:25], v[22:23], 0, s[100:101]
	v_lshl_add_u64 v[26:27], v[24:25], 0, s[100:101]
	v_lshl_add_u64 v[28:29], v[26:27], 0, s[100:101]
	v_lshl_add_u64 v[30:31], v[28:29], 0, s[100:101]
	v_lshl_add_u64 v[32:33], v[30:31], 0, s[100:101]
	v_lshl_add_u64 v[34:35], v[32:33], 0, s[100:101]
	s_mov_b64 s[100:101], 0x20000
	global_load_dword v46, v[20:21], off nt
	global_load_dword v47, v[22:23], off nt
	global_load_dword v48, v[24:25], off nt
	global_load_dword v49, v[26:27], off nt
	global_load_dword v58, v[28:29], off nt
	global_load_dword v59, v[30:31], off nt
	global_load_dword v60, v[32:33], off nt
	global_load_dword v61, v[34:35], off nt
	v_lshl_add_u64 v[20:21], v[20:21], 0, s[100:101]
	v_lshl_add_u64 v[22:23], v[22:23], 0, s[100:101]
	v_lshl_add_u64 v[24:25], v[24:25], 0, s[100:101]
	v_lshl_add_u64 v[26:27], v[26:27], 0, s[100:101]
	v_lshl_add_u64 v[28:29], v[28:29], 0, s[100:101]
	v_lshl_add_u64 v[30:31], v[30:31], 0, s[100:101]
	v_lshl_add_u64 v[32:33], v[32:33], 0, s[100:101]
	v_lshl_add_u64 v[34:35], v[34:35], 0, s[100:101]
	global_load_dword v62, v[20:21], off nt
	global_load_dword v63, v[22:23], off nt
	global_load_dword v64, v[24:25], off nt
	global_load_dword v65, v[26:27], off nt
	global_load_dword v67, v[28:29], off nt
	global_load_dword v68, v[30:31], off nt
	global_load_dword v69, v[32:33], off nt
	global_load_dword v70, v[34:35], off nt
	v_lshl_add_u64 v[20:21], v[20:21], 0, s[100:101]
	v_lshl_add_u64 v[22:23], v[22:23], 0, s[100:101]
	v_lshl_add_u64 v[24:25], v[24:25], 0, s[100:101]
	v_lshl_add_u64 v[26:27], v[26:27], 0, s[100:101]
	v_lshl_add_u64 v[28:29], v[28:29], 0, s[100:101]
	v_lshl_add_u64 v[30:31], v[30:31], 0, s[100:101]
	v_lshl_add_u64 v[32:33], v[32:33], 0, s[100:101]
	v_lshl_add_u64 v[34:35], v[34:35], 0, s[100:101]
	global_load_dword v71, v[20:21], off nt
	global_load_dword v72, v[22:23], off nt
	global_load_dword v73, v[24:25], off nt
	global_load_dword v74, v[26:27], off nt
	global_load_dword v75, v[28:29], off nt
	global_load_dword v76, v[30:31], off nt
	global_load_dword v77, v[32:33], off nt
	global_load_dword v78, v[34:35], off nt
	v_lshl_add_u64 v[20:21], v[20:21], 0, s[100:101]
	v_lshl_add_u64 v[22:23], v[22:23], 0, s[100:101]
	v_lshl_add_u64 v[24:25], v[24:25], 0, s[100:101]
	v_lshl_add_u64 v[26:27], v[26:27], 0, s[100:101]
	v_lshl_add_u64 v[28:29], v[28:29], 0, s[100:101]
	v_lshl_add_u64 v[30:31], v[30:31], 0, s[100:101]
	v_lshl_add_u64 v[32:33], v[32:33], 0, s[100:101]
	v_lshl_add_u64 v[34:35], v[34:35], 0, s[100:101]
	global_load_dword v79, v[20:21], off nt
	global_load_dword v80, v[22:23], off nt
	global_load_dword v81, v[24:25], off nt
	global_load_dword v82, v[26:27], off nt
	global_load_dword v83, v[28:29], off nt
	global_load_dword v84, v[30:31], off nt
	global_load_dword v85, v[32:33], off nt
	global_load_dword v86, v[34:35], off nt
	s_branch .Lbw3_fin

; #define WAVE_LDS_SYNC() do { int _z = 0; (void)emu::wave_xchg(&_z, 4); } while (0)
; #define LAS __attribute__((address_space(3)))
; #define WAVE_LDS_SYNC() asm volatile("s_waitcnt lgkmcnt(0)" ::: "memory")
; #define NT_LOAD(p) __builtin_nontemporal_load(p)
; #define NT_STORE(v, p) __builtin_nontemporal_store((v), (p))
; DEV void tr_item(const float* W, int ldw, int col0, int k0, bf16_t* WT, int K, int row0, LAS float* scr, int lane) {
; #pragma unroll 8
;     for (int i = 0; i < 32; ++i) { const int kk = 2 * i + (lane >> 5); scr[kk * 33 + (lane & 31)] = NT_LOAD(&W[(size_t)(k0 + kk) * ldw + col0 + (lane & 31)]); }
;     WAVE_LDS_SYNC();
;     const int c = lane & 7;
; #pragma unroll
;     for (int j = 0; j < 4; ++j) { const int n = (lane >> 3) + 8 * j; const LAS float* s = scr + (8 * c) * 33 + n;
;         u32x4 o; o.x = pk2(s[0 * 33], s[1 * 33]); o.y = pk2(s[2 * 33], s[3 * 33]); o.z = pk2(s[4 * 33], s[5 * 33]); o.w = pk2(s[6 * 33], s[7 * 33]);
;         NT_STORE(o, (u32x4*)(WT + (size_t)(row0 + n) * K + k0 + 8 * c)); }
;     WAVE_LDS_SYNC();
; DEV void seq_s5_item(const Frame& F, int l, int item, int which) {
;     const int o = l >> 1; const int g = item & 31, d = (item >> 5) & 1, b = item >> 6;
;     LAS float* El = (LAS float*)(F.lds);
;     LAS unsigned char* wl = F.lds + 36864 + F.wave * 14336;
;     LAS float* scr = (LAS float*)wl; LAS bf16_t* hb = (LAS bf16_t*)(wl + 10240);
;     const bf16_t* P = (const bf16_t*)(F.ws + WS_P);
;     const float* Ab = (const float*)(F.ws + WS_S5A) + (size_t)((o * 2 + d) * 32 + g) * 128;
;     const bf16_t* Bb = (const bf16_t*)(F.ws + WS_S5B) + (size_t)((o * 2 + d) * 32 + g) * 128 * 16;
;     const bf16_t* Cm = (const bf16_t*)(F.ws + WS_S5C) + (size_t)(o * 32 + g) * 16 * 128;
;     const int l15 = F.lane & 15, kg = F.lane >> 4;
;     const float ar = Ab[F.lane], ai = Ab[64 + F.lane];
;     bf16x8 bB[8], cB[4]; const bf16x8 zero8 = (bf16x8){0, 0, 0, 0, 0, 0, 0, 0};
; #pragma unroll
;     for (int ct = 0; ct < 8; ++ct) bB[ct] = kg < 2 ? *(const bf16x8*)(Bb + (size_t)(16 * ct + l15) * 16 + 8 * kg) : zero8;
; #pragma unroll
;     for (int s = 0; s < 4; ++s) cB[s] = *(const bf16x8*)(Cm + (size_t)l15 * 128 + 32 * s + 8 * kg);
;     bf16_t* Obase = (bf16_t*)(F.ws + WS_O) + (size_t)d * MROWS * 1024 + 512 + 16 * g;
;     float* SE = (float*)(F.ws + WS_S5E) + (size_t)item * NCH * 128;
.Lbw3_fin:
	v_writelane_b32 v255, s41, 60
	s_nop 0
	v_readlane_b32 s40, v255, 60
	s_cmp_eq_u32 s40, 0
	s_cbranch_scc1 .Lbw3_skip
	s_lshr_b32 s41, s40, 16
	s_and_b32 s40, s40, 0xffff
	s_and_b32 s38, s40, 0x7ff
	s_lshr_b32 s39, s38, 7
	s_and_b32 s38, s38, 0x7f
	s_lshl_b32 s42, s38, 16
	s_lshl_b32 s39, s39, 7
	s_add_i32 s42, s42, s39
	s_lshr_b32 s39, s40, 11
	s_lshl_b32 s39, s39, 23
	s_add_i32 s42, s42, s39
	s_lshl_b32 s39, s41, 27
	s_add_u32 s42, s42, s39
	s_add_u32 s42, s42, 0x2bc8000
	v_readlane_b32 s100, v255, 53
	v_readlane_b32 s101, v255, 54
	s_add_u32 s42, s100, s42
	s_addc_u32 s43, s101, 0
	v_readlane_b32 s39, v251, 29
	s_lshl_b32 s39, s39, 14
	v_and_b32_e32 v144, 31, v200
	v_lshrrev_b32_e32 v145, 5, v200
	v_mul_u32_u24_e32 v145, 33, v145
	v_add_u32_e32 v145, v145, v144
	v_lshl_add_u32 v87, v145, 2, s39
	v_add_u32_e32 v136, 0x400, v87
	v_add_u32_e32 v137, 0x840, v87
	v_add_u32_e32 v138, 0xc40, v87
	v_add_u32_e32 v139, 0x1080, v87
	v_add_u32_e32 v140, 0x1480, v87
	v_add_u32_e32 v141, 0x18c0, v87
	v_add_u32_e32 v142, 0x1cc0, v87
	v_and_b32_e32 v144, 7, v200
	v_lshrrev_b32_e32 v145, 3, v200
	v_mul_u32_u24_e32 v147, 0x108, v144
	v_add_u32_e32 v147, v147, v145
	v_lshl_add_u32 v143, v147, 2, s39
	v_lshlrev_b32_e32 v144, 4, v144
	v_lshl_add_u32 v36, v145, 11, v144
	v_mov_b32_e32 v37, 0
	s_mov_b64 s[100:101], 0x4000
	v_lshl_add_u64 v[20:21], s[42:43], 0, v[36:37]
	v_lshl_add_u64 v[22:23], v[20:21], 0, s[100:101]
	v_lshl_add_u64 v[24:25], v[22:23], 0, s[100:101]
	v_lshl_add_u64 v[26:27], v[24:25], 0, s[100:101]
	s_waitcnt vmcnt(0)
	ds_write2_b32 v87, v46, v47 offset1:66
	ds_write2_b32 v87, v48, v49 offset0:132 offset1:198
	ds_write2_b32 v136, v58, v59 offset0:8 offset1:74
	ds_write2_b32 v136, v60, v61 offset0:140 offset1:206
	ds_write2_b32 v137, v62, v63 offset1:66
	ds_write2_b32 v137, v64, v65 offset0:132 offset1:198
	ds_write2_b32 v138, v67, v68 offset0:8 offset1:74
	ds_write2_b32 v138, v69, v70 offset0:140 offset1:206
	ds_write2_b32 v139, v71, v72 offset1:66
	ds_write2_b32 v139, v73, v74 offset0:132 offset1:198
	ds_write2_b32 v140, v75, v76 offset0:8 offset1:74
	ds_write2_b32 v140, v77, v78 offset0:140 offset1:206
	ds_write2_b32 v141, v79, v80 offset1:66
	ds_write2_b32 v141, v81, v82 offset0:132 offset1:198
	ds_write2_b32 v142, v83, v84 offset0:8 offset1:74
	ds_write2_b32 v142, v85, v86 offset0:140 offset1:206
	ds_read2_b32 v[88:89], v143 offset1:8
	ds_read2_b32 v[90:91], v143 offset0:33 offset1:41
	ds_read2_b32 v[92:93], v143 offset0:66 offset1:74
	ds_read2_b32 v[94:95], v143 offset0:99 offset1:107
	ds_read2_b32 v[96:97], v143 offset0:132 offset1:140
	ds_read2_b32 v[98:99], v143 offset0:165 offset1:173
	ds_read2_b32 v[100:101], v143 offset0:198 offset1:206
	ds_read2_b32 v[102:103], v143 offset0:231 offset1:239
	ds_read2_b32 v[104:105], v143 offset0:16 offset1:24
	ds_read2_b32 v[106:107], v143 offset0:49 offset1:57
	ds_read2_b32 v[108:109], v143 offset0:82 offset1:90
	ds_read2_b32 v[110:111], v143 offset0:115 offset1:123
	s_waitcnt lgkmcnt(4)
	v_cvt_pk_bf16_f32 v120, v88, v90
	v_cvt_pk_bf16_f32 v121, v92, v94
	v_cvt_pk_bf16_f32 v122, v96, v98
	v_cvt_pk_bf16_f32 v123, v100, v102
	v_cvt_pk_bf16_f32 v124, v89, v91
	v_cvt_pk_bf16_f32 v125, v93, v95
	v_cvt_pk_bf16_f32 v126, v97, v99
	v_cvt_pk_bf16_f32 v127, v101, v103
	ds_read2_b32 v[112:113], v143 offset0:148 offset1:156
	ds_read2_b32 v[114:115], v143 offset0:181 offset1:189
	ds_read2_b32 v[116:117], v143 offset0:214 offset1:222
	ds_read2_b32 v[118:119], v143 offset0:247 offset1:255
	global_store_dwordx4 v[20:21], v[120:123], off nt
	global_store_dwordx4 v[22:23], v[124:127], off nt
	s_waitcnt lgkmcnt(0)
	v_cvt_pk_bf16_f32 v128, v104, v106
	v_cvt_pk_bf16_f32 v129, v108, v110
	v_cvt_pk_bf16_f32 v130, v112, v114
	v_cvt_pk_bf16_f32 v131, v116, v118
	v_cvt_pk_bf16_f32 v132, v105, v107
	v_cvt_pk_bf16_f32 v133, v109, v111
	v_cvt_pk_bf16_f32 v134, v113, v115
	v_cvt_pk_bf16_f32 v135, v117, v119
	global_store_dwordx4 v[24:25], v[128:131], off nt
	global_store_dwordx4 v[26:27], v[132:135], off nt
.Lbw3_skip:
	s_waitcnt lgkmcnt(0)
	v_readlane_b32 s38, v255, 61
	s_cmp_lg_u32 s38, 0
	v_readlane_b32 s2, v252, 10
	v_readlane_b32 s64, v251, 29
	v_mov_b32_e32 v66, v200
	v_readlane_b32 s4, v251, 0
	v_readlane_b32 s3, v252, 11
	s_waitcnt lgkmcnt(0)
	s_barrier
	s_lshl_b32 s65, s64, 6
	v_readlane_b32 s6, v251, 2
	v_readlane_b32 s7, v251, 3
	s_or_b64 s[2:3], s[2:3], s[58:59]
	v_lshlrev_b32_e32 v73, 2, v66
	v_add_u32_e32 v68, s65, v66
	s_mov_b64 s[20:21], s[6:7]
	s_and_b64 vcc, exec, s[2:3]
	v_ashrrev_i32_e32 v67, 31, v66
	v_add_u32_e32 v148, 0, v73
	v_readlane_b32 s5, v251, 1
	s_cbranch_vccnz .LBB0_472
	s_mul_i32 s0, s64, 0x3800
	v_readlane_b32 s2, v253, 62
	s_add_i32 s0, s0, 0
	s_and_b32 s33, s2, 2
	s_add_u32 s22, s20, 0x415d4c00
	s_addc_u32 s23, s21, 0
	s_add_u32 s38, s20, 0x40d54c00
	s_addc_u32 s39, s21, 0
	s_cmpk_lt_i32 s64, 0x44
	s_cselect_b64 s[24:25], -1, 0
	s_cmp_eq_u32 s64, 0
	v_ashrrev_i32_e32 v0, 4, v66
	s_cselect_b64 s[26:27], -1, 0
	v_max_i32_e32 v4, 0x2000, v68
	s_lshl_b32 s18, s64, 9
	v_readlane_b32 s3, v253, 63
	v_lshlrev_b32_e32 v74, 3, v0
	v_sub_u32_e32 v4, v4, v68
	s_add_i32 s18, s18, 0
	v_lshl_add_u64 v[2:3], v[66:67], 2, s[20:21]
	s_mov_b64 s[2:3], 0x32bc8000
	v_ashrrev_i32_e32 v75, 31, v74
	v_add_u32_e32 v4, 0x1ff, v4
	v_add_u32_e32 v97, s18, v73
	s_lshl_b32 s18, s64, 8
	v_and_b32_e32 v78, 15, v66
	v_lshl_add_u64 v[70:71], v[2:3], 0, s[2:3]
	v_lshl_add_u64 v[2:3], v[74:75], 1, s[20:21]
	s_mov_b64 s[4:5], 0x32bd8000
	v_lshrrev_b32_e32 v5, 9, v4
	s_add_i32 s18, s18, 0
	v_lshl_add_u64 v[76:77], v[2:3], 0, s[4:5]
	v_or_b32_e32 v79, s65, v78
	v_mov_b32_e32 v2, s0
	s_movk_i32 s12, 0x50
	v_add_u32_e32 v5, 1, v5
	v_add_u32_e32 v98, s18, v73
	v_readlane_b32 s18, v252, 58
	v_cmp_gt_i32_e64 s[2:3], 2, v0
	v_and_b32_e32 v0, -16, v66
	v_or_b32_e32 v83, 16, v79
	v_or_b32_e32 v87, 32, v79
	v_or_b32_e32 v91, 48, v79
	v_mad_u32_u24 v2, v78, s12, v2
	v_mul_lo_u32 v3, v66, s12
	s_movk_i32 s12, 0x2200
	s_movk_i32 s14, 0x1ff
	v_and_b32_e32 v95, 0xfffffe, v5
	s_add_u32 s28, s20, s18
	v_readlane_b32 s18, v252, 59
	v_lshlrev_b32_e32 v72, 4, v78
	v_cmp_gt_i32_e64 s[4:5], s63, v79
	v_add_u32_e32 v80, 0xffffff00, v79
	v_sub_u32_e32 v81, 0x10ff, v79
	v_sub_u32_e32 v82, 0xff, v79
	v_cmp_gt_i32_e64 s[6:7], s63, v83
	v_add_u32_e32 v84, 0xffffff10, v79
	v_sub_u32_e32 v85, 0x10ff, v83
	v_sub_u32_e32 v86, 0xff, v83
	v_cmp_gt_i32_e64 s[8:9], s63, v87
	v_add_u32_e32 v88, 0xffffff20, v79
	v_sub_u32_e32 v89, 0x10ff, v87
	v_sub_u32_e32 v90, 0xff, v87
	v_cmp_gt_i32_e64 s[10:11], s63, v91
	v_add_u32_e32 v92, 0xffffff30, v79
	v_sub_u32_e32 v93, 0x10ff, v91
	v_sub_u32_e32 v94, 0xff, v91
	v_cmp_gt_i32_e64 s[12:13], s12, v68
	v_cmp_lt_u32_e64 s[14:15], s14, v4
	v_lshl_add_u32 v96, v95, 9, v68
	v_add_u32_e32 v69, 0x200, v68
	v_cmp_ne_u32_e64 s[16:17], v5, v95
	s_addc_u32 s29, s21, s18
	v_add_u32_e32 v99, v2, v0
	v_add_u32_e32 v100, s0, v3
	s_mov_b32 s40, s95
	s_branch .LBB0_425

; #define LAS __attribute__((address_space(3)))
; #define NT_LOAD(p) __builtin_nontemporal_load(p)
; DEV void tr_item(const float* W, int ldw, int col0, int k0, bf16_t* WT, int K, int row0, LAS float* scr, int lane) {
; #pragma unroll 8
;     for (int i = 0; i < 32; ++i) { const int kk = 2 * i + (lane >> 5); scr[kk * 33 + (lane & 31)] = NT_LOAD(&W[(size_t)(k0 + kk) * ldw + col0 + (lane & 31)]); }
.Lbw4_gate:
	s_add_u32 s42, s100, s42
	s_addc_u32 s43, s101, 0
	s_lshl_b32 s39, s41, 16
	s_or_b32 s41, s39, s40
	v_lshrrev_b32_e32 v141, 5, v200
	v_and_b32_e32 v142, 31, v200
	v_lshlrev_b32_e32 v142, 2, v142
	v_lshl_add_u32 v36, v141, 13, v142
	v_mov_b32_e32 v37, 0
	s_mov_b64 s[100:101], 0x4000
	v_lshl_add_u64 v[20:21], s[42:43], 0, v[36:37]
	v_lshl_add_u64 v[22:23], v[20:21], 0, s[100:101]
	v_lshl_add_u64 v[24:25], v[22:23], 0, s[100:101]
	v_lshl_add_u64 v[26:27], v[24:25], 0, s[100:101]
	v_lshl_add_u64 v[28:29], v[26:27], 0, s[100:101]
	v_lshl_add_u64 v[30:31], v[28:29], 0, s[100:101]
	v_lshl_add_u64 v[32:33], v[30:31], 0, s[100:101]
	v_lshl_add_u64 v[34:35], v[32:33], 0, s[100:101]
	s_mov_b64 s[100:101], 0x20000
	global_load_dword v38, v[20:21], off nt
	global_load_dword v39, v[22:23], off nt
	global_load_dword v40, v[24:25], off nt
	global_load_dword v41, v[26:27], off nt
	global_load_dword v42, v[28:29], off nt
	global_load_dword v43, v[30:31], off nt
	global_load_dword v44, v[32:33], off nt
	global_load_dword v45, v[34:35], off nt
	v_lshl_add_u64 v[20:21], v[20:21], 0, s[100:101]
	v_lshl_add_u64 v[22:23], v[22:23], 0, s[100:101]
	v_lshl_add_u64 v[24:25], v[24:25], 0, s[100:101]
	v_lshl_add_u64 v[26:27], v[26:27], 0, s[100:101]
	v_lshl_add_u64 v[28:29], v[28:29], 0, s[100:101]
	v_lshl_add_u64 v[30:31], v[30:31], 0, s[100:101]
	v_lshl_add_u64 v[32:33], v[32:33], 0, s[100:101]
	v_lshl_add_u64 v[34:35], v[34:35], 0, s[100:101]
	global_load_dword v46, v[20:21], off nt
	global_load_dword v47, v[22:23], off nt
	global_load_dword v48, v[24:25], off nt
	global_load_dword v49, v[26:27], off nt
	global_load_dword v50, v[28:29], off nt
	global_load_dword v51, v[30:31], off nt
	global_load_dword v52, v[32:33], off nt
	global_load_dword v53, v[34:35], off nt
	v_lshl_add_u64 v[20:21], v[20:21], 0, s[100:101]
	v_lshl_add_u64 v[22:23], v[22:23], 0, s[100:101]
	v_lshl_add_u64 v[24:25], v[24:25], 0, s[100:101]
	v_lshl_add_u64 v[26:27], v[26:27], 0, s[100:101]
	v_lshl_add_u64 v[28:29], v[28:29], 0, s[100:101]
	v_lshl_add_u64 v[30:31], v[30:31], 0, s[100:101]
	v_lshl_add_u64 v[32:33], v[32:33], 0, s[100:101]
	v_lshl_add_u64 v[34:35], v[34:35], 0, s[100:101]
	global_load_dword v54, v[20:21], off nt
	global_load_dword v55, v[22:23], off nt
	global_load_dword v56, v[24:25], off nt
	global_load_dword v57, v[26:27], off nt
	global_load_dword v70, v[28:29], off nt
	global_load_dword v71, v[30:31], off nt
	global_load_dword v72, v[32:33], off nt
	global_load_dword v73, v[34:35], off nt
	v_lshl_add_u64 v[20:21], v[20:21], 0, s[100:101]
	v_lshl_add_u64 v[22:23], v[22:23], 0, s[100:101]
	v_lshl_add_u64 v[24:25], v[24:25], 0, s[100:101]
	v_lshl_add_u64 v[26:27], v[26:27], 0, s[100:101]
	v_lshl_add_u64 v[28:29], v[28:29], 0, s[100:101]
	v_lshl_add_u64 v[30:31], v[30:31], 0, s[100:101]
	v_lshl_add_u64 v[32:33], v[32:33], 0, s[100:101]
	v_lshl_add_u64 v[34:35], v[34:35], 0, s[100:101]
	global_load_dword v74, v[20:21], off nt
	global_load_dword v75, v[22:23], off nt
	global_load_dword v76, v[24:25], off nt
	global_load_dword v77, v[26:27], off nt
	global_load_dword v78, v[28:29], off nt
	global_load_dword v79, v[30:31], off nt
	global_load_dword v80, v[32:33], off nt
	global_load_dword v81, v[34:35], off nt
	s_branch .Lbw4_fin

; #define WAVE_LDS_SYNC() do { int _z = 0; (void)emu::wave_xchg(&_z, 4); } while (0)
; #define LAS __attribute__((address_space(3)))
; #define WAVE_LDS_SYNC() asm volatile("s_waitcnt lgkmcnt(0)" ::: "memory")
; #define NT_LOAD(p) __builtin_nontemporal_load(p)
; #define NT_STORE(v, p) __builtin_nontemporal_store((v), (p))
; DEV unsigned pk2(float lo, float hi) { return f2bf(lo) | (f2bf(hi) << 16); }
; DEV unsigned pk2(float lo, float hi) { const f32x2n_t v = {lo, hi}; return __builtin_bit_cast(unsigned, __builtin_convertvector(v, bf16x2n_t)); }
; DEV void tr_item(const float* W, int ldw, int col0, int k0, bf16_t* WT, int K, int row0, LAS float* scr, int lane) {
; #pragma unroll 8
;     for (int i = 0; i < 32; ++i) { const int kk = 2 * i + (lane >> 5); scr[kk * 33 + (lane & 31)] = NT_LOAD(&W[(size_t)(k0 + kk) * ldw + col0 + (lane & 31)]); }
;     WAVE_LDS_SYNC();
;     const int c = lane & 7;
; #pragma unroll
;     for (int j = 0; j < 4; ++j) { const int n = (lane >> 3) + 8 * j; const LAS float* s = scr + (8 * c) * 33 + n;
;         u32x4 o; o.x = pk2(s[0 * 33], s[1 * 33]); o.y = pk2(s[2 * 33], s[3 * 33]); o.z = pk2(s[4 * 33], s[5 * 33]); o.w = pk2(s[6 * 33], s[7 * 33]);
;         NT_STORE(o, (u32x4*)(WT + (size_t)(row0 + n) * K + k0 + 8 * c)); }
;     WAVE_LDS_SYNC();
;     const Frame F = refresh(F0);
;     const int odd = l & 1; const int nlin = B_ * (odd ? 4 : 8) * 2 * 4; const int ns5 = odd ? B_ * 2 * 32 : 0;
;     const int vcu = (F.G % 8 == 0) ? (F.bid % 8) * (F.G / 8) + F.bid / 8 : F.bid;
;     if (!odd || F.G <= nlin) {
;         for (int it = vcu; it < nlin + ns5; it += F.G) {
;             if (it < nlin) { if (mode != 2) seq_linear_item(F, l, it, mode >= 10 ? mode - 10 : 0); } else if (mode != 1 && mode < 10) seq_s5_item(F, l, it - nlin, 1);
;             __syncthreads();
;         }
;     } else if (vcu < nlin) { if (mode != 2) seq_linear_item(F, l, vcu, mode >= 10 ? mode - 10 : 0); }
;     else { for (int it = vcu - nlin; it < ns5; it += F.G - nlin) { if (mode != 1 && mode < 10) seq_s5_item(F, l, it, 1); __syncthreads(); } }
; }
.Lbw4_fin:
	v_writelane_b32 v255, s41, 60
	s_nop 0
	v_readlane_b32 s40, v255, 60
	s_cmp_eq_u32 s40, 0
	s_cbranch_scc1 .Lbw4_skip
	s_lshr_b32 s41, s40, 16
	s_and_b32 s40, s40, 0xffff
	s_and_b32 s38, s40, 0x7ff
	s_lshr_b32 s39, s38, 7
	s_and_b32 s38, s38, 0x7f
	s_lshl_b32 s42, s38, 16
	s_lshl_b32 s39, s39, 7
	s_add_i32 s42, s42, s39
	s_lshr_b32 s39, s40, 11
	s_lshl_b32 s39, s39, 23
	s_add_i32 s42, s42, s39
	s_lshl_b32 s39, s41, 27
	s_add_u32 s42, s42, s39
	s_add_u32 s42, s42, 0x2bc8000
	v_readlane_b32 s100, v255, 53
	v_readlane_b32 s101, v255, 54
	s_add_u32 s42, s100, s42
	s_addc_u32 s43, s101, 0
	v_readlane_b32 s39, v251, 29
	s_lshl_b32 s39, s39, 14
	v_and_b32_e32 v141, 31, v200
	v_lshrrev_b32_e32 v142, 5, v200
	v_mul_u32_u24_e32 v142, 33, v142
	v_add_u32_e32 v142, v142, v141
	v_lshl_add_u32 v132, v142, 2, s39
	v_add_u32_e32 v133, 0x400, v132
	v_add_u32_e32 v134, 0x840, v132
	v_add_u32_e32 v135, 0xc40, v132
	v_add_u32_e32 v136, 0x1080, v132
	v_add_u32_e32 v137, 0x1480, v132
	v_add_u32_e32 v138, 0x18c0, v132
	v_add_u32_e32 v139, 0x1cc0, v132
	v_and_b32_e32 v141, 7, v200
	v_lshrrev_b32_e32 v142, 3, v200
	v_mul_u32_u24_e32 v143, 0x108, v141
	v_add_u32_e32 v143, v143, v142
	v_lshl_add_u32 v140, v143, 2, s39
	v_lshlrev_b32_e32 v141, 4, v141
	v_lshl_add_u32 v36, v142, 11, v141
	v_mov_b32_e32 v37, 0
	s_mov_b64 s[100:101], 0x4000
	v_lshl_add_u64 v[20:21], s[42:43], 0, v[36:37]
	v_lshl_add_u64 v[22:23], v[20:21], 0, s[100:101]
	v_lshl_add_u64 v[24:25], v[22:23], 0, s[100:101]
	v_lshl_add_u64 v[26:27], v[24:25], 0, s[100:101]
	s_waitcnt vmcnt(0)
	ds_write2_b32 v132, v38, v39 offset1:66
	ds_write2_b32 v132, v40, v41 offset0:132 offset1:198
	ds_write2_b32 v133, v42, v43 offset0:8 offset1:74
	ds_write2_b32 v133, v44, v45 offset0:140 offset1:206
	ds_write2_b32 v134, v46, v47 offset1:66
	ds_write2_b32 v134, v48, v49 offset0:132 offset1:198
	ds_write2_b32 v135, v50, v51 offset0:8 offset1:74
	ds_write2_b32 v135, v52, v53 offset0:140 offset1:206
	ds_write2_b32 v136, v54, v55 offset1:66
	ds_write2_b32 v136, v56, v57 offset0:132 offset1:198
	ds_write2_b32 v137, v70, v71 offset0:8 offset1:74
	ds_write2_b32 v137, v72, v73 offset0:140 offset1:206
	ds_write2_b32 v138, v74, v75 offset1:66
	ds_write2_b32 v138, v76, v77 offset0:132 offset1:198
	ds_write2_b32 v139, v78, v79 offset0:8 offset1:74
	ds_write2_b32 v139, v80, v81 offset0:140 offset1:206
	ds_read2_b32 v[82:83], v140 offset1:8
	ds_read2_b32 v[84:85], v140 offset0:33 offset1:41
	ds_read2_b32 v[86:87], v140 offset0:66 offset1:74
	ds_read2_b32 v[88:89], v140 offset0:99 offset1:107
	ds_read2_b32 v[90:91], v140 offset0:132 offset1:140
	ds_read2_b32 v[92:93], v140 offset0:165 offset1:173
	ds_read2_b32 v[94:95], v140 offset0:198 offset1:206
	ds_read2_b32 v[96:97], v140 offset0:231 offset1:239
	ds_read2_b32 v[98:99], v140 offset0:16 offset1:24
	ds_read2_b32 v[100:101], v140 offset0:49 offset1:57
	ds_read2_b32 v[102:103], v140 offset0:82 offset1:90
	ds_read2_b32 v[104:105], v140 offset0:115 offset1:123
	s_waitcnt lgkmcnt(4)
	v_cvt_pk_bf16_f32 v116, v82, v84
	v_cvt_pk_bf16_f32 v117, v86, v88
	v_cvt_pk_bf16_f32 v118, v90, v92
	v_cvt_pk_bf16_f32 v119, v94, v96
	v_cvt_pk_bf16_f32 v120, v83, v85
	v_cvt_pk_bf16_f32 v121, v87, v89
	v_cvt_pk_bf16_f32 v122, v91, v93
	v_cvt_pk_bf16_f32 v123, v95, v97
	ds_read2_b32 v[106:107], v140 offset0:148 offset1:156
	ds_read2_b32 v[110:111], v140 offset0:181 offset1:189
	ds_read2_b32 v[112:113], v140 offset0:214 offset1:222
	ds_read2_b32 v[114:115], v140 offset0:247 offset1:255
	global_store_dwordx4 v[20:21], v[116:119], off nt
	global_store_dwordx4 v[22:23], v[120:123], off nt
	s_waitcnt lgkmcnt(0)
	v_cvt_pk_bf16_f32 v124, v98, v100
	v_cvt_pk_bf16_f32 v125, v102, v104
	v_cvt_pk_bf16_f32 v126, v106, v110
	v_cvt_pk_bf16_f32 v127, v112, v114
	v_cvt_pk_bf16_f32 v128, v99, v101
	v_cvt_pk_bf16_f32 v129, v103, v105
	v_cvt_pk_bf16_f32 v130, v107, v111
	v_cvt_pk_bf16_f32 v131, v113, v115
	global_store_dwordx4 v[24:25], v[124:127], off nt
	global_store_dwordx4 v[26:27], v[128:131], off nt
.Lbw4_skip:
	s_waitcnt lgkmcnt(0)
	v_readlane_b32 s38, v255, 61
	s_cmp_lg_u32 s38, 0
	v_readlane_b32 s62, v251, 29
	v_readlane_b32 s4, v251, 0
	s_waitcnt lgkmcnt(0)
	s_barrier
	v_mov_b32_e32 v82, v200
	s_lshl_b32 s0, s62, 6
	v_readlane_b32 s6, v251, 2
	v_readlane_b32 s7, v251, 3
	v_writelane_b32 v254, s0, 27
	v_add_u32_e32 v84, s0, v82
	s_mov_b64 s[2:3], s[6:7]
	v_readlane_b32 s0, v253, 49
	v_readlane_b32 s5, v251, 1
	s_cmp_lg_u32 s0, 0
	v_writelane_b32 v254, s2, 28
	s_cselect_b64 s[4:5], -1, 0
	s_nop 0
	v_writelane_b32 v254, s3, 29
	s_and_b64 s[2:3], s[4:5], exec
	s_cselect_b32 s69, 0x80, s63
	s_lshl_b32 s0, s0, 8
	v_writelane_b32 v254, s0, 30
	s_cmp_gt_i32 s96, s69
	s_cselect_b64 s[2:3], -1, 0
	v_writelane_b32 v254, s4, 31
	s_nop 1
	v_writelane_b32 v254, s5, 32
	s_and_b64 s[4:5], s[4:5], s[2:3]
	s_mov_b64 s[2:3], -1
	s_and_b64 vcc, exec, s[4:5]
	s_cbranch_vccnz .LBB0_1047
	v_writelane_b32 v254, s62, 33
	v_readlane_b32 s68, v253, 11
	v_readlane_b32 s0, v254, 30
	s_add_i32 s83, s69, s0
	v_readlane_b32 s0, v252, 61
	s_cmp_ge_i32 s0, s83
	v_readlane_b32 s67, v253, 12
	s_movk_i32 s62, 0x67f
	s_cbranch_scc1 .LBB0_1046
; template <int KIND>
; DEV void seq_dma(const Frame& F, const SeqCtx& C, int n, LAS unsigned char* img) {
;     const int p = C.chain * NCH + n, w = F.wave; int ln = F.lane; LAUNDER(ln);
;     if (w < 2) {
;         if (KIND == 0) { const GAS char* g = (const GAS char*)(F.ws + WS_CLW) + (size_t)p * 16384; LAUNDER_S(g);
; #pragma unroll
;             for (int i = 0; i < 8; ++i) { const int r = 4 * (8 * w + i) + (ln >> 4), pp = ln & 15; glds16(g + r * 256 + 16 * (pp ^ (r & 15)), img + SQ_W + 1024 * (8 * w + i)); } }
;     } else if (w < 4) {
;         const GAS char* g = (const GAS char*)(F.ws + WS_CLQ) + (size_t)p * 16384; LAUNDER_S(g);
; #pragma unroll
;         for (int i = 0; i < 8; ++i) { const int c = 8 * (w - 2) + i, r = 4 * c + (ln >> 4), pp = ln & 15; glds16(g + r * 256 + 16 * (pp ^ (r & 15)), img + SQ_Q + 1024 * c); }
;     } else if (w < 6) {
;         const GAS char* g = (const GAS char*)(F.ws + WS_CLK) + (size_t)p * 16384; LAUNDER_S(g);
; #pragma unroll
;         for (int i = 0; i < 8; ++i) { const int c = 8 * (w - 4) + i, r = 8 * c + (ln >> 3), pp = ln & 7; glds16(g + r * 128 + 16 * (pp ^ ((r >> 1) & 7)), img + SQ_K + 1024 * c); }
;     } else if (w == 6) {
;         const GAS char* g = (const GAS char*)(F.ws + WS_CLA) + (size_t)p * 8192; LAUNDER_S(g);
; #pragma unroll
;         for (int i = 0; i < 8; ++i) { const int r = 8 * i + (ln >> 3), pp = ln & 7; glds16(g + r * 128 + 16 * (pp ^ ((r >> 1) & 7)), img + SQ_A + 1024 * i); }
;     } else {
;     ...
; #pragma unroll
;             for (int i = 0; i < 4; ++i) { const int r = 16 * i + (ln >> 2); glds16(g + r * 256 + 16 * (ln & 3), img + SQ_U + 1024 * i); }
;         } else { const int r0 = tok_row(C.b, C.d, n * 64); const long st = C.d ? -(long)C.vld * 2 : (long)C.vld * 2;
;             const GAS char* g = (const GAS char*)C.vsrc + (long)r0 * C.vld * 2 + 64 * C.sl; LAUNDER_S(g);
;     const int odd = l & 1, nhh = odd ? 4 : 8;
;     ...
;     const GAS bf16_t* P = (const GAS bf16_t*)(F.ws + WS_P); const GAS bf16_t* Q = (const GAS bf16_t*)(F.ws + WS_QKV);
;     ...
;     for (int i = F.tid; i < 32 * 136 / 2; i += NTHREADS) ((LAS unsigned*)(F.lds + SQ_SB))[i] = 0u;
;     if (F.tid < 128) ((LAS float*)(F.lds + SQ_NV))[F.tid] = 0.f;
;     __syncthreads();
;     if (C.kind == 0) seq_kind_loop<0>(F, C, F.lds); else if (C.kind == 1) seq_kind_loop<1>(F, C, F.lds); else seq_kind_loop<2>(F, C, F.lds);
;     WAIT_VM(0);
; }
	v_readlane_b32 s7, v254, 33
	s_mul_i32 s0, s7, 0x3800
	v_readlane_b32 s2, v253, 62
	s_add_i32 s77, s0, 0
	s_and_b32 s0, s2, 2
	v_writelane_b32 v254, s0, 34
	s_lshl_b32 s0, s2, 4
	s_and_b32 s0, s0, 32
	v_writelane_b32 v254, s0, 35
	v_readlane_b32 s3, v253, 63
	v_readlane_b32 s8, v254, 28
	v_readlane_b32 s9, v254, 29
	s_add_u32 s36, s8, 0x415d4c00
	s_addc_u32 s37, s9, 0
	s_add_u32 s0, s8, 0x40d54c00
	v_writelane_b32 v254, s0, 36
	s_addc_u32 s0, s9, 0
	s_cmpk_lt_i32 s7, 0x44
	v_writelane_b32 v254, s0, 37
	s_cselect_b64 s[2:3], -1, 0
	v_writelane_b32 v254, s2, 38
	s_lshl_b32 s6, s72, 1
	s_add_u32 s0, s8, 0x4a655400
	v_writelane_b32 v254, s3, 39
	v_writelane_b32 v254, s0, 40
	s_addc_u32 s0, s9, 0
	v_writelane_b32 v254, s0, 41
	s_add_u32 s0, s8, 0x415d5400
	v_writelane_b32 v254, s0, 42
	s_addc_u32 s0, s9, 0
	s_cmp_gt_i32 s7, 1
	s_cselect_b64 s[40:41], -1, 0
	s_cmp_lt_u32 s7, 4
	s_cselect_b64 s[42:43], -1, 0
	s_cmp_gt_u32 s7, 3
	s_cselect_b64 s[44:45], -1, 0
	s_cmp_gt_u32 s7, 5
	s_cselect_b64 s[46:47], -1, 0
	s_cmp_lg_u32 s7, 6
	v_writelane_b32 v254, s0, 43
	s_cselect_b64 s[2:3], -1, 0
	s_add_u32 s0, s8, 0x60b54c00
	v_writelane_b32 v254, s0, 44
	s_addc_u32 s0, s9, 0
	v_writelane_b32 v254, s0, 45
	s_add_u32 s0, s8, 0x5a554c00
	v_writelane_b32 v254, s0, 46
	s_addc_u32 s0, s9, 0
	v_writelane_b32 v254, s0, 47
	s_add_u32 s0, s8, 0x56154c00
	v_writelane_b32 v254, s0, 8
	s_addc_u32 s0, s9, 0
	v_writelane_b32 v253, s2, 49
	v_writelane_b32 v254, s0, 2
	s_lshl_b32 s0, s7, 3
	v_writelane_b32 v253, s3, 50
	s_sub_i32 s2, s0, 32
	s_lshl_b32 s3, s2, 3
	v_writelane_b32 v254, s3, 6
	s_lshl_b32 s2, s2, 10
	v_writelane_b32 v254, s2, 13
	s_sub_i32 s2, s0, 31
	s_lshl_b32 s3, s2, 3
	v_writelane_b32 v254, s3, 15
	s_lshl_b32 s2, s2, 10
	v_writelane_b32 v254, s2, 17
	s_sub_i32 s2, s0, 30
	s_lshl_b32 s3, s2, 3
	v_writelane_b32 v254, s3, 19
	s_lshl_b32 s2, s2, 10
	v_writelane_b32 v254, s2, 21
	s_sub_i32 s2, s0, 29
	s_lshl_b32 s3, s2, 3
	v_writelane_b32 v254, s3, 23
	s_lshl_b32 s2, s2, 10
	v_writelane_b32 v254, s2, 25
	s_sub_i32 s2, s0, 28
	s_lshl_b32 s3, s2, 3
	s_lshl_b32 s2, s2, 10
	v_writelane_b32 v253, s2, 51
	s_sub_i32 s2, s0, 27
	v_writelane_b32 v254, s3, 11
	s_lshl_b32 s3, s2, 3
	v_writelane_b32 v254, s3, 10
	s_lshl_b32 s2, s2, 10
	v_writelane_b32 v254, s2, 4
	s_sub_i32 s2, s0, 26
	s_lshl_b32 s3, s2, 3
	s_lshl_b32 s2, s2, 10
	v_writelane_b32 v254, s2, 0
	s_sub_i32 s2, s0, 25
	v_writelane_b32 v253, s3, 60
	s_lshl_b32 s3, s2, 3
	s_lshl_b32 s2, s2, 10
	v_writelane_b32 v253, s3, 56
	s_add_u32 s11, s8, 0x51d54c00
	v_writelane_b32 v253, s2, 58
	s_addc_u32 s12, s9, 0
	s_add_i32 s2, s0, -16
	s_lshl_b32 s13, s2, 2
	s_lshl_b32 s22, s2, 10
	s_add_i32 s2, s0, -15
	s_lshl_b32 s23, s2, 2
	s_lshl_b32 s78, s2, 10
	s_add_i32 s2, s0, -14
	s_lshl_b32 s79, s2, 2
	s_lshl_b32 s38, s2, 10
	s_add_i32 s2, s0, -13
	v_cvt_f32_ubyte0_e32 v0, s72
	s_lshl_b32 s39, s2, 2
	s_lshl_b32 s4, s2, 10
	s_add_i32 s2, s0, -12
	v_rcp_iflag_f32_e32 v0, v0
	s_lshl_b32 s5, s2, 2
	s_lshl_b32 s14, s2, 10
	s_add_i32 s2, s0, -11
	s_lshl_b32 s15, s2, 2
	s_lshl_b32 s16, s2, 10
	s_add_i32 s2, s0, -10
	s_lshl_b32 s17, s2, 2
	s_lshl_b32 s33, s2, 10
	s_add_i32 s2, s0, -9
	v_readlane_b32 s10, v254, 27
	s_lshl_b32 s92, s7, 5
	s_lshl_b32 s74, s2, 2
	s_lshl_b32 s30, s2, 10
	s_add_i32 s31, s68, s10
	s_sub_i32 s90, s92, 64
	s_lshl_b32 s91, s7, 11
	s_and_b32 s2, s7, -2
	v_mul_f32_e32 v0, 0x4f7ffffe, v0
	s_cmp_lg_u32 s2, 2
	v_cvt_u32_f32_e32 v0, v0
	s_cselect_b64 s[50:51], -1, 0
	s_cmp_lt_i32 s7, 4
	s_cselect_b64 s[52:53], -1, 0
	s_add_i32 s87, s92, 0xffffff80
	s_lshl_b32 s2, s87, 1
	s_add_i32 s18, s67, s2
	v_readfirstlane_b32 s3, v0
	v_cvt_f32_ubyte0_e32 v0, s6
	s_add_u32 s2, s8, 0x613d4c00
	v_rcp_iflag_f32_e32 v0, v0
	v_writelane_b32 v254, s2, 48
	s_addc_u32 s2, s9, 0
	v_writelane_b32 v254, s2, 49
	s_add_u32 s2, s8, 0x5c754c00
	v_writelane_b32 v254, s2, 50
	s_addc_u32 s2, s9, 0
	s_add_u32 s19, s8, 0x4d954c00
	v_mul_f32_e32 v0, 0x4f7ffffe, v0
	v_writelane_b32 v254, s2, 51
	s_addc_u32 s20, s9, 0
	s_sub_i32 s2, 0, s72
	v_cvt_u32_f32_e32 v0, v0
	s_mul_i32 s2, s2, s3
	s_mul_hi_u32 s2, s3, s2
	s_add_i32 s2, s3, s2
	v_writelane_b32 v254, s2, 52
	s_sub_i32 s2, 0, s6
	v_readfirstlane_b32 s3, v0
	s_mul_i32 s2, s2, s3
	s_mul_hi_u32 s2, s3, s2
	v_writelane_b32 v254, s6, 53
	s_add_i32 s2, s3, s2
	v_writelane_b32 v254, s2, 54
	s_or_b32 s2, s0, 1
	s_lshl_b32 s21, s2, 2
	s_lshl_b32 s76, s2, 10
	s_or_b32 s2, s0, 2
	s_lshl_b32 s73, s2, 2
	s_lshl_b32 s75, s2, 10
	s_or_b32 s2, s0, 3
	s_lshl_b32 s82, s2, 2
	s_lshl_b32 s48, s2, 10
	s_or_b32 s2, s0, 4
	s_lshl_b32 s49, s2, 2
	s_lshl_b32 s93, s2, 10
	s_or_b32 s2, s0, 5
	s_lshl_b32 s94, s2, 2
	s_lshl_b32 s95, s2, 10
	s_or_b32 s2, s0, 6
	s_or_b32 s0, s0, 7
	s_lshl_b32 s80, s0, 2
	s_lshl_b32 s81, s0, 10
	s_lshl_b32 s0, s90, 2
	v_readlane_b32 s6, v253, 13
	s_add_i32 s0, s6, s0
	s_lshl_b32 s96, s2, 2
	s_lshl_b32 s97, s2, 10
	v_writelane_b32 v253, s0, 55
	s_lshl_b32 s85, s7, 13
	v_readlane_b32 s0, v252, 62
	s_add_u32 s0, s8, s0
	v_readlane_b32 s2, v252, 63
	s_addc_u32 s2, s9, s2
	s_mul_i32 s3, s69, 0xffff7800
	v_ashrrev_i32_e32 v6, 4, v82
; #define LAS __attribute__((address_space(3)))
; DEV void seq_s5_item(const Frame& F, int l, int item, int which) {
;     const int o = l >> 1; const int g = item & 31, d = (item >> 5) & 1, b = item >> 6;
;     LAS float* El = (LAS float*)(F.lds);
;     LAS unsigned char* wl = F.lds + 36864 + F.wave * 14336;
;     LAS float* scr = (LAS float*)wl; LAS bf16_t* hb = (LAS bf16_t*)(wl + 10240);
;     const bf16_t* P = (const bf16_t*)(F.ws + WS_P);
;     const float* Ab = (const float*)(F.ws + WS_S5A) + (size_t)((o * 2 + d) * 32 + g) * 128;
;     const bf16_t* Bb = (const bf16_t*)(F.ws + WS_S5B) + (size_t)((o * 2 + d) * 32 + g) * 128 * 16;
;     const bf16_t* Cm = (const bf16_t*)(F.ws + WS_S5C) + (size_t)(o * 32 + g) * 16 * 128;
;     const int l15 = F.lane & 15, kg = F.lane >> 4;
;     const float ar = Ab[F.lane], ai = Ab[64 + F.lane];
;     bf16x8 bB[8], cB[4]; const bf16x8 zero8 = (bf16x8){0, 0, 0, 0, 0, 0, 0, 0};
; #pragma unroll
;     for (int ct = 0; ct < 8; ++ct) bB[ct] = kg < 2 ? *(const bf16x8*)(Bb + (size_t)(16 * ct + l15) * 16 + 8 * kg) : zero8;
; #pragma unroll
;     for (int s = 0; s < 4; ++s) cB[s] = *(const bf16x8*)(Cm + (size_t)l15 * 128 + 32 * s + 8 * kg);
;     bf16_t* Obase = (bf16_t*)(F.ws + WS_O) + (size_t)d * MROWS * 1024 + 512 + 16 * g;
;     float* SE = (float*)(F.ws + WS_S5E) + (size_t)item * NCH * 128;
;     if (which == 1) { for (int i = F.tid; i < NCH * 128; i += NTHREADS) El[i] = SE[i]; __syncthreads(); }
;     for (int pass = which; pass < which + 1; ++pass) {
;         bf16x8 an[4];
; #pragma unroll
;         for (int st = 0; st < 4; ++st) an[st] = kg < 2 ? *(const bf16x8*)(P + (size_t)tok_row(b, d, F.wave * 64 + 16 * st + l15) * NIN_O + 2048 + 16 * g + 8 * kg) : zero8;
;         for (int n = F.wave; n < NCH; n += NWAVES) {
;             float hr = 0.f, hi = 0.f;
;             if (pass) { hr = El[n * 128 + F.lane]; hi = El[n * 128 + 64 + F.lane]; }
;             bf16x8 ac[4];
; #pragma unroll
;             for (int st = 0; st < 4; ++st) ac[st] = an[st];
;             { const int nn = n + NWAVES < NCH ? n + NWAVES : n;
; #pragma unroll
;               for (int st = 0; st < 4; ++st) an[st] = kg < 2 ? *(const bf16x8*)(P + (size_t)tok_row(b, d, nn * 64 + 16 * st + l15) * NIN_O + 2048 + 16 * g + 8 * kg) : zero8; }
;             const int r0 = tok_row(b, d, n * 64); const int sg = d ? -1 : 1;
	s_add_u32 s54, s0, s3
	s_mul_hi_i32 s0, s69, 0xffff7800
	v_ashrrev_i32_e32 v83, 31, v82
	v_lshlrev_b32_e32 v92, 3, v6
	s_addc_u32 s55, s2, s0
	v_lshl_add_u64 v[2:3], v[82:83], 2, s[8:9]
	s_mov_b64 s[2:3], 0x32bc8000
	v_ashrrev_i32_e32 v93, 31, v92
	v_and_b32_e32 v86, 15, v82
	v_lshl_add_u64 v[88:89], v[2:3], 0, s[2:3]
	v_lshlrev_b64 v[2:3], 1, v[92:93]
	v_lshl_add_u64 v[4:5], s[8:9], 0, v[2:3]
	s_mov_b64 s[2:3], 0x32bd8000
	v_lshlrev_b32_e32 v0, 8, v86
	v_lshl_add_u64 v[94:95], v[4:5], 0, s[2:3]
	v_lshl_add_u64 v[4:5], s[8:9], 0, v[0:1]
	v_lshl_add_u64 v[2:3], v[4:5], 0, v[2:3]
	v_add_u32_e32 v5, 0xffffff00, v84
	v_and_b32_e32 v7, 3, v82
	s_lshl_b32 s0, s7, 9
	v_ashrrev_i32_e32 v160, 2, v5
	v_lshlrev_b32_e32 v8, 2, v7
	v_lshlrev_b32_e32 v87, 2, v82
	s_add_i32 s0, s0, 0
	s_mov_b64 s[2:3], 0x32c58000
	v_bitop3_b32 v10, v160, v8, 15 bitop3:0x6c
	v_add_u32_e32 v91, s0, v87
	v_lshl_add_u64 v[96:97], v[2:3], 0, s[2:3]
	v_mov_b32_e32 v3, s77
	s_movk_i32 s0, 0x50
	v_lshlrev_b32_e32 v162, 4, v10
	v_or_b32_e32 v10, 1, v8
	v_mad_u32_u24 v3, v86, s0, v3
	v_mul_lo_u32 v4, v82, s0
	v_readlane_b32 s0, v253, 10
	v_bitop3_b32 v10, v160, v10, 15 bitop3:0x6c
	v_lshlrev_b32_e32 v163, 4, v10
	v_lshl_add_u32 v159, v84, 2, s0
	v_or_b32_e32 v10, 2, v8
	s_sub_i32 s0, 0, s10
	v_bitop3_b32 v10, v160, v10, 15 bitop3:0x6c
	v_and_b32_e32 v5, -4, v5
	v_writelane_b32 v254, s0, 55
	s_movk_i32 s0, 0x2200
	v_lshlrev_b32_e32 v164, 4, v10
	v_add_u32_e32 v166, s6, v5
	v_lshl_add_u32 v10, s7, 8, v87
	v_cmp_gt_i32_e64 s[6:7], s0, v84
	v_or_b32_e32 v110, s10, v86
	v_or_b32_e32 v114, 16, v110
	v_writelane_b32 v254, s6, 56
	v_or_b32_e32 v118, 32, v110
	v_or_b32_e32 v122, 48, v110
	v_writelane_b32 v254, s7, 57
	v_cmp_gt_i32_e64 s[6:7], s63, v110
	s_movk_i32 s0, 0x880
	v_max_i32_e32 v5, 0x2000, v84
	v_writelane_b32 v254, s6, 58
	v_or_b32_e32 v8, 3, v8
	v_sub_u32_e32 v5, v5, v84
	v_writelane_b32 v254, s7, 59
	v_cmp_gt_i32_e64 s[6:7], s63, v114
	v_bitop3_b32 v8, v160, v8, 15 bitop3:0x6c
	v_add_u32_e32 v5, 0x1ff, v5
	v_writelane_b32 v254, s6, 60
	v_lshlrev_b32_e32 v165, 4, v8
	v_lshrrev_b32_e32 v8, 9, v5
	v_writelane_b32 v254, s7, 61
	v_cmp_gt_i32_e64 s[6:7], s63, v118
	v_add_u32_e32 v8, 1, v8
	v_and_b32_e32 v168, 0xfffffe, v8
	v_writelane_b32 v254, s6, 62
	v_and_b32_e32 v2, -16, v82
	v_add_u32_e32 v0, s77, v0
	v_writelane_b32 v254, s7, 63
	v_cmp_gt_i32_e64 s[6:7], s63, v122
	v_lshlrev_b32_e32 v83, 2, v6
	v_lshlrev_b32_e32 v9, 7, v7
	v_writelane_b32 v255, s6, 0
	v_or_b32_e32 v127, 1, v83
	v_or_b32_e32 v129, 2, v83
	v_writelane_b32 v255, s7, 1
	v_cmp_gt_i32_e64 s[6:7], s0, v84
	s_movk_i32 s0, 0x80
	v_or_b32_e32 v131, 3, v83
	v_writelane_b32 v255, s6, 2
	v_add_u32_e32 v175, v0, v2
	v_add_u32_e32 v0, 0, v9
	v_writelane_b32 v255, s7, 3
	v_cmp_gt_i32_e64 s[6:7], s0, v84
	s_movk_i32 s0, 0x180
	v_lshlrev_b32_e32 v90, 4, v86
	v_writelane_b32 v255, s6, 4
	v_add_u32_e32 v111, 0xffffff00, v110
	v_sub_u32_e32 v112, 0x10ff, v110
	v_writelane_b32 v255, s7, 5
	v_cmp_eq_u32_e64 s[6:7], 0, v7
	v_sub_u32_e32 v113, 0xff, v110
	v_add_u32_e32 v115, 0xffffff10, v110
	v_writelane_b32 v255, s6, 6
	v_sub_u32_e32 v116, 0x10ff, v114
	v_sub_u32_e32 v117, 0xff, v114
	v_writelane_b32 v255, s7, 7
	v_cmp_gt_i32_e64 s[6:7], s0, v84
	s_movk_i32 s0, 0x1ff
	v_add_u32_e32 v119, 0xffffff20, v110
	v_writelane_b32 v255, s6, 8
	v_sub_u32_e32 v120, 0x10ff, v118
	v_sub_u32_e32 v121, 0xff, v118
	v_writelane_b32 v255, s7, 9
	v_cmp_lt_u32_e64 s[6:7], s0, v5
	v_add_u32_e32 v123, 0xffffff30, v110
	v_sub_u32_e32 v124, 0x10ff, v122
	v_writelane_b32 v255, s6, 10
	v_sub_u32_e32 v125, 0xff, v122
	v_sub_u32_e32 v126, 0, v83
	v_writelane_b32 v255, s7, 11
	v_cmp_ne_u32_e64 s[6:7], v8, v168
	v_sub_u32_e32 v128, 0, v127
	v_sub_u32_e32 v130, 0, v129
	v_writelane_b32 v255, s6, 12
	v_sub_u32_e32 v132, 0, v131
	v_add_u32_e32 v133, 16, v83
	v_writelane_b32 v255, s7, 13
	v_writelane_b32 v255, s69, 14
	v_sub_u32_e32 v134, -16, v83
	v_add_u32_e32 v135, 17, v83
	v_sub_u32_e32 v136, 0xffffffef, v83
	v_add_u32_e32 v137, 18, v83
	v_sub_u32_e32 v138, 0xffffffee, v83
	v_add_u32_e32 v139, 19, v83
	v_sub_u32_e32 v140, 0xffffffed, v83
	v_add_u32_e32 v141, 32, v83
	v_sub_u32_e32 v142, 0xffffffe0, v83
	v_add_u32_e32 v143, 33, v83
	v_sub_u32_e32 v144, 0xffffffdf, v83
	v_add_u32_e32 v145, 34, v83
	v_sub_u32_e32 v147, 0xffffffde, v83
	v_add_u32_e32 v148, 35, v83
	v_sub_u32_e32 v150, 0xffffffdd, v83
	v_add_u32_e32 v151, 48, v83
	v_sub_u32_e32 v152, 0xffffffd0, v83
	v_add_u32_e32 v153, 49, v83
	v_sub_u32_e32 v154, 0xffffffcf, v83
	v_add_u32_e32 v155, 50, v83
	v_sub_u32_e32 v156, 0xffffffce, v83
	v_add_u32_e32 v157, 51, v83
	v_sub_u32_e32 v158, 0xffffffcd, v83
	v_lshlrev_b32_e32 v161, 8, v160
	v_add_u32_e32 v167, 0xfffffc00, v159
	v_lshl_add_u32 v169, v168, 9, v84
	v_add_u32_e32 v85, 0x200, v84
	v_add_u32_e32 v170, 0, v10
	v_add_u32_e32 v171, 0xfffffe00, v84
	v_add_u32_e32 v172, s67, v10
	v_add_u32_e32 v173, v3, v2
	v_add_u32_e32 v174, s77, v4
	v_add_u32_e32 v176, 0x24400, v0
	v_readlane_b32 s86, v252, 61
	v_cmp_gt_i32_e64 s[2:3], 2, v6
	v_writelane_b32 v255, s83, 15
	s_branch .LBB0_817

; #define LAS __attribute__((address_space(3)))
; #define NT_LOAD(p) __builtin_nontemporal_load(p)
; DEV void tr_item(const float* W, int ldw, int col0, int k0, bf16_t* WT, int K, int row0, LAS float* scr, int lane) {
; #pragma unroll 8
;     for (int i = 0; i < 32; ++i) { const int kk = 2 * i + (lane >> 5); scr[kk * 33 + (lane & 31)] = NT_LOAD(&W[(size_t)(k0 + kk) * ldw + col0 + (lane & 31)]); }
.Lbw5_gate:
	s_add_u32 s42, s100, s42
	s_addc_u32 s43, s101, 0
	s_lshl_b32 s39, s41, 16
	s_or_b32 s41, s39, s40
	v_lshrrev_b32_e32 v127, 5, v200
	v_and_b32_e32 v128, 31, v200
	v_lshlrev_b32_e32 v128, 2, v128
	v_lshl_add_u32 v36, v127, 13, v128
	v_mov_b32_e32 v37, 0
	s_mov_b64 s[100:101], 0x4000
	v_lshl_add_u64 v[20:21], s[42:43], 0, v[36:37]
	v_lshl_add_u64 v[22:23], v[20:21], 0, s[100:101]
	v_lshl_add_u64 v[24:25], v[22:23], 0, s[100:101]
	v_lshl_add_u64 v[26:27], v[24:25], 0, s[100:101]
	v_lshl_add_u64 v[28:29], v[26:27], 0, s[100:101]
	v_lshl_add_u64 v[30:31], v[28:29], 0, s[100:101]
	v_lshl_add_u64 v[32:33], v[30:31], 0, s[100:101]
	v_lshl_add_u64 v[34:35], v[32:33], 0, s[100:101]
	s_mov_b64 s[100:101], 0x20000
	global_load_dword v38, v[20:21], off nt
	global_load_dword v39, v[22:23], off nt
	global_load_dword v40, v[24:25], off nt
	global_load_dword v41, v[26:27], off nt
	global_load_dword v42, v[28:29], off nt
	global_load_dword v43, v[30:31], off nt
	global_load_dword v44, v[32:33], off nt
	global_load_dword v45, v[34:35], off nt
	v_lshl_add_u64 v[20:21], v[20:21], 0, s[100:101]
	v_lshl_add_u64 v[22:23], v[22:23], 0, s[100:101]
	v_lshl_add_u64 v[24:25], v[24:25], 0, s[100:101]
	v_lshl_add_u64 v[26:27], v[26:27], 0, s[100:101]
	v_lshl_add_u64 v[28:29], v[28:29], 0, s[100:101]
	v_lshl_add_u64 v[30:31], v[30:31], 0, s[100:101]
	v_lshl_add_u64 v[32:33], v[32:33], 0, s[100:101]
	v_lshl_add_u64 v[34:35], v[34:35], 0, s[100:101]
	global_load_dword v46, v[20:21], off nt
	global_load_dword v47, v[22:23], off nt
	global_load_dword v48, v[24:25], off nt
	global_load_dword v49, v[26:27], off nt
	global_load_dword v50, v[28:29], off nt
	global_load_dword v51, v[30:31], off nt
	global_load_dword v52, v[32:33], off nt
	global_load_dword v53, v[34:35], off nt
	v_lshl_add_u64 v[20:21], v[20:21], 0, s[100:101]
	v_lshl_add_u64 v[22:23], v[22:23], 0, s[100:101]
	v_lshl_add_u64 v[24:25], v[24:25], 0, s[100:101]
	v_lshl_add_u64 v[26:27], v[26:27], 0, s[100:101]
	v_lshl_add_u64 v[28:29], v[28:29], 0, s[100:101]
	v_lshl_add_u64 v[30:31], v[30:31], 0, s[100:101]
	v_lshl_add_u64 v[32:33], v[32:33], 0, s[100:101]
	v_lshl_add_u64 v[34:35], v[34:35], 0, s[100:101]
	global_load_dword v54, v[20:21], off nt
	global_load_dword v55, v[22:23], off nt
	global_load_dword v56, v[24:25], off nt
	global_load_dword v57, v[26:27], off nt
	global_load_dword v58, v[28:29], off nt
	global_load_dword v59, v[30:31], off nt
	global_load_dword v60, v[32:33], off nt
	global_load_dword v61, v[34:35], off nt
	v_lshl_add_u64 v[20:21], v[20:21], 0, s[100:101]
	v_lshl_add_u64 v[22:23], v[22:23], 0, s[100:101]
	v_lshl_add_u64 v[24:25], v[24:25], 0, s[100:101]
	v_lshl_add_u64 v[26:27], v[26:27], 0, s[100:101]
	v_lshl_add_u64 v[28:29], v[28:29], 0, s[100:101]
	v_lshl_add_u64 v[30:31], v[30:31], 0, s[100:101]
	v_lshl_add_u64 v[32:33], v[32:33], 0, s[100:101]
	v_lshl_add_u64 v[34:35], v[34:35], 0, s[100:101]
	global_load_dword v62, v[20:21], off nt
	global_load_dword v63, v[22:23], off nt
	global_load_dword v64, v[24:25], off nt
	global_load_dword v65, v[26:27], off nt
	global_load_dword v66, v[28:29], off nt
	global_load_dword v67, v[30:31], off nt
	global_load_dword v68, v[32:33], off nt
	global_load_dword v69, v[34:35], off nt
	s_branch .Lbw5_fin

; #define WAVE_LDS_SYNC() do { int _z = 0; (void)emu::wave_xchg(&_z, 4); } while (0)
; #define LAS __attribute__((address_space(3)))
; #define WAVE_LDS_SYNC() asm volatile("s_waitcnt lgkmcnt(0)" ::: "memory")
; #define NT_LOAD(p) __builtin_nontemporal_load(p)
; #define NT_STORE(v, p) __builtin_nontemporal_store((v), (p))
; DEV unsigned pk2(float lo, float hi) { return f2bf(lo) | (f2bf(hi) << 16); }
; DEV unsigned pk2(float lo, float hi) { const f32x2n_t v = {lo, hi}; return __builtin_bit_cast(unsigned, __builtin_convertvector(v, bf16x2n_t)); }
; DEV void tr_item(const float* W, int ldw, int col0, int k0, bf16_t* WT, int K, int row0, LAS float* scr, int lane) {
; #pragma unroll 8
;     for (int i = 0; i < 32; ++i) { const int kk = 2 * i + (lane >> 5); scr[kk * 33 + (lane & 31)] = NT_LOAD(&W[(size_t)(k0 + kk) * ldw + col0 + (lane & 31)]); }
;     WAVE_LDS_SYNC();
;     const int c = lane & 7;
; #pragma unroll
;     for (int j = 0; j < 4; ++j) { const int n = (lane >> 3) + 8 * j; const LAS float* s = scr + (8 * c) * 33 + n;
;         u32x4 o; o.x = pk2(s[0 * 33], s[1 * 33]); o.y = pk2(s[2 * 33], s[3 * 33]); o.z = pk2(s[4 * 33], s[5 * 33]); o.w = pk2(s[6 * 33], s[7 * 33]);
;         NT_STORE(o, (u32x4*)(WT + (size_t)(row0 + n) * K + k0 + 8 * c)); }
;     WAVE_LDS_SYNC();
.Lbw5_fin:
	v_writelane_b32 v255, s41, 60
	s_nop 0
	v_readlane_b32 s40, v255, 60
	s_cmp_eq_u32 s40, 0
	s_cbranch_scc1 .Lbw5_skip
	s_lshr_b32 s41, s40, 16
	s_and_b32 s40, s40, 0xffff
	s_and_b32 s38, s40, 0x7ff
	s_lshr_b32 s39, s38, 7
	s_and_b32 s38, s38, 0x7f
	s_lshl_b32 s42, s38, 16
	s_lshl_b32 s39, s39, 7
	s_add_i32 s42, s42, s39
	s_lshr_b32 s39, s40, 11
	s_lshl_b32 s39, s39, 23
	s_add_i32 s42, s42, s39
	s_lshl_b32 s39, s41, 27
	s_add_u32 s42, s42, s39
	s_add_u32 s42, s42, 0x2bc8000
	v_readlane_b32 s100, v255, 53
	v_readlane_b32 s101, v255, 54
	s_add_u32 s42, s100, s42
	s_addc_u32 s43, s101, 0
	v_readlane_b32 s39, v251, 29
	s_lshl_b32 s39, s39, 14
	v_and_b32_e32 v127, 31, v200
	v_lshrrev_b32_e32 v128, 5, v200
	v_mul_u32_u24_e32 v128, 33, v128
	v_add_u32_e32 v128, v128, v127
	v_lshl_add_u32 v118, v128, 2, s39
	v_add_u32_e32 v119, 0x400, v118
	v_add_u32_e32 v120, 0x840, v118
	v_add_u32_e32 v121, 0xc40, v118
	v_add_u32_e32 v122, 0x1080, v118
	v_add_u32_e32 v123, 0x1480, v118
	v_add_u32_e32 v124, 0x18c0, v118
	v_add_u32_e32 v125, 0x1cc0, v118
	v_and_b32_e32 v127, 7, v200
	v_lshrrev_b32_e32 v128, 3, v200
	v_mul_u32_u24_e32 v129, 0x108, v127
	v_add_u32_e32 v129, v129, v128
	v_lshl_add_u32 v126, v129, 2, s39
	v_lshlrev_b32_e32 v127, 4, v127
	v_lshl_add_u32 v36, v128, 11, v127
	v_mov_b32_e32 v37, 0
	s_mov_b64 s[100:101], 0x4000
	v_lshl_add_u64 v[20:21], s[42:43], 0, v[36:37]
	v_lshl_add_u64 v[22:23], v[20:21], 0, s[100:101]
	v_lshl_add_u64 v[24:25], v[22:23], 0, s[100:101]
	v_lshl_add_u64 v[26:27], v[24:25], 0, s[100:101]
	s_waitcnt vmcnt(0)
	ds_write2_b32 v118, v38, v39 offset1:66
	ds_write2_b32 v118, v40, v41 offset0:132 offset1:198
	ds_write2_b32 v119, v42, v43 offset0:8 offset1:74
	ds_write2_b32 v119, v44, v45 offset0:140 offset1:206
	ds_write2_b32 v120, v46, v47 offset1:66
	ds_write2_b32 v120, v48, v49 offset0:132 offset1:198
	ds_write2_b32 v121, v50, v51 offset0:8 offset1:74
	ds_write2_b32 v121, v52, v53 offset0:140 offset1:206
	ds_write2_b32 v122, v54, v55 offset1:66
	ds_write2_b32 v122, v56, v57 offset0:132 offset1:198
	ds_write2_b32 v123, v58, v59 offset0:8 offset1:74
	ds_write2_b32 v123, v60, v61 offset0:140 offset1:206
	ds_write2_b32 v124, v62, v63 offset1:66
	ds_write2_b32 v124, v64, v65 offset0:132 offset1:198
	ds_write2_b32 v125, v66, v67 offset0:8 offset1:74
	ds_write2_b32 v125, v68, v69 offset0:140 offset1:206
	ds_read2_b32 v[70:71], v126 offset1:8
	ds_read2_b32 v[72:73], v126 offset0:33 offset1:41
	ds_read2_b32 v[74:75], v126 offset0:66 offset1:74
	ds_read2_b32 v[76:77], v126 offset0:99 offset1:107
	ds_read2_b32 v[78:79], v126 offset0:132 offset1:140
	ds_read2_b32 v[80:81], v126 offset0:165 offset1:173
	ds_read2_b32 v[82:83], v126 offset0:198 offset1:206
	ds_read2_b32 v[84:85], v126 offset0:231 offset1:239
	ds_read2_b32 v[86:87], v126 offset0:16 offset1:24
	ds_read2_b32 v[88:89], v126 offset0:49 offset1:57
	ds_read2_b32 v[90:91], v126 offset0:82 offset1:90
	ds_read2_b32 v[92:93], v126 offset0:115 offset1:123
	s_waitcnt lgkmcnt(4)
	v_cvt_pk_bf16_f32 v102, v70, v72
	v_cvt_pk_bf16_f32 v103, v74, v76
	v_cvt_pk_bf16_f32 v104, v78, v80
	v_cvt_pk_bf16_f32 v105, v82, v84
	v_cvt_pk_bf16_f32 v106, v71, v73
	v_cvt_pk_bf16_f32 v107, v75, v77
	v_cvt_pk_bf16_f32 v108, v79, v81
	v_cvt_pk_bf16_f32 v109, v83, v85
	ds_read2_b32 v[94:95], v126 offset0:148 offset1:156
	ds_read2_b32 v[96:97], v126 offset0:181 offset1:189
	ds_read2_b32 v[98:99], v126 offset0:214 offset1:222
	ds_read2_b32 v[100:101], v126 offset0:247 offset1:255
	global_store_dwordx4 v[20:21], v[102:105], off nt
	global_store_dwordx4 v[22:23], v[106:109], off nt
	s_waitcnt lgkmcnt(0)
	v_cvt_pk_bf16_f32 v110, v86, v88
	v_cvt_pk_bf16_f32 v111, v90, v92
	v_cvt_pk_bf16_f32 v112, v94, v96
	v_cvt_pk_bf16_f32 v113, v98, v100
	v_cvt_pk_bf16_f32 v114, v87, v89
	v_cvt_pk_bf16_f32 v115, v91, v93
	v_cvt_pk_bf16_f32 v116, v95, v97
	v_cvt_pk_bf16_f32 v117, v99, v101
	global_store_dwordx4 v[24:25], v[110:113], off nt
	global_store_dwordx4 v[26:27], v[114:117], off nt
; #define ROW_LOOP_SPREAD(r, NROWS) for (int _it = 0, _nf = (NROWS) / F.NGW, r = (_nf > 0 ? F.gw : F.wave * F.G + F.bid); _it <= _nf && r < (NROWS); ++_it, r = _it * F.NGW + (_it < _nf ? F.gw : F.wave * F.G + F.bid))
; DEV void phase_merge(const Frame& F0, int l) {
;     const Frame F = refresh(F0);
;     const int odd = l & 1, li = l >> 1; const bf16_t* P = (const bf16_t*)(F.ws + WS_P);
;     const bf16_t* O0 = (const bf16_t*)(F.ws + WS_O); const bf16_t* O1 = O0 + (size_t)MROWS * 1024;
;     bf16_t* MG = (bf16_t*)(F.ws + WS_MERGED);
;     const int nrows = (l == DEPTH - 1) ? LATR : MROWS;
;     ROW_LOOP_SPREAD(r, nrows) {
.Lbw5_skip:
	s_waitcnt lgkmcnt(0)
	v_readlane_b32 s38, v255, 61
	s_cmp_lg_u32 s38, 0
	v_readlane_b32 s4, v251, 0
	v_readlane_b32 s0, v251, 29
	v_readlane_b32 s2, v251, 30
	v_readlane_b32 s5, v251, 1
	s_waitcnt lgkmcnt(0)
	s_barrier
	s_add_i32 s14, s0, s2
	v_readlane_b32 s4, v253, 62
	s_cmp_lg_u32 s4, 3
	v_readlane_b32 s5, v253, 63
	s_cselect_b64 s[58:59], -1, 0
	s_cmp_eq_u32 s4, 3
	s_cselect_b64 s[4:5], -1, 0
	v_writelane_b32 v253, s4, 51
	v_readlane_b32 s8, v252, 54
	v_readlane_b32 s6, v251, 2
	v_writelane_b32 v253, s5, 52
	s_and_b64 s[4:5], s[4:5], exec
	s_movk_i32 s4, 0x4400
	s_cselect_b32 s70, 0x4000, s4
	v_readlane_b32 s4, v252, 55
	s_mul_hi_u32 s4, s70, s4
	s_mul_i32 s5, s4, s8
	v_readlane_b32 s7, v251, 3
	s_sub_i32 s5, s70, s5
	s_mov_b64 s[2:3], s[6:7]
	s_add_i32 s6, s4, 1
	s_sub_i32 s7, s5, s8
	s_cmp_ge_u32 s5, s8
	s_cselect_b32 s4, s6, s4
	s_cselect_b32 s5, s7, s5
	s_add_i32 s6, s4, 1
	s_cmp_ge_u32 s5, s8
	s_cselect_b32 s4, s6, s4
	s_xor_b32 s4, s4, s55
	s_mul_i32 s16, s0, s96
	s_sub_i32 s15, s4, s55
	s_add_i32 s16, s16, s95
	s_cmp_gt_i32 s15, 0
	s_cselect_b32 s8, s14, s16
	s_cmp_gt_i32 s15, -1
	s_cselect_b64 s[4:5], -1, 0
	s_cmp_lt_i32 s8, s70
	s_cselect_b64 s[6:7], -1, 0
	s_and_b64 s[4:5], s[4:5], s[6:7]
	v_mov_b32_e32 v2, v200
	s_andn2_b64 vcc, exec, s[4:5]
	s_cbranch_vccnz .LBB0_1209
	v_lshlrev_b32_e32 v34, 3, v2
	s_add_u32 s6, s2, 0x415d4c00
	v_readlane_b32 s4, v253, 62
	v_ashrrev_i32_e32 v35, 31, v34
	s_addc_u32 s7, s3, 0
	s_lshr_b32 s4, s4, 1
	v_lshl_add_u64 v[4:5], v[34:35], 1, s[2:3]
	s_mov_b64 s[2:3], 0x613d4c00
	v_lshl_add_u64 v[36:37], v[4:5], 0, s[2:3]
	s_mov_b64 s[2:3], 0x635d4c00
	s_lshl_b32 s0, s4, 9
	v_readlane_b32 s36, v251, 31
	v_lshl_add_u64 v[38:39], v[4:5], 0, s[2:3]
	s_mov_b64 s[2:3], 0x393a8800
	v_ashrrev_i32_e32 v3, 31, v2
	s_lshl_b32 s4, s4, 7
	s_lshl_b64 s[10:11], s[0:1], 2
	v_readlane_b32 s38, v251, 33
	v_readlane_b32 s20, v251, 4
	v_lshl_add_u64 v[40:41], v[4:5], 0, s[2:3]
	v_lshlrev_b64 v[6:7], 4, v[2:3]
	v_readlane_b32 s39, v251, 34
	s_add_u32 s12, s38, s10
	v_readlane_b32 s22, v251, 6
	v_readlane_b32 s23, v251, 7
	v_readlane_b32 s5, v253, 63
	s_mov_b64 s[2:3], 0x3b5a8800
	v_lshl_add_u64 v[44:45], v[36:37], 0, v[6:7]
	v_lshl_add_u64 v[46:47], v[38:39], 0, v[6:7]
	v_lshl_add_u64 v[50:51], v[40:41], 0, v[6:7]
	v_readlane_b32 s37, v251, 32
	v_readlane_b32 s40, v251, 35
	v_readlane_b32 s41, v251, 36
	v_readlane_b32 s42, v251, 37
	v_readlane_b32 s43, v251, 38
	v_readlane_b32 s44, v251, 39
	v_readlane_b32 s45, v251, 40
	v_readlane_b32 s46, v251, 41
	v_readlane_b32 s47, v251, 42
	v_readlane_b32 s48, v251, 43
	v_readlane_b32 s49, v251, 44
	v_readlane_b32 s50, v251, 45
	v_readlane_b32 s51, v251, 46
	s_addc_u32 s13, s39, s11
	v_lshlrev_b64 v[6:7], 2, v[34:35]
	s_mov_b64 s[18:19], s[22:23]
	v_lshl_add_u64 v[42:43], v[4:5], 0, s[2:3]
	v_cmp_lt_i32_e64 s[2:3], 31, v2
	v_mov_b32_e32 v0, 0x600
	v_mov_b32_e32 v3, 0xc00
	s_mov_b32 s5, s1
	v_lshl_add_u64 v[52:53], s[12:13], 0, v[6:7]
	s_add_u32 s12, s18, s10
	v_readlane_b32 s36, v251, 12
	v_lshlrev_b32_e32 v4, 4, v2
	v_cndmask_b32_e64 v0, v0, v3, s[2:3]
	s_addc_u32 s13, s19, s11
	s_lshl_b64 s[4:5], s[4:5], 2
	v_readlane_b32 s42, v251, 18
	v_add_u32_e32 v8, v0, v4
	v_readlane_b32 s43, v251, 19
	s_add_u32 s4, s42, s4
	v_lshlrev_b32_e32 v0, 6, v2
	v_readlane_b32 s44, v251, 20
	s_addc_u32 s5, s43, s5
	v_and_b32_e32 v2, 0x1c0, v0
	v_mov_b32_e32 v3, v1
	v_readlane_b32 s45, v251, 21
	v_lshl_add_u64 v[2:3], s[4:5], 0, v[2:3]
	s_add_u32 s4, s44, s10
	v_mov_b32_e32 v5, v1
	s_addc_u32 s5, s45, s11
	v_lshl_add_u64 v[4:5], v[4:5], 2, s[4:5]
	s_movk_i32 s4, 0xf800
	s_mov_b32 s5, -1
	v_ashrrev_i32_e32 v9, 31, v8
	v_lshl_add_u64 v[4:5], v[4:5], 0, s[4:5]
	v_lshl_add_u64 v[48:49], v[8:9], 1, s[6:7]
	v_lshl_add_u64 v[54:55], s[12:13], 0, v[6:7]
	v_cndmask_b32_e64 v57, v3, v5, s[2:3]
	v_cndmask_b32_e64 v56, v2, v4, s[2:3]
	s_mov_b32 s17, 0
	s_mov_b32 s0, s54
	v_readlane_b32 s21, v251, 5
	v_readlane_b32 s24, v251, 8
	v_readlane_b32 s25, v251, 9
	v_readlane_b32 s26, v251, 10
	v_readlane_b32 s27, v251, 11
	v_readlane_b32 s37, v251, 13
	v_readlane_b32 s38, v251, 14
	v_readlane_b32 s39, v251, 15
	v_readlane_b32 s40, v251, 16
	v_readlane_b32 s41, v251, 17
	v_readlane_b32 s46, v251, 22
	v_readlane_b32 s47, v251, 23
	v_readlane_b32 s48, v251, 24
	v_readlane_b32 s49, v251, 25
	v_readlane_b32 s50, v251, 26
	v_readlane_b32 s51, v251, 27
	s_branch .LBB0_1205

; #define LAS __attribute__((address_space(3)))
;     DEV size_t idx_base(const Unit& u) const { return (size_t)u.e * EPAD + (size_t)u.pm * BM; }
; template <class Epi, class Sched>
; DEV void gemm_phase(LAS unsigned char* lds, const int K, const Sched& S, const Epi& E, const int wid, const int lane) {
;     const int tid = wid * 64 + lane; const int wr = wid >> 2, wc = wid & 3, fr = lane & 15, fq = lane >> 4;
;     const int nt = K / BK;
;     unsigned voffA[2], voffB[2]; int Ri[2], Ci[2];
; #pragma unroll
;     for (int i = 0; i < 2; ++i) { int R, C; stage_rc(tid * 16 + i * 8192, R, C); const int Rb = Epi::PERM ? ((R & ~31) + perm32(R & 31)) : R; Ri[i] = R; Ci[i] = C;
;         voffA[i] = (unsigned)(R * K + C) * 2u; voffB[i] = (unsigned)(Rb * K + C) * 2u; }
;     unsigned goffC[2][2] = {{0u, 0u}, {0u, 0u}}, goffN[2][2] = {{0u, 0u}, {0u, 0u}};
;     constexpr int GIDX_OFF = STAGE_BYTES;
;     const size_t kstep = (size_t)(BK * 2);
;     const size_t hstep = (size_t)HALF * K * 2;
;     const unsigned ldsw = (unsigned)wid * 1024u;
;     const int aoff = lds_byte(wr * 64 + fr, fq * 8), boff = lds_byte(wc * 32 + fr, fq * 8);
;     ...
;     Unit cur, nxt; int ui = 0;
;     if (!S.next(0, cur)) return;
;     f32x4 acc[2][2][4][2];
; #pragma unroll
;     for (int a = 0; a < 2; ++a)
; #pragma unroll
;         for (int b = 0; b < 2; ++b)
; #pragma unroll
;             for (int m = 0; m < 4; ++m)
; #pragma unroll
;                 for (int n = 0; n < 2; ++n) acc[a][b][m][n] = (f32x4){0.f, 0.f, 0.f, 0.f};
;     bf16x8 At[4][2], B0[2][2], B1[2][2];
;     const char* cA = cur.A; const char* cB = cur.B;
;     if constexpr (Sched::GATHER_A) {
; #pragma unroll
;         for (int hh = 0; hh < 2; ++hh)
; #pragma unroll
;             for (int i = 0; i < 2; ++i) { goffC[hh][i] = (unsigned)S.gidx[S.idx_base(cur) + hh * HALF + Ri[i]] * (unsigned)(K * 2) + (unsigned)(Ci[i] * 2); goffN[hh][i] = goffC[hh][i]; }
;     }
; DEV void gemm_glu(const Frame& F0, int l, int vcu) {
;     const Frame F = refresh(F0);
;     const int li = l >> 1;
;     pg8::PlainOrder S; S.init((const void*)(F.ws + WS_YS), (const bf16_t*)(F.ws + WS_WGLU) + (size_t)li * 512 * 512, 512, (l == DEPTH - 1) ? LATPAD : MPAD, 512, F.G, vcu);
;     EpiGlu E; E.MG = (bf16_t*)(F.ws + WS_MERGED); E.YS = (const bf16_t*)(F.ws + WS_YS); E.bias = GIN(I_ODBGLU) + li * 512;
;     pg8::gemm_phase(F.lds, 512, S, E, F.wave, F.lane);
.Lbw6_skip:
	s_waitcnt lgkmcnt(0)
	v_readlane_b32 s38, v255, 61
	s_cmp_lg_u32 s38, 0
	s_mov_b64 s[2:3], -1
	s_and_b64 vcc, exec, s[56:57]
	s_waitcnt lgkmcnt(0)
	s_barrier
	s_cbranch_vccz .LBB0_1315
	v_readlane_b32 s4, v251, 0
	v_readlane_b32 s5, v251, 1
	v_readlane_b32 s4, v253, 51
	v_readlane_b32 s5, v253, 52
	s_and_b64 s[4:5], s[4:5], exec
	s_cselect_b32 s33, 64, 0x44
	v_readlane_b32 s6, v251, 2
	v_readlane_b32 s7, v251, 3
	s_lshl_b32 s0, s33, 1
	v_readlane_b32 s12, v251, 29
	v_mov_b32_e32 v16, v200
	s_mov_b64 s[2:3], s[6:7]
	s_cmp_ge_i32 s95, s0
	s_cbranch_scc1 .LBB0_1270
	v_readlane_b32 s4, v253, 62
	s_lshr_b32 s10, s4, 1
	v_readlane_b32 s5, v253, 63
	s_add_u32 s4, s2, 0x3b5a8800
	s_addc_u32 s5, s3, 0
	s_lshl_b32 s6, s10, 19
	s_add_u32 s6, s2, s6
	s_addc_u32 s7, s3, 0
	s_add_u32 s30, s6, 0x2ac8000
	s_addc_u32 s31, s7, 0
	s_lshl_b32 s34, s12, 10
	v_lshl_add_u32 v0, v16, 4, s34
	v_add_u32_e32 v2, 0x2000, v0
	v_ashrrev_i32_e32 v3, 31, v2
	v_lshrrev_b32_e32 v3, 22, v3
	v_add_u32_e32 v3, v2, v3
	v_ashrrev_i32_e32 v10, 10, v3
	v_mul_i32_i24_e32 v3, 0x400, v10
	v_sub_u32_e32 v2, v2, v3
	v_lshrrev_b32_e32 v3, 4, v2
	v_bitop3_b32 v2, v3, v2, 32 bitop3:0x6c
	v_ashrrev_i32_e32 v3, 31, v2
	v_lshrrev_b32_e32 v3, 26, v3
	v_add_u32_e32 v3, v2, v3
	v_ashrrev_i32_e32 v11, 6, v3
	v_lshlrev_b32_e32 v4, 3, v10
	v_and_b32_e32 v3, 0xffc0, v3
	v_and_b32_e32 v4, -16, v4
	v_sub_u32_e32 v2, v2, v3
	v_add_u32_e32 v4, v11, v4
	v_lshrrev_b16_e32 v3, 7, v2
	v_and_b32_e32 v5, 3, v11
	s_mov_b32 s6, 0x3fffe0
	v_lshrrev_b32_e32 v6, 2, v4
	v_lshlrev_b32_e32 v7, 1, v4
	v_and_b32_e32 v3, 1, v3
	v_and_or_b32 v5, v4, s6, v5
	v_and_b32_e32 v6, 4, v6
	v_and_b32_e32 v7, 24, v7
	v_add_u16_e32 v2, v2, v3
	v_or3_b32 v5, v5, v6, v7
	v_lshlrev_b32_e32 v6, 5, v10
	v_ashrrev_i16_sdwa v2, v202, sext(v2) dst_sel:DWORD dst_unused:UNUSED_PAD src0_sel:DWORD src1_sel:BYTE_0
	v_and_b32_e32 v6, 32, v6
	v_bfe_i32 v13, v2, 0, 16
	v_add_lshl_u32 v2, v6, v13, 1
	v_lshl_add_u32 v130, v5, 10, v2
	v_lshl_add_u32 v132, v4, 10, v2
	v_ashrrev_i32_e32 v2, 31, v0
	v_lshrrev_b32_e32 v2, 22, v2
	v_add_u32_e32 v2, v0, v2
	v_ashrrev_i32_e32 v12, 10, v2
	v_mul_i32_i24_e32 v2, 0x400, v12
	v_sub_u32_e32 v0, v0, v2
	v_lshrrev_b32_e32 v2, 4, v0
	v_bitop3_b32 v0, v2, v0, 32 bitop3:0x6c
	v_ashrrev_i32_e32 v2, 31, v0
	v_lshrrev_b32_e32 v2, 26, v2
	v_add_u32_e32 v2, v0, v2
	v_lshlrev_b32_e32 v3, 3, v12
	v_ashrrev_i32_e32 v14, 6, v2
	v_and_b32_e32 v3, -16, v3
	v_add_u32_e32 v3, v14, v3
	v_and_b32_e32 v4, 3, v14
	v_and_or_b32 v4, v3, s6, v4
	s_lshr_b32 s35, s33, 2
	v_readlane_b32 s6, v252, 24
	s_ashr_i32 s13, s12, 2
	s_add_i32 s36, s35, 1
	v_readlane_b32 s7, v252, 25
	s_and_b64 s[6:7], s[6:7], exec
	s_cselect_b32 s6, s36, s35
	v_readlane_b32 s7, v252, 23
	s_mul_i32 s6, s6, s7
	v_readlane_b32 s7, v252, 21
	s_add_i32 s6, s6, s7
	s_ashr_i32 s7, s6, 31
	s_lshr_b32 s7, s7, 28
	s_add_i32 s7, s6, s7
	v_lshrrev_b32_e32 v5, 2, v3
	v_lshlrev_b32_e32 v6, 1, v3
	v_and_b32_e32 v2, 0xc0, v2
	s_ashr_i32 s8, s7, 4
	v_and_b32_e32 v5, 4, v5
	v_and_b32_e32 v6, 24, v6
	v_sub_u32_e32 v0, v0, v2
	s_lshl_b32 s9, s8, 3
	v_or3_b32 v4, v4, v5, v6
	v_lshlrev_b32_e32 v5, 5, v12
	v_ashrrev_i16_sdwa v0, v202, sext(v0) dst_sel:DWORD dst_unused:UNUSED_PAD src0_sel:DWORD src1_sel:BYTE_0
	s_sub_i32 s8, s33, s9
	v_and_b32_e32 v5, 32, v5
	v_bfe_i32 v15, v0, 0, 16
	s_min_u32 s11, s8, 8
	s_and_b32 s7, s7, -16
	v_add_lshl_u32 v2, v5, v15, 1
	s_sub_i32 s14, s6, s7
	v_cvt_f32_ubyte0_e32 v5, s11
	v_lshl_add_u32 v0, v4, 10, v2
	v_cvt_f32_i32_e32 v4, s14
	v_rcp_iflag_f32_e32 v6, v5
	v_lshl_add_u32 v134, v3, 10, v2
	s_ashr_i32 s6, s14, 30
	s_or_b32 s8, s6, 1
	v_mul_f32_e32 v2, v4, v6
	v_trunc_f32_e32 v2, v2
	v_fma_f32 v3, -v2, v5, v4
	v_cvt_i32_f32_e32 v2, v2
	v_cmp_ge_f32_e64 s[6:7], |v3|, v5
	s_and_b64 s[6:7], s[6:7], exec
	s_cselect_b32 s6, s8, 0
	v_readfirstlane_b32 s7, v2
	s_add_i32 s8, s7, s6
	s_mul_i32 s6, s8, s11
	s_sub_i32 s6, s14, s6
	s_sext_i32_i8 s6, s6
	s_add_i32 s22, s9, s6
	s_ashr_i32 s23, s22, 31
	s_lshl_b64 s[6:7], s[22:23], 18
	s_add_u32 s24, s4, s6
	s_addc_u32 s25, s5, s7
	s_bfe_i64 s[6:7], s[8:9], 0x80000
	s_lshl_b64 s[6:7], s[6:7], 18
	s_add_u32 s26, s30, s6
	s_addc_u32 s27, s31, s7
	s_add_i32 s23, s34, 0
	s_add_i32 m0, s23, 0x10000
	v_add_u32_e32 v136, 0x20000, v134
	global_load_lds_dwordx4 v0, s[26:27]
	s_add_i32 m0, s23, 0x12000
	s_add_u32 s6, s26, 0x20000
	global_load_lds_dwordx4 v130, s[26:27]
	s_addc_u32 s7, s27, 0
	s_add_i32 m0, s23, 0x14000
	s_add_i32 s37, s23, 0x2000
	global_load_lds_dwordx4 v0, s[6:7]
	s_add_i32 m0, s23, 0x16000
	s_add_i32 s38, s23, 0x4000
	global_load_lds_dwordx4 v130, s[6:7]
	s_mov_b32 m0, s23
	s_add_i32 s39, s23, 0x6000
	global_load_lds_dwordx4 v134, s[24:25]
	s_mov_b32 m0, s37
	v_add_u32_e32 v138, 0x20000, v132
	global_load_lds_dwordx4 v132, s[24:25]
	s_mov_b32 m0, s38
	v_mov_b32_e32 v131, v1
	global_load_lds_dwordx4 v136, s[24:25]
	s_mov_b32 m0, s39
	v_mov_b32_e32 v135, v1
	global_load_lds_dwordx4 v138, s[24:25]
	v_mov_b32_e32 v133, v1
	s_cmp_eq_u32 s13, 1
	v_lshl_add_u64 v[8:9], s[26:27], 0, v[0:1]
	v_lshl_add_u64 v[6:7], s[26:27], 0, v[130:131]
	v_lshl_add_u64 v[2:3], s[24:25], 0, v[134:135]
	s_cselect_b64 s[6:7], -1, 0
	s_cmp_lg_u32 s13, 1
	v_lshl_add_u64 v[4:5], s[24:25], 0, v[132:133]
	s_cbranch_scc1 .LBB0_1257
	s_barrier

; #define WAIT_VM(n) do {} while (0)
; #define WAIT_VM(n) asm volatile("s_waitcnt vmcnt(" #n ")" ::: "memory")
; DEV unsigned xb_ld(unsigned* p) { return __hip_atomic_load(p, __ATOMIC_RELAXED, __HIP_MEMORY_SCOPE_AGENT); }
; DEV unsigned xb_add(unsigned* p, unsigned v) { return __hip_atomic_fetch_add(p, v, __ATOMIC_RELAXED, __HIP_MEMORY_SCOPE_AGENT); }
; DEV void fence_acquire() { __builtin_amdgcn_fence(__ATOMIC_ACQUIRE, "agent"); }
; #define XB_SPIN(cond, bar) do { unsigned _sp = 0; while (cond) { s_sleep1(); \
;     if ((++_sp & 255u) == 0u) { if (xb_ld(&(bar)[XB_TMO])) break; if (_sp > XB_SPIN_CAP) { xb_add(&(bar)[XB_TMO], 1u); break; } } } } while (0)
; DEV void xcd_barrier(const XcdBarrier& b) {
;     ...
;             xb_add(&bar[XB_XGEN(bx)], 1u);
;             WAIT_VM(0);
;         } else {
;             XB_SPIN(xb_ld(&bar[XB_XGEN(bx)]) == gen, bar);
;             fence_acquire();
;             WAIT_VM(0);
;         }
;     }
;     __syncthreads();
.Lbw7_skip:
	s_waitcnt lgkmcnt(0)
	v_readlane_b32 s38, v255, 61
	s_cmp_lg_u32 s38, 0
	s_mov_b64 s[2:3], 0
	s_waitcnt lgkmcnt(0)
	s_barrier

; #define ROW_GROUPS(nrows, CALL4, CALL2) do { const int _r4 = ((nrows) / (4 * F.NGW)) * (4 * F.NGW); \
;     for (int r = 4 * F.gw; r < _r4; r += 4 * F.NGW) { CALL4; } for (int r = _r4 + (F.wave * F.G + F.bid); r < (nrows); r += F.NGW) { CALL2; } } while (0)
; DEV void phase_ln1(const Frame& F0, int l) {
;     const Frame F = refresh(F0);
;     const int nrows = (l == DEPTH - 1) ? LATR : MROWS;
;     ROW_GROUPS(nrows, ln1_group<4>(F, l, r), ln1_group<1>(F, l, r));
.Lbw8_skip:
	s_waitcnt lgkmcnt(0)
	v_readlane_b32 s38, v255, 61
	s_cmp_lg_u32 s38, 0
	v_readlane_b32 s0, v252, 2
	s_mul_hi_u32 s0, s70, s0
	v_readlane_b32 s3, v252, 3
	s_mul_i32 s0, s0, s3
	s_sub_i32 s0, s70, s0
	s_sub_i32 s2, s0, s3
	s_cmp_ge_u32 s0, s3
	s_cselect_b32 s0, s2, s0
	s_sub_i32 s2, s0, s3
	s_cmp_ge_u32 s0, s3
	v_readlane_b32 s33, v251, 29
	v_readlane_b32 s4, v251, 0
	s_cselect_b32 s0, s2, s0
	s_waitcnt lgkmcnt(0)
	s_barrier
	v_mov_b32_e32 v78, v200
	v_readlane_b32 s5, v251, 1
	s_sub_i32 s71, s70, s0
	s_lshl_b32 s0, s33, 2
	v_readlane_b32 s2, v252, 4
	s_add_i32 s8, s0, s2
	v_ashrrev_i32_e32 v79, 31, v78
	v_readlane_b32 s4, v253, 62
	v_readlane_b32 s6, v251, 2
	v_readlane_b32 s7, v251, 3
	s_cmp_ge_i32 s8, s71
	v_cmp_gt_i32_e64 s[2:3], 16, v78
	s_mul_hi_u32 s57, s4, 5
	s_mul_i32 s48, s4, 5
	v_lshrrev_b32_e32 v128, 28, v79
	v_readlane_b32 s5, v253, 63
	s_cbranch_scc1 .LBB0_1458
	v_readlane_b32 s14, v253, 62
	s_add_u32 s10, s6, 0x32c98000
	v_readlane_b32 s15, v253, 63
	s_addc_u32 s11, s7, 0
	s_lshl_b32 s0, s14, 10
	s_lshl_b64 s[4:5], s[14:15], 16
	s_add_u32 s4, s6, s4
	s_addc_u32 s5, s7, s5
	s_add_u32 s44, s6, 0x10000
	v_lshl_add_u64 v[2:3], v[78:79], 3, s[6:7]
	s_mov_b64 s[16:17], 0x3c6a8800
	s_addc_u32 s45, s7, 0
	v_lshl_add_u64 v[80:81], v[2:3], 0, s[16:17]
	v_lshlrev_b64 v[82:83], 4, v[78:79]
	s_mov_b64 s[16:17], 0x37098000
	s_cmp_lg_u32 s14, 0
	v_lshl_add_u64 v[86:87], v[2:3], 0, s[16:17]
	v_lshl_add_u64 v[2:3], s[4:5], 0, v[82:83]
	s_mov_b64 s[4:5], 0x40cf0c00
	s_cselect_b64 s[12:13], -1, 0
	s_cmp_eq_u32 s14, 0
	v_lshl_add_u64 v[88:89], v[2:3], 0, s[4:5]
	v_lshl_add_u64 v[2:3], v[78:79], 2, s[6:7]
	s_mov_b64 s[4:5], 0x40aa8800
	s_cselect_b64 s[14:15], -1, 0
	v_lshl_add_u64 v[90:91], v[2:3], 0, s[4:5]
	s_lshl_b64 s[4:5], s[0:1], 2
	s_add_u32 s16, s76, s4
	s_addc_u32 s17, s77, s5
	v_add_u32_e32 v0, v78, v128
	s_add_u32 s4, s78, s4
	v_and_b32_e32 v0, -16, v0
	s_addc_u32 s5, s79, s5
	v_lshl_add_u64 v[84:85], s[10:11], 0, v[82:83]
	v_sub_u32_e32 v129, v78, v0
	v_lshl_add_u64 v[92:93], s[16:17], 0, v[82:83]
	v_lshl_add_u64 v[94:95], s[4:5], 0, v[82:83]
	s_branch .LBB0_1380

; #define LAS __attribute__((address_space(3)))
; template <class T> DEV T shfl_t(T v, int src) { return __shfl(v, src); }
; DEV void phase_topk(const Frame& F0, int l) {
;     const Frame F = refresh(F0);
;     const int nitems = (l == DEPTH - 1) ? B_ * NE : 2 * B_ * NE;
;     LAS unsigned* hist = (LAS unsigned*)(F.lds);
;     LAS unsigned* selw = (LAS unsigned*)(F.lds + 1024);
;     LAS unsigned* cnt = (LAS unsigned*)(F.lds + 2048);
;     LAS int* selrow = (LAS int*)(F.lds + 8192);
;     const float* AFF = (const float*)(F.ws + WS_AFF); int* SLOT = (int*)(F.ws + WS_SLOT); float* EG = (float*)(F.ws + WS_EGATE);
;     for (int it = F.bid; it < nitems; it += F.G) {
;         const int e = it % NE, set = it / NE, kind = set / B_, b = set % B_;
;         const int n = kind ? CTX : SEQ, cap = kind ? CAPC : CAPL; const int row0 = kind ? LATR + b * CTX : b * SEQ;
;         const int sbase = kind ? B_ * CAPL + b * CAPC : b * CAPL;
;         const int per = n >= NTHREADS ? n / NTHREADS : 1; const bool act = F.tid * per < n;
;     ...
;                 const unsigned h0 = hist[4 * F.lane], h1 = hist[4 * F.lane + 1], h2 = hist[4 * F.lane + 2], h3 = hist[4 * F.lane + 3];
;                 unsigned suf = h0 + h1 + h2 + h3;
; #pragma unroll
;                 for (int o = 1; o < 64; o <<= 1) { const unsigned tv = shfl_t(suf, F.lane + o); if (F.lane + o < 64) suf += tv; }
;                 unsigned cum = suf - (h0 + h1 + h2 + h3);
.Lbw9_skip:
	s_waitcnt lgkmcnt(0)
	v_readlane_b32 s38, v255, 61
	s_cmp_lg_u32 s38, 0
	v_readlane_b32 s2, v253, 51
	v_readlane_b32 s3, v253, 52
	v_readlane_b32 s4, v251, 0
	s_and_b64 s[2:3], s[2:3], exec
	v_writelane_b32 v254, s58, 8
	v_readlane_b32 s5, v251, 1
	v_readlane_b32 s6, v251, 2
	v_readlane_b32 s7, v251, 3
	s_cselect_b32 s0, 64, 0x80
	v_writelane_b32 v254, s59, 9
	v_readlane_b32 s18, v251, 29
	v_mov_b32_e32 v0, v200
	s_mov_b64 s[4:5], s[6:7]
	s_cmp_ge_i32 s95, s0
	v_writelane_b32 v254, s57, 2
	v_writelane_b32 v253, s48, 49
	s_waitcnt lgkmcnt(0)
	s_barrier
	s_cbranch_scc1 .LBB0_1705
	v_add_u32_e32 v2, 1, v0
	v_and_b32_e32 v3, 64, v200
	v_and_or_b32 v2, v2, 63, v3
	v_lshlrev_b32_e32 v20, 2, v2
	v_add_u32_e32 v2, 2, v0
	v_and_or_b32 v2, v2, 63, v3
	v_lshlrev_b32_e32 v21, 2, v2
	v_add_u32_e32 v2, 4, v0
	v_writelane_b32 v254, s71, 10
	v_writelane_b32 v253, s70, 53
	v_writelane_b32 v251, s64, 47
	v_and_or_b32 v2, v2, 63, v3
	v_lshlrev_b32_e32 v22, 2, v2
	v_writelane_b32 v251, s65, 48
	v_add_u32_e32 v2, 8, v0
	v_writelane_b32 v251, s66, 49
	v_and_or_b32 v2, v2, 63, v3
	v_writelane_b32 v251, s67, 50
	v_lshlrev_b32_e32 v23, 2, v2
	v_add_u32_e32 v2, 16, v0
	v_writelane_b32 v251, s68, 51
	v_and_or_b32 v2, v2, 63, v3
	v_writelane_b32 v251, s69, 52
	s_lshl_b32 s19, s18, 6
	v_lshlrev_b32_e32 v24, 2, v2
	v_and_or_b32 v2, v0, 63, v3
	v_writelane_b32 v251, s70, 53
	s_add_u32 s2, s4, 0x40aa8800
	v_lshlrev_b32_e32 v2, 2, v2
	v_writelane_b32 v251, s71, 54
	v_writelane_b32 v254, s2, 6
	s_addc_u32 s2, s5, 0
	v_xor_b32_e32 v25, 0x80, v2
	v_add_u32_e32 v2, -1, v0
	v_writelane_b32 v251, s72, 55
	v_writelane_b32 v254, s2, 13
	s_add_u32 s2, s4, 0x40bb8800
	v_and_or_b32 v2, v2, 63, v3
	v_writelane_b32 v251, s73, 56
	v_writelane_b32 v254, s2, 15
	s_addc_u32 s2, s5, 0
	v_lshlrev_b32_e32 v26, 2, v2
	v_add_u32_e32 v2, 62, v0
	v_writelane_b32 v251, s74, 57
	s_add_u32 s92, s4, 0x40cc8800
	v_and_or_b32 v2, v2, 63, v3
	v_writelane_b32 v251, s75, 58
	v_writelane_b32 v254, s2, 17
	s_addc_u32 s93, s5, 0
	v_cmp_eq_u32_e64 s[6:7], 63, v0
	v_lshlrev_b32_e32 v27, 2, v2
	v_add_u32_e32 v2, 60, v0
	v_writelane_b32 v251, s76, 59
	s_cmp_eq_u32 s18, 0
	v_writelane_b32 v254, s6, 19
	v_and_or_b32 v2, v2, 63, v3
	v_writelane_b32 v251, s77, 60
	s_cselect_b64 s[90:91], -1, 0
	v_writelane_b32 v254, s7, 20
	s_lshl_b32 s6, s18, 2
	v_lshlrev_b32_e32 v28, 2, v2
	v_add_u32_e32 v2, 56, v0
	v_writelane_b32 v251, s78, 61
	s_add_i32 s6, s6, 0
	v_and_or_b32 v2, v2, 63, v3
	v_writelane_b32 v251, s79, 62
	v_add_u32_e32 v6, s19, v0
	s_add_u32 s78, s4, 0x40d30c00
	v_lshlrev_b32_e32 v29, 2, v2
	v_add_u32_e32 v2, 48, v0
	s_addc_u32 s79, s5, 0
	v_add_u32_e32 v8, 0x880, v6
	v_and_or_b32 v2, v2, 63, v3
	s_movk_i32 s4, 0x7f
	v_lshlrev_b32_e32 v30, 2, v2
	s_cmp_gt_i32 s18, 0
	v_max_i32_e32 v2, 0x700, v8
	v_writelane_b32 v254, s6, 23
	v_cmp_lt_i32_e32 vcc, s4, v6
	v_cmp_lt_i32_e64 s[4:5], 0, v0
	s_cselect_b64 s[74:75], -1, 0
	s_cmp_gt_i32 s18, 1
	v_sub_u32_e32 v2, v2, v6
	v_writelane_b32 v254, s4, 21
	s_cselect_b64 s[96:97], -1, 0
	s_cmp_gt_i32 s18, 2
	v_add_u32_e32 v2, 0xfffff97f, v2
	v_writelane_b32 v254, s5, 22
	s_cselect_b64 s[88:89], -1, 0
	s_cmp_gt_i32 s18, 3
	v_lshrrev_b32_e32 v3, 9, v2
	s_movk_i32 s4, 0x1ff
	s_cselect_b64 s[70:71], -1, 0
	s_cmp_gt_i32 s18, 4
	v_add_u32_e32 v3, 1, v3
	v_cmp_lt_u32_e64 s[4:5], s4, v2
	s_cselect_b64 s[30:31], -1, 0
	s_cmp_gt_i32 s18, 5
	v_writelane_b32 v254, s4, 25
	v_and_b32_e32 v32, 0xfffffe, v3
	s_cselect_b64 s[80:81], -1, 0
	s_cmp_gt_i32 s18, 6
	v_writelane_b32 v254, s5, 26
	v_cmp_ne_u32_e64 s[4:5], v3, v32
	s_cselect_b64 s[72:73], -1, 0
	s_cmp_gt_i32 s18, 7
	v_writelane_b32 v254, s4, 11
	s_cselect_b64 s[76:77], -1, 0
	v_lshlrev_b32_e32 v15, 2, v0
	v_writelane_b32 v254, s5, 12
	s_lshl_b32 s4, s18, 8
	s_add_i32 s4, s4, 0
	v_lshl_add_u32 v16, v0, 4, 0
	v_cmp_gt_i32_e64 s[6:7], 63, v0
	v_cmp_gt_i32_e64 s[8:9], 62, v0
	v_cmp_gt_i32_e64 s[10:11], 60, v0
	v_cmp_gt_i32_e64 s[12:13], 56, v0
	v_cmp_gt_i32_e64 s[14:15], 48, v0
	v_cmp_gt_i32_e64 s[16:17], 32, v0
	v_cmp_gt_i32_e64 s[20:21], 2, v0
	v_cmp_gt_i32_e64 s[22:23], 4, v0
	v_cmp_gt_i32_e64 s[24:25], 8, v0
	v_cmp_gt_i32_e64 s[26:27], 16, v0
	v_not_b32_e32 v0, v0
	s_addk_i32 s4, 0x2000
	v_cmp_gt_i32_e64 s[2:3], s63, v6
	v_lshl_add_u32 v14, v6, 2, 0
	v_or_b32_e32 v17, 1, v15
	v_or_b32_e32 v18, 2, v15
	v_or_b32_e32 v19, 3, v15
	s_mov_b32 s33, s95
	v_subrev_u32_e32 v31, s19, v0
	v_add_u32_e32 v7, 0x200, v6
	v_lshl_add_u32 v33, v32, 9, v8
	v_add_u32_e32 v9, 0xa80, v6
	v_add_u32_e32 v34, s4, v15
	s_xor_b64 s[84:85], vcc, -1
	s_branch .LBB0_1534

; template <class Epi, class Sched>
; DEV void gemm_phase(LAS unsigned char* lds, const int K, const Sched& S, const Epi& E, const int wid, const int lane) {
;     const int tid = wid * 64 + lane; const int wr = wid >> 2, wc = wid & 3, fr = lane & 15, fq = lane >> 4;
;     const int nt = K / BK;
;     unsigned voffA[2], voffB[2]; int Ri[2], Ci[2];
; #pragma unroll
;     for (int i = 0; i < 2; ++i) { int R, C; stage_rc(tid * 16 + i * 8192, R, C); const int Rb = Epi::PERM ? ((R & ~31) + perm32(R & 31)) : R; Ri[i] = R; Ci[i] = C;
;         voffA[i] = (unsigned)(R * K + C) * 2u; voffB[i] = (unsigned)(Rb * K + C) * 2u; }
;     unsigned goffC[2][2] = {{0u, 0u}, {0u, 0u}}, goffN[2][2] = {{0u, 0u}, {0u, 0u}};
;     constexpr int GIDX_OFF = STAGE_BYTES;
;     const size_t kstep = (size_t)(BK * 2);
;     const size_t hstep = (size_t)HALF * K * 2;
;     const unsigned ldsw = (unsigned)wid * 1024u;
;     const int aoff = lds_byte(wr * 64 + fr, fq * 8), boff = lds_byte(wc * 32 + fr, fq * 8);
;     ...
;     Unit cur, nxt; int ui = 0;
;     if (!S.next(0, cur)) return;
;     f32x4 acc[2][2][4][2];
; #pragma unroll
;     for (int a = 0; a < 2; ++a)
; #pragma unroll
;         for (int b = 0; b < 2; ++b)
; #pragma unroll
;             for (int m = 0; m < 4; ++m)
; #pragma unroll
;                 for (int n = 0; n < 2; ++n) acc[a][b][m][n] = (f32x4){0.f, 0.f, 0.f, 0.f};
;     bf16x8 At[4][2], B0[2][2], B1[2][2];
;     const char* cA = cur.A; const char* cB = cur.B;
;     if constexpr (Sched::GATHER_A) {
; #pragma unroll
;         for (int hh = 0; hh < 2; ++hh)
; #pragma unroll
;             for (int i = 0; i < 2; ++i) { goffC[hh][i] = (unsigned)S.gidx[S.idx_base(cur) + hh * HALF + Ri[i]] * (unsigned)(K * 2) + (unsigned)(Ci[i] * 2); goffN[hh][i] = goffC[hh][i]; }
;     }
;     PG8_STAGE(PG8_SB(0, 0), cB, voffB); PG8_STAGE(PG8_SB(0, 1), cB + hstep, voffB); PG8_STAGEA(PG8_SA(0, 0), cA, 0, false); PG8_STAGEA(PG8_SA(0, 1), cA, 1, false);
; DEV void gemm_g4(const Frame& F0, int l, int vcu) {
;     const Frame F = refresh(F0);
;     pg8::GatherOrder S; S.init((const void*)(F.ws + WS_XIN), (const bf16_t*)(F.ws + WS_WGU) + (size_t)l * NE * 2 * FF * 1024, 1024, 2 * FF, F.G, vcu, (l == DEPTH - 1) ? B_ * CAPL : EROWS); S.gidx = (const int*)(F.ws + WS_EIDX);
;     EpiSwiglu E; E.HID = (bf16_t*)(F.ws + WS_HID);
;     pg8::gemm_phase(F.lds, 1024, S, E, F.wave, F.lane);
.Lbw10_skip:
	s_waitcnt lgkmcnt(0)
	v_readlane_b32 s38, v255, 61
	s_cmp_lg_u32 s38, 0
	v_readlane_b32 s4, v251, 0
	v_readlane_b32 s5, v251, 1
	v_readlane_b32 s4, v253, 51
	v_readlane_b32 s5, v253, 52
	s_and_b64 s[4:5], s[4:5], exec
	s_cselect_b32 s33, 8, 9
	s_lshl_b32 s0, s33, 8
	v_readlane_b32 s3, v251, 29
	v_mov_b32_e32 v0, v200
	v_readlane_b32 s6, v251, 2
	v_readlane_b32 s7, v251, 3
	s_cmp_ge_i32 s95, s0
	s_mov_b64 s[66:67], s[54:55]
	s_waitcnt lgkmcnt(0)
	s_barrier
	s_cbranch_scc1 .LBB0_1769
	v_readlane_b32 s4, v253, 62
	s_add_u32 s8, s6, 0x37098000
	v_readlane_b32 s5, v253, 63
	s_addc_u32 s9, s7, 0
	s_lshl_b64 s[4:5], s[4:5], 27
	s_add_u32 s2, s6, s4
	s_addc_u32 s4, s7, s5
	s_add_u32 s38, s2, 0x2bc8000
	s_addc_u32 s39, s4, 0
	s_add_u32 s40, s6, 0x40d30c00
	s_addc_u32 s41, s7, 0
	s_lshl_b32 s42, s3, 10
	v_lshlrev_b32_e32 v130, 4, v0
	v_add_u32_e32 v3, s42, v130
	v_ashrrev_i32_e32 v2, 31, v3
	v_lshrrev_b32_e32 v2, 22, v2
	v_add_u32_e32 v2, v3, v2
	v_ashrrev_i32_e32 v4, 10, v2
	v_mul_i32_i24_e32 v2, 0x400, v4
	v_sub_u32_e32 v2, v3, v2
	v_lshrrev_b32_e32 v5, 4, v2
	v_bitop3_b32 v5, v5, v2, 32 bitop3:0x6c
	v_ashrrev_i32_e32 v6, 31, v5
	v_lshrrev_b32_e32 v6, 26, v6
	v_add_u32_e32 v6, v5, v6
	v_ashrrev_i32_e32 v7, 6, v6
	v_and_b32_e32 v6, 0xc0, v6
	v_sub_u32_e32 v5, v5, v6
	v_lshlrev_b32_e32 v2, 3, v4
	v_lshlrev_b32_e32 v4, 5, v4
	v_ashrrev_i16_sdwa v5, v202, sext(v5) dst_sel:DWORD dst_unused:UNUSED_PAD src0_sel:DWORD src1_sel:BYTE_0
	v_and_b32_e32 v4, 32, v4
	v_bfe_i32 v5, v5, 0, 16
	v_add_u32_e32 v3, 0x2000, v3
	v_add_lshl_u32 v147, v4, v5, 1
	v_ashrrev_i32_e32 v4, 31, v3
	v_lshrrev_b32_e32 v4, 22, v4
	v_add_u32_e32 v4, v3, v4
	v_ashrrev_i32_e32 v5, 10, v4
	v_mul_i32_i24_e32 v4, 0x400, v5
	v_sub_u32_e32 v3, v3, v4
	v_lshrrev_b32_e32 v4, 4, v3
	v_bitop3_b32 v3, v4, v3, 32 bitop3:0x6c
	v_ashrrev_i32_e32 v6, 31, v3
	v_lshrrev_b32_e32 v6, 26, v6
	v_add_u32_e32 v6, v3, v6
	v_ashrrev_i32_e32 v8, 6, v6
	v_and_b32_e32 v6, 0xffc0, v6
	v_sub_u32_e32 v3, v3, v6
	v_lshrrev_b16_e32 v6, 7, v3
	v_and_b32_e32 v6, 1, v6
	v_lshlrev_b32_e32 v4, 3, v5
	v_add_u16_e32 v3, v3, v6
	v_and_b32_e32 v4, -16, v4
	v_lshlrev_b32_e32 v5, 5, v5
	v_ashrrev_i16_sdwa v3, v202, sext(v3) dst_sel:DWORD dst_unused:UNUSED_PAD src0_sel:DWORD src1_sel:BYTE_0
	v_add_u32_e32 v4, v8, v4
	v_and_b32_e32 v5, 32, v5
	v_bfe_i32 v3, v3, 0, 16
	v_add_lshl_u32 v148, v5, v3, 1
	v_and_b32_e32 v3, 3, v8
	s_mov_b32 s2, 0x1fffe0
	v_lshrrev_b32_e32 v5, 2, v4
	v_lshlrev_b32_e32 v6, 1, v4
	v_and_b32_e32 v2, -16, v2
	v_and_or_b32 v3, v4, s2, v3
	v_and_b32_e32 v5, 4, v5
	v_and_b32_e32 v6, 24, v6
	s_lshl_b32 s43, s33, 5
	v_readlane_b32 s4, v252, 24
	s_ashr_i32 s14, s3, 2
	v_add_u32_e32 v2, v7, v2
	v_or3_b32 v3, v3, v5, v6
	s_or_b32 s44, s43, 1
	v_readlane_b32 s5, v252, 25
	v_lshl_add_u32 v132, v3, 11, v148
	v_and_b32_e32 v3, 3, v7
	v_lshrrev_b32_e32 v5, 2, v2
	v_lshlrev_b32_e32 v6, 1, v2
	s_and_b64 s[4:5], s[4:5], exec
	v_and_or_b32 v3, v2, s2, v3
	v_and_b32_e32 v5, 4, v5
	v_and_b32_e32 v6, 24, v6
	s_cselect_b32 s2, s44, s43
	s_lshl_b32 s45, s33, 4
	v_or3_b32 v3, v3, v5, v6
	s_abs_i32 s47, s45
	v_lshl_add_u32 v134, v3, 11, v147
	v_cvt_f32_u32_e32 v3, s47
	v_readlane_b32 s4, v252, 23
	s_sub_i32 s10, 0, s47
	s_mul_i32 s2, s2, s4
	v_rcp_iflag_f32_e32 v3, v3
	v_readlane_b32 s4, v252, 21
	s_add_i32 s2, s2, s4
	s_abs_i32 s5, s2
	v_mul_f32_e32 v3, 0x4f7ffffe, v3
	v_cvt_u32_f32_e32 v3, v3
	s_ashr_i32 s4, s2, 31
	s_bfe_i32 s46, s33, 0x1001b
	s_xor_b32 s4, s4, s46
	v_readfirstlane_b32 s48, v3
	s_mul_i32 s10, s10, s48
	s_mul_hi_u32 s10, s48, s10
	s_add_i32 s48, s48, s10
	s_mul_hi_u32 s10, s5, s48
	s_mul_i32 s11, s10, s47
	s_sub_i32 s5, s5, s11
	s_add_i32 s11, s10, 1
	s_sub_i32 s12, s5, s47
	s_cmp_ge_u32 s5, s47
	s_cselect_b32 s10, s11, s10
	s_cselect_b32 s5, s12, s5
	s_add_i32 s11, s10, 1
	s_cmp_ge_u32 s5, s47
	s_cselect_b32 s5, s11, s10
	s_xor_b32 s5, s5, s4
	s_sub_i32 s28, s5, s4
	s_mul_i32 s4, s28, s45
	s_sub_i32 s10, s2, s4
	s_sext_i32_i16 s2, s33
	v_cvt_f32_i32_e32 v5, s2
	v_cvt_f32_i32_e32 v3, s10
	s_xor_b32 s4, s10, s2
	s_ashr_i32 s4, s4, 30
	v_rcp_iflag_f32_e32 v6, v5
	s_or_b32 s11, s4, 1
	s_mul_i32 s15, s28, 0x2400
	v_mov_b32_e32 v135, v1
	v_mul_f32_e32 v6, v3, v6
	v_trunc_f32_e32 v6, v6
	v_fma_f32 v3, -v6, v5, v3
	v_cvt_i32_f32_e32 v6, v6
	v_cmp_ge_f32_e64 s[4:5], |v3|, |v5|
	s_and_b64 s[4:5], s[4:5], exec
	s_cselect_b32 s2, s11, 0
	v_readfirstlane_b32 s4, v6
	s_add_i32 s2, s4, s2
	s_mul_i32 s4, s2, s33
	s_ashr_i32 s29, s28, 31
	s_sub_i32 s12, s10, s4
	s_lshl_b64 s[4:5], s[28:29], 23
	s_add_u32 s10, s38, s4
	s_addc_u32 s11, s39, s5
	s_bfe_i64 s[4:5], s[2:3], 0x100000
	s_lshl_b64 s[4:5], s[4:5], 19
	s_add_u32 s4, s10, s4
	s_addc_u32 s5, s11, s5
	s_bfe_i64 s[10:11], s[12:13], 0x100000
	s_mul_hi_i32 s13, s28, 0x2400
	s_add_u32 s15, s40, s15
	s_addc_u32 s13, s41, s13
	s_lshl_b64 s[10:11], s[10:11], 10
	s_add_u32 s10, s15, s10
	s_addc_u32 s11, s13, s11
	v_ashrrev_i32_e32 v3, 31, v2
	v_lshl_add_u64 v[6:7], v[2:3], 2, s[10:11]
	global_load_dword v3, v[6:7], off
	v_ashrrev_i32_e32 v5, 31, v4
	v_lshl_add_u64 v[8:9], v[4:5], 2, s[10:11]
	s_add_i32 s29, s42, 0
	s_add_i32 m0, s29, 0x10000
	v_mov_b32_e32 v133, v1
	global_load_lds_dwordx4 v134, s[4:5]
	s_add_i32 m0, s29, 0x12000
	s_add_u32 s10, s4, 0x40000
	global_load_lds_dwordx4 v132, s[4:5]
	s_addc_u32 s11, s5, 0
	s_add_i32 m0, s29, 0x14000
	s_add_i32 s49, s29, 0x2000
	global_load_lds_dwordx4 v134, s[10:11]
	s_add_i32 m0, s29, 0x16000
	s_add_i32 s50, s29, 0x4000
	global_load_lds_dwordx4 v132, s[10:11]
	s_mov_b32 m0, s29
	s_add_i32 s51, s29, 0x6000
	s_cmp_eq_u32 s14, 1
	s_cselect_b64 s[10:11], -1, 0
	s_cmp_lg_u32 s14, 1
	s_waitcnt vmcnt(0)
	v_lshl_add_u32 v136, v3, 11, v147
	global_load_dword v3, v[8:9], off
	s_waitcnt vmcnt(0)
	v_lshl_add_u32 v138, v3, 11, v148
	global_load_dword v3, v[6:7], off offset:512
	v_lshl_add_u64 v[6:7], s[4:5], 0, v[134:135]
	global_load_lds_dwordx4 v136, s[8:9]
	s_mov_b32 m0, s49
	s_waitcnt vmcnt(0)
	v_lshl_add_u32 v140, v3, 11, v147
	global_load_dword v3, v[8:9], off offset:512
	v_lshl_add_u64 v[8:9], s[4:5], 0, v[132:133]
	global_load_lds_dwordx4 v138, s[8:9]
	s_mov_b32 m0, s50
	s_waitcnt vmcnt(0)
	v_lshl_add_u32 v142, v3, 11, v148
	global_load_lds_dwordx4 v140, s[8:9]
	s_mov_b32 m0, s51
	s_nop 0
	global_load_lds_dwordx4 v142, s[8:9]
	s_cbranch_scc1 .LBB0_1752
	s_barrier

; template <class Epi, class Sched>
; DEV void gemm_phase(LAS unsigned char* lds, const int K, const Sched& S, const Epi& E, const int wid, const int lane) {
;     const int tid = wid * 64 + lane; const int wr = wid >> 2, wc = wid & 3, fr = lane & 15, fq = lane >> 4;
;     const int nt = K / BK;
;     unsigned voffA[2], voffB[2]; int Ri[2], Ci[2];
; #pragma unroll
;     for (int i = 0; i < 2; ++i) { int R, C; stage_rc(tid * 16 + i * 8192, R, C); const int Rb = Epi::PERM ? ((R & ~31) + perm32(R & 31)) : R; Ri[i] = R; Ci[i] = C;
;         voffA[i] = (unsigned)(R * K + C) * 2u; voffB[i] = (unsigned)(Rb * K + C) * 2u; }
;     unsigned goffC[2][2] = {{0u, 0u}, {0u, 0u}}, goffN[2][2] = {{0u, 0u}, {0u, 0u}};
;     constexpr int GIDX_OFF = STAGE_BYTES;
;     const size_t kstep = (size_t)(BK * 2);
;     const size_t hstep = (size_t)HALF * K * 2;
;     const unsigned ldsw = (unsigned)wid * 1024u;
;     const int aoff = lds_byte(wr * 64 + fr, fq * 8), boff = lds_byte(wc * 32 + fr, fq * 8);
;     ...
;     Unit cur, nxt; int ui = 0;
;     if (!S.next(0, cur)) return;
;     f32x4 acc[2][2][4][2];
; #pragma unroll
;     for (int a = 0; a < 2; ++a)
; #pragma unroll
;         for (int b = 0; b < 2; ++b)
; #pragma unroll
;             for (int m = 0; m < 4; ++m)
; #pragma unroll
;                 for (int n = 0; n < 2; ++n) acc[a][b][m][n] = (f32x4){0.f, 0.f, 0.f, 0.f};
;     bf16x8 At[4][2], B0[2][2], B1[2][2];
;     const char* cA = cur.A; const char* cB = cur.B;
;     if constexpr (Sched::GATHER_A) {
; #pragma unroll
;         for (int hh = 0; hh < 2; ++hh)
; #pragma unroll
;             for (int i = 0; i < 2; ++i) { goffC[hh][i] = (unsigned)S.gidx[S.idx_base(cur) + hh * HALF + Ri[i]] * (unsigned)(K * 2) + (unsigned)(Ci[i] * 2); goffN[hh][i] = goffC[hh][i]; }
;     }
;     PG8_STAGE(PG8_SB(0, 0), cB, voffB); PG8_STAGE(PG8_SB(0, 1), cB + hstep, voffB); PG8_STAGEA(PG8_SA(0, 0), cA, 0, false); PG8_STAGEA(PG8_SA(0, 1), cA, 1, false);
;     if (wr == 1) S_BARRIER();
; DEV void gemm_g5(const Frame& F0, int l, int vcu) {
;     const Frame F = refresh(F0);
;     pg8::GroupedOrder S; S.init((const void*)(F.ws + WS_HID), (const bf16_t*)(F.ws + WS_WD) + (size_t)l * NE * 1024 * FF, FF, 1024, F.G, vcu, (l == DEPTH - 1) ? B_ * CAPL : EROWS);
;     EpiYse E; E.O = (bf16_t*)(F.ws + WS_YSE); E.rowscale = (const float*)(F.ws + WS_EGATE);
;     pg8::gemm_phase(F.lds, FF, S, E, F.wave, F.lane);
.Lbw11_skip:
	s_waitcnt lgkmcnt(0)
	v_readlane_b32 s38, v255, 61
	s_cmp_lg_u32 s38, 0
	v_readlane_b32 s4, v251, 0
	v_readlane_b32 s6, v251, 2
	v_readlane_b32 s7, v251, 3
	s_lshl_b32 s0, s33, 6
	v_readlane_b32 s10, v251, 29
	v_mov_b32_e32 v16, v200
	s_mov_b64 s[2:3], s[6:7]
	s_cmp_ge_i32 s95, s0
	s_waitcnt lgkmcnt(0)
	s_barrier
	v_readlane_b32 s5, v251, 1
	s_cbranch_scc1 .LBB0_1829
	v_readlane_b32 s4, v253, 62
	s_add_u32 s30, s2, 0x45dd4c00
	v_readlane_b32 s5, v253, 63
	s_addc_u32 s31, s3, 0
	s_lshl_b64 s[4:5], s[4:5], 26
	s_add_u32 s4, s2, s4
	s_addc_u32 s5, s3, s5
	s_add_u32 s34, s4, 0x22bc8000
	s_addc_u32 s35, s5, 0
	s_lshl_b32 s36, s10, 10
	v_lshl_add_u32 v0, v16, 4, s36
	v_add_u32_e32 v2, 0x2000, v0
	v_ashrrev_i32_e32 v3, 31, v2
	v_lshrrev_b32_e32 v3, 22, v3
	v_add_u32_e32 v3, v2, v3
	v_ashrrev_i32_e32 v10, 10, v3
	v_mul_i32_i24_e32 v3, 0x400, v10
	v_sub_u32_e32 v2, v2, v3
	v_lshrrev_b32_e32 v3, 4, v2
	v_bitop3_b32 v2, v3, v2, 32 bitop3:0x6c
	v_ashrrev_i32_e32 v3, 31, v2
	v_lshrrev_b32_e32 v3, 26, v3
	v_add_u32_e32 v3, v2, v3
	v_ashrrev_i32_e32 v11, 6, v3
	v_lshlrev_b32_e32 v4, 3, v10
	v_and_b32_e32 v3, 0xffc0, v3
	v_and_b32_e32 v4, -16, v4
	v_sub_u32_e32 v2, v2, v3
	v_add_u32_e32 v4, v11, v4
	v_lshrrev_b16_e32 v3, 7, v2
	v_and_b32_e32 v5, 3, v11
	s_mov_b32 s4, 0xfffe0
	v_lshrrev_b32_e32 v6, 2, v4
	v_lshlrev_b32_e32 v7, 1, v4
	v_and_b32_e32 v3, 1, v3
	v_and_or_b32 v5, v4, s4, v5
	v_and_b32_e32 v6, 4, v6
	v_and_b32_e32 v7, 24, v7
	v_add_u16_e32 v2, v2, v3
	v_or3_b32 v5, v5, v6, v7
	v_lshlrev_b32_e32 v6, 5, v10
	v_ashrrev_i16_sdwa v2, v202, sext(v2) dst_sel:DWORD dst_unused:UNUSED_PAD src0_sel:DWORD src1_sel:BYTE_0
	v_and_b32_e32 v6, 32, v6
	v_bfe_i32 v13, v2, 0, 16
	v_add_lshl_u32 v2, v6, v13, 1
	v_lshl_add_u32 v130, v5, 12, v2
	v_lshl_add_u32 v132, v4, 12, v2
	v_ashrrev_i32_e32 v2, 31, v0
	v_lshrrev_b32_e32 v2, 22, v2
	v_add_u32_e32 v2, v0, v2
	v_ashrrev_i32_e32 v12, 10, v2
	v_mul_i32_i24_e32 v2, 0x400, v12
	v_sub_u32_e32 v0, v0, v2
	v_lshrrev_b32_e32 v2, 4, v0
	v_bitop3_b32 v0, v2, v0, 32 bitop3:0x6c
	v_ashrrev_i32_e32 v2, 31, v0
	v_lshrrev_b32_e32 v2, 26, v2
	v_add_u32_e32 v2, v0, v2
	v_lshlrev_b32_e32 v3, 3, v12
	v_ashrrev_i32_e32 v14, 6, v2
	v_and_b32_e32 v3, -16, v3
	v_add_u32_e32 v3, v14, v3
	v_and_b32_e32 v4, 3, v14
	v_and_or_b32 v4, v3, s4, v4
	s_lshl_b32 s37, s33, 3
	v_readlane_b32 s4, v252, 24
	s_ashr_i32 s11, s10, 2
	v_lshrrev_b32_e32 v5, 2, v3
	v_lshlrev_b32_e32 v6, 1, v3
	v_and_b32_e32 v2, 0xc0, v2
	s_or_b32 s38, s37, 1
	v_readlane_b32 s5, v252, 25
	v_and_b32_e32 v5, 4, v5
	v_and_b32_e32 v6, 24, v6
	v_sub_u32_e32 v0, v0, v2
	s_and_b64 s[4:5], s[4:5], exec
	v_or3_b32 v4, v4, v5, v6
	v_lshlrev_b32_e32 v5, 5, v12
	v_ashrrev_i16_sdwa v0, v202, sext(v0) dst_sel:DWORD dst_unused:UNUSED_PAD src0_sel:DWORD src1_sel:BYTE_0
	s_cselect_b32 s4, s38, s37
	s_lshl_b32 s39, s33, 2
	v_and_b32_e32 v5, 32, v5
	v_bfe_i32 v15, v0, 0, 16
	s_abs_i32 s40, s39
	v_add_lshl_u32 v2, v5, v15, 1
	v_cvt_f32_u32_e32 v5, s40
	v_lshl_add_u32 v0, v4, 12, v2
	v_lshl_add_u32 v134, v3, 12, v2
	v_readlane_b32 s5, v252, 23
	v_rcp_iflag_f32_e32 v2, v5
	s_sub_i32 s7, 0, s40
	s_mul_i32 s4, s4, s5
	v_readlane_b32 s5, v252, 21
	v_mul_f32_e32 v2, 0x4f7ffffe, v2
	v_cvt_u32_f32_e32 v2, v2
	s_add_i32 s4, s4, s5
	s_abs_i32 s6, s4
	s_ashr_i32 s5, s4, 31
	v_readfirstlane_b32 s42, v2
	s_mul_i32 s7, s7, s42
	s_mul_hi_u32 s7, s42, s7
	s_add_i32 s42, s42, s7
	s_mul_hi_u32 s7, s6, s42
	s_mul_i32 s8, s7, s40
	s_bfe_i32 s41, s33, 0x1001d
	s_sub_i32 s6, s6, s8
	s_xor_b32 s5, s5, s41
	s_add_i32 s8, s7, 1
	s_sub_i32 s9, s6, s40
	s_cmp_ge_u32 s6, s40
	s_cselect_b32 s7, s8, s7
	s_cselect_b32 s6, s9, s6
	s_add_i32 s8, s7, 1
	s_cmp_ge_u32 s6, s40
	s_cselect_b32 s6, s8, s7
	s_xor_b32 s6, s6, s5
	s_sub_i32 s22, s6, s5
	s_sext_i32_i8 s5, s33
	v_cvt_f32_i32_e32 v2, s5
	s_mul_i32 s6, s22, s39
	s_sub_i32 s7, s4, s6
	v_cvt_f32_i32_e32 v3, s7
	v_rcp_iflag_f32_e32 v4, v2
	s_xor_b32 s4, s7, s5
	s_ashr_i32 s4, s4, 30
	s_or_b32 s6, s4, 1
	v_mul_f32_e32 v4, v3, v4
	v_trunc_f32_e32 v4, v4
	v_fma_f32 v3, -v4, v2, v3
	v_cvt_i32_f32_e32 v4, v4
	v_cmp_ge_f32_e64 s[4:5], |v3|, |v2|
	s_and_b64 s[4:5], s[4:5], exec
	s_cselect_b32 s4, s6, 0
	v_readfirstlane_b32 s5, v4
	s_add_i32 s6, s5, s4
	s_mul_i32 s4, s6, s33
	s_sub_i32 s8, s7, s4
	s_bfe_i64 s[4:5], s[8:9], 0x80000
	s_ashr_i32 s23, s22, 31
	s_lshl_b64 s[4:5], s[4:5], 20
	s_add_u32 s4, s30, s4
	s_mul_i32 s9, s22, 0x900000
	s_addc_u32 s5, s31, s5
	s_mul_hi_i32 s7, s22, 0x900000
	s_add_u32 s24, s4, s9
	s_addc_u32 s25, s5, s7
	s_lshl_b64 s[4:5], s[22:23], 22
	s_add_u32 s7, s34, s4
	s_addc_u32 s9, s35, s5
	s_bfe_i64 s[4:5], s[6:7], 0x80000
	s_lshl_b64 s[4:5], s[4:5], 20
	s_add_u32 s26, s7, s4
	s_addc_u32 s27, s9, s5
	s_add_i32 s43, s36, 0
	s_add_i32 m0, s43, 0x10000
	v_add_u32_e32 v136, 0x80000, v134
	global_load_lds_dwordx4 v0, s[26:27]
	s_add_i32 m0, s43, 0x12000
	s_add_u32 s4, s26, 0x80000
	global_load_lds_dwordx4 v130, s[26:27]
	s_addc_u32 s5, s27, 0
	s_add_i32 m0, s43, 0x14000
	s_add_i32 s44, s43, 0x2000
	global_load_lds_dwordx4 v0, s[4:5]
	s_add_i32 m0, s43, 0x16000
	s_add_i32 s45, s43, 0x4000
	global_load_lds_dwordx4 v130, s[4:5]
	s_mov_b32 m0, s43
	s_add_i32 s46, s43, 0x6000
	global_load_lds_dwordx4 v134, s[24:25]
	s_mov_b32 m0, s44
	v_add_u32_e32 v138, 0x80000, v132
	global_load_lds_dwordx4 v132, s[24:25]
	s_mov_b32 m0, s45
	v_mov_b32_e32 v131, v1
	global_load_lds_dwordx4 v136, s[24:25]
	s_mov_b32 m0, s46
	v_mov_b32_e32 v135, v1
	global_load_lds_dwordx4 v138, s[24:25]
	v_mov_b32_e32 v133, v1
	s_cmp_eq_u32 s11, 1
	v_lshl_add_u64 v[8:9], s[26:27], 0, v[0:1]
	v_lshl_add_u64 v[6:7], s[26:27], 0, v[130:131]
	v_lshl_add_u64 v[2:3], s[24:25], 0, v[134:135]
	s_cselect_b64 s[4:5], -1, 0
	s_cmp_lg_u32 s11, 1
	v_lshl_add_u64 v[4:5], s[24:25], 0, v[132:133]
	s_cbranch_scc1 .LBB0_1816
	s_barrier

; #define ROW_GROUPS(nrows, CALL4, CALL2) do { const int _r4 = ((nrows) / (4 * F.NGW)) * (4 * F.NGW); \
;     for (int r = 4 * F.gw; r < _r4; r += 4 * F.NGW) { CALL4; } for (int r = _r4 + (F.wave * F.G + F.bid); r < (nrows); r += F.NGW) { CALL2; } } while (0)
; DEV void phase_ln2(const Frame& F0, int l) {
;     const Frame F = refresh(F0);
;     const int nrows = (l == DEPTH - 1) ? LATR : MROWS;
;     ROW_GROUPS(nrows, ln2_group<4>(F, l, r), ln2_group<1>(F, l, r));
.Lbw12_skip:
	s_waitcnt lgkmcnt(0)
	v_readlane_b32 s38, v255, 61
	s_cmp_lg_u32 s38, 0
	v_readlane_b32 s33, v251, 29
	s_waitcnt lgkmcnt(0)
	s_barrier
	s_lshl_b32 s0, s33, 2
	v_readlane_b32 s2, v252, 4
	v_mov_b32_e32 v82, v200
	v_readlane_b32 s4, v251, 0
	s_add_i32 s8, s0, s2
	v_readlane_b32 s6, v251, 2
	v_readlane_b32 s7, v251, 3
	s_cmp_ge_i32 s8, s71
	v_ashrrev_i32_e32 v83, 31, v82
	v_readlane_b32 s5, v251, 1
	s_cbranch_scc1 .LBB0_1910
	s_add_u32 s10, s6, 0x32c98000
	s_addc_u32 s11, s7, 0
	s_add_u32 s12, s6, 0x4edd4c00
	v_readlane_b32 s2, v253, 62
	s_addc_u32 s13, s7, 0
	s_lshl_b32 s0, s2, 10
	s_add_u32 s14, s6, 0x39298000
	v_lshl_add_u64 v[2:3], v[82:83], 2, s[6:7]
	s_mov_b64 s[4:5], 0x40bb8800
	s_addc_u32 s15, s7, 0
	v_readlane_b32 s16, v251, 0
	v_lshl_add_u64 v[86:87], v[2:3], 0, s[4:5]
	v_lshlrev_b64 v[2:3], 4, v[82:83]
	s_add_u32 s42, s6, 0x10000
	v_lshl_add_u64 v[4:5], v[82:83], 3, s[6:7]
	s_mov_b64 s[4:5], 0x37098000
	v_readlane_b32 s17, v251, 1
	v_readlane_b32 s18, v251, 2
	v_readlane_b32 s19, v251, 3
	s_addc_u32 s43, s7, 0
	s_add_i32 s44, s48, 5
	v_lshl_add_u64 v[90:91], v[4:5], 0, s[4:5]
	v_lshl_add_u64 v[92:93], s[16:17], 0, v[2:3]
	s_lshl_b64 s[4:5], s[0:1], 2
	v_readlane_b32 s16, v253, 26
	v_readlane_b32 s17, v253, 27
	s_add_u32 s16, s16, s4
	v_readlane_b32 s18, v253, 28
	s_addc_u32 s17, s17, s5
	v_readlane_b32 s3, v253, 63
	v_readlane_b32 s19, v253, 29
	s_add_u32 s18, s18, s4
	v_cmp_gt_i32_e64 s[2:3], 64, v82
	v_mov_b32_e32 v84, v82
	v_mov_b32_e32 v85, v1
	v_lshl_add_u64 v[88:89], s[10:11], 0, v[2:3]
	s_addc_u32 s19, s19, s5
	v_readlane_b32 s20, v253, 30
	v_readlane_b32 s21, v253, 31
	v_readlane_b32 s22, v253, 32
	v_readlane_b32 s23, v253, 33
	v_readlane_b32 s24, v253, 34
	v_readlane_b32 s25, v253, 35
	v_readlane_b32 s26, v253, 36
	v_readlane_b32 s27, v253, 37
	v_readlane_b32 s28, v253, 38
	v_readlane_b32 s29, v253, 39
	v_readlane_b32 s30, v253, 40
	v_readlane_b32 s31, v253, 41
	s_branch .LBB0_1876
